# GEMM loops: duplicate s_waitcnt lgkmcnt(0) after the hand-off barrier removed (already satisfied before the barrier), 35 sites
# baseline (speedup 1.0000x reference)
.LBB0_81:
	s_add_u32 s20, s94, 0xfce78080
	s_addc_u32 s59, s95, -1
	s_cmp_lg_u32 s58, 12
	s_cselect_b32 s20, s20, 0
	s_cselect_b32 s59, s59, 0
	s_add_u32 vcc_lo, s40, s20
	s_addc_u32 vcc_hi, s41, s59
	s_add_i32 s82, 0, 0x10000
	s_add_u32 s96, s42, s20
	v_add_u32_e32 v143, s82, v141
	s_addc_u32 s97, s43, s59
	s_add_i32 s20, 0, 0x14000
	ds_read_b128 v[144:147], v143
	ds_read_b128 v[148:151], v143 offset:1024
	ds_read_b128 v[152:155], v143 offset:2048
	ds_read_b128 v[158:161], v143 offset:3072
	v_add_u32_e32 v143, s20, v141
	ds_read_b128 v[162:165], v143
	ds_read_b128 v[196:199], v143 offset:1024
	ds_read_b128 v[200:203], v143 offset:2048
	ds_read_b128 v[204:207], v143 offset:3072
	v_lshl_add_u64 v[176:177], v[138:139], 0, s[94:95]
	s_add_i32 m0, s16, 0xc000
	ds_read_b128 v[208:211], v142
	ds_read_b128 v[212:215], v142 offset:1024
	ds_read_b128 v[216:219], v142 offset:2048
	ds_read_b128 v[220:223], v142 offset:3072
	ds_read_b128 v[224:227], v142 offset:4096
	ds_read_b128 v[228:231], v142 offset:5120
	ds_read_b128 v[232:235], v142 offset:6144
	ds_read_b128 v[236:239], v142 offset:7168
	global_load_lds_dwordx4 v[176:177], off
	v_lshl_add_u64 v[176:177], v[136:137], 0, s[94:95]
	s_add_i32 m0, s16, 0xe000
	s_nop 0
	global_load_lds_dwordx4 v[176:177], off
	s_waitcnt vmcnt(8)
	s_waitcnt lgkmcnt(0)
	s_barrier
	s_setprio 1
	v_mfma_f32_16x16x32_bf16 v[126:129], v[144:147], v[208:211], v[126:129]
	v_mfma_f32_16x16x32_bf16 v[122:125], v[152:155], v[208:211], v[122:125]
	v_mfma_f32_16x16x32_bf16 v[118:121], v[144:147], v[216:219], v[118:121]
	v_mfma_f32_16x16x32_bf16 v[114:117], v[152:155], v[216:219], v[114:117]
	v_mfma_f32_16x16x32_bf16 v[102:105], v[144:147], v[224:227], v[102:105]
	v_mfma_f32_16x16x32_bf16 v[98:101], v[152:155], v[224:227], v[98:101]
	v_mfma_f32_16x16x32_bf16 v[86:89], v[144:147], v[232:235], v[86:89]
	v_mfma_f32_16x16x32_bf16 v[82:85], v[152:155], v[232:235], v[82:85]
	s_setprio 0
	s_setprio 1
	v_mfma_f32_16x16x32_bf16 v[126:129], v[148:151], v[212:215], v[126:129]
	v_mfma_f32_16x16x32_bf16 v[122:125], v[158:161], v[212:215], v[122:125]
	v_mfma_f32_16x16x32_bf16 v[118:121], v[148:151], v[220:223], v[118:121]
	v_mfma_f32_16x16x32_bf16 v[114:117], v[158:161], v[220:223], v[114:117]
	v_mfma_f32_16x16x32_bf16 v[102:105], v[148:151], v[228:231], v[102:105]
	v_mfma_f32_16x16x32_bf16 v[98:101], v[158:161], v[228:231], v[98:101]
	v_mfma_f32_16x16x32_bf16 v[86:89], v[148:151], v[236:239], v[86:89]
	v_mfma_f32_16x16x32_bf16 v[82:85], v[158:161], v[236:239], v[82:85]
	s_setprio 0
	s_setprio 1
	v_mfma_f32_16x16x32_bf16 v[110:113], v[162:165], v[208:211], v[110:113]
	v_mfma_f32_16x16x32_bf16 v[106:109], v[200:203], v[208:211], v[106:109]
	v_mfma_f32_16x16x32_bf16 v[94:97], v[162:165], v[216:219], v[94:97]
	v_mfma_f32_16x16x32_bf16 v[90:93], v[200:203], v[216:219], v[90:93]
	v_mfma_f32_16x16x32_bf16 v[78:81], v[162:165], v[224:227], v[78:81]
	v_mfma_f32_16x16x32_bf16 v[74:77], v[200:203], v[224:227], v[74:77]
	v_mfma_f32_16x16x32_bf16 v[70:73], v[162:165], v[232:235], v[70:73]
	v_mfma_f32_16x16x32_bf16 v[66:69], v[200:203], v[232:235], v[66:69]
	s_setprio 0
	s_setprio 1
	v_mfma_f32_16x16x32_bf16 v[110:113], v[196:199], v[212:215], v[110:113]
	v_mfma_f32_16x16x32_bf16 v[106:109], v[204:207], v[212:215], v[106:109]
	v_mfma_f32_16x16x32_bf16 v[94:97], v[196:199], v[220:223], v[94:97]
	v_mfma_f32_16x16x32_bf16 v[90:93], v[204:207], v[220:223], v[90:93]
	v_mfma_f32_16x16x32_bf16 v[78:81], v[196:199], v[228:231], v[78:81]
	v_mfma_f32_16x16x32_bf16 v[74:77], v[204:207], v[228:231], v[74:77]
	v_mfma_f32_16x16x32_bf16 v[70:73], v[196:199], v[236:239], v[70:73]
	v_mfma_f32_16x16x32_bf16 v[66:69], v[204:207], v[236:239], v[66:69]
	s_setprio 0
	s_barrier
	s_add_i32 s59, s82, s3
	v_lshl_add_u64 v[176:177], s[96:97], 0, v[0:1]
	s_mov_b32 m0, s59
	ds_read_b128 v[208:211], v142 offset:16384
	ds_read_b128 v[212:215], v142 offset:17408
	ds_read_b128 v[216:219], v142 offset:18432
	ds_read_b128 v[220:223], v142 offset:19456
	ds_read_b128 v[224:227], v142 offset:20480
	ds_read_b128 v[228:231], v142 offset:21504
	ds_read_b128 v[232:235], v142 offset:22528
	ds_read_b128 v[236:239], v142 offset:23552
	global_load_lds_dwordx4 v[176:177], off
	s_add_i32 m0, s59, 0x2000
	s_add_u32 s82, s96, 0x580000
	v_lshl_add_u64 v[178:179], s[96:97], 0, v[134:135]
	s_addc_u32 s83, s97, 0
	s_add_i32 s20, s20, s3
	global_load_lds_dwordx4 v[178:179], off
	v_lshl_add_u64 v[194:195], s[82:83], 0, v[0:1]
	s_mov_b32 m0, s20
	v_lshl_add_u64 v[240:241], vcc, 0, v[132:133]
	global_load_lds_dwordx4 v[194:195], off
	v_lshl_add_u64 v[194:195], s[82:83], 0, v[134:135]
	s_add_i32 m0, s20, 0x2000
	s_nop 0
	global_load_lds_dwordx4 v[194:195], off
	v_lshl_add_u64 v[194:195], vcc, 0, v[130:131]
	s_mov_b32 m0, s16
	s_nop 0
	global_load_lds_dwordx4 v[194:195], off
	s_mov_b32 m0, s17
	s_nop 0
	global_load_lds_dwordx4 v[240:241], off
	s_waitcnt vmcnt(8)
	s_waitcnt lgkmcnt(0)
	s_barrier
	s_setprio 1
	v_mfma_f32_16x16x32_bf16 v[62:65], v[144:147], v[208:211], v[62:65]
	v_mfma_f32_16x16x32_bf16 v[58:61], v[152:155], v[208:211], v[58:61]
	v_mfma_f32_16x16x32_bf16 v[54:57], v[144:147], v[216:219], v[54:57]
	v_mfma_f32_16x16x32_bf16 v[50:53], v[152:155], v[216:219], v[50:53]
	v_mfma_f32_16x16x32_bf16 v[38:41], v[144:147], v[224:227], v[38:41]
	v_mfma_f32_16x16x32_bf16 v[34:37], v[152:155], v[224:227], v[34:37]
	v_mfma_f32_16x16x32_bf16 v[22:25], v[144:147], v[232:235], v[22:25]
	v_mfma_f32_16x16x32_bf16 v[18:21], v[152:155], v[232:235], v[18:21]
	s_setprio 0
	s_setprio 1
	v_mfma_f32_16x16x32_bf16 v[62:65], v[148:151], v[212:215], v[62:65]
	v_mfma_f32_16x16x32_bf16 v[58:61], v[158:161], v[212:215], v[58:61]
	v_mfma_f32_16x16x32_bf16 v[54:57], v[148:151], v[220:223], v[54:57]
	v_mfma_f32_16x16x32_bf16 v[50:53], v[158:161], v[220:223], v[50:53]
	v_mfma_f32_16x16x32_bf16 v[38:41], v[148:151], v[228:231], v[38:41]
	v_mfma_f32_16x16x32_bf16 v[34:37], v[158:161], v[228:231], v[34:37]
	v_mfma_f32_16x16x32_bf16 v[22:25], v[148:151], v[236:239], v[22:25]
	v_mfma_f32_16x16x32_bf16 v[18:21], v[158:161], v[236:239], v[18:21]
	s_setprio 0
	s_setprio 1
	v_mfma_f32_16x16x32_bf16 v[46:49], v[162:165], v[208:211], v[46:49]
	v_mfma_f32_16x16x32_bf16 v[42:45], v[200:203], v[208:211], v[42:45]
	v_mfma_f32_16x16x32_bf16 v[30:33], v[162:165], v[216:219], v[30:33]
	v_mfma_f32_16x16x32_bf16 v[26:29], v[200:203], v[216:219], v[26:29]
	v_mfma_f32_16x16x32_bf16 v[14:17], v[162:165], v[224:227], v[14:17]
	v_mfma_f32_16x16x32_bf16 v[10:13], v[200:203], v[224:227], v[10:13]
	v_mfma_f32_16x16x32_bf16 v[6:9], v[162:165], v[232:235], v[6:9]
	v_mfma_f32_16x16x32_bf16 v[2:5], v[200:203], v[232:235], v[2:5]
	s_setprio 0
	s_setprio 1
	v_mfma_f32_16x16x32_bf16 v[46:49], v[196:199], v[212:215], v[46:49]
	v_mfma_f32_16x16x32_bf16 v[42:45], v[204:207], v[212:215], v[42:45]
	v_mfma_f32_16x16x32_bf16 v[30:33], v[196:199], v[220:223], v[30:33]
	v_mfma_f32_16x16x32_bf16 v[26:29], v[204:207], v[220:223], v[26:29]
	v_mfma_f32_16x16x32_bf16 v[14:17], v[196:199], v[228:231], v[14:17]
	v_mfma_f32_16x16x32_bf16 v[10:13], v[204:207], v[228:231], v[10:13]
	v_mfma_f32_16x16x32_bf16 v[6:9], v[196:199], v[236:239], v[6:9]
	v_mfma_f32_16x16x32_bf16 v[2:5], v[204:207], v[236:239], v[2:5]
	s_setprio 0
	s_barrier
	s_add_i32 s20, 0, 0x18000
	v_add_u32_e32 v143, s20, v141
	s_add_i32 s59, 0, 0x1c000
	ds_read_b128 v[144:147], v143
	ds_read_b128 v[148:151], v143 offset:1024
	ds_read_b128 v[152:155], v143 offset:2048
	ds_read_b128 v[158:161], v143 offset:3072
	v_add_u32_e32 v143, s59, v141
	ds_read_b128 v[162:165], v143
	ds_read_b128 v[196:199], v143 offset:1024
	ds_read_b128 v[200:203], v143 offset:2048
	ds_read_b128 v[204:207], v143 offset:3072
	s_add_u32 s82, vcc_lo, 0x40000
	s_addc_u32 s83, vcc_hi, 0
	s_mov_b32 m0, s28
	v_lshl_add_u64 v[242:243], s[82:83], 0, v[130:131]
	ds_read_b128 v[208:211], v142 offset:32768
	ds_read_b128 v[212:215], v142 offset:33792
	ds_read_b128 v[216:219], v142 offset:34816
	ds_read_b128 v[220:223], v142 offset:35840
	ds_read_b128 v[224:227], v142 offset:36864
	ds_read_b128 v[228:231], v142 offset:37888
	ds_read_b128 v[232:235], v142 offset:38912
	ds_read_b128 v[236:239], v142 offset:39936
	global_load_lds_dwordx4 v[242:243], off
	v_lshl_add_u64 v[242:243], s[82:83], 0, v[132:133]
	s_mov_b32 m0, s70
	s_nop 0
	global_load_lds_dwordx4 v[242:243], off
	s_waitcnt vmcnt(8)
	s_waitcnt lgkmcnt(0)
	s_barrier
	s_setprio 1
	v_mfma_f32_16x16x32_bf16 v[126:129], v[144:147], v[208:211], v[126:129]
	v_mfma_f32_16x16x32_bf16 v[122:125], v[152:155], v[208:211], v[122:125]
	v_mfma_f32_16x16x32_bf16 v[118:121], v[144:147], v[216:219], v[118:121]
	v_mfma_f32_16x16x32_bf16 v[114:117], v[152:155], v[216:219], v[114:117]
	v_mfma_f32_16x16x32_bf16 v[102:105], v[144:147], v[224:227], v[102:105]
	v_mfma_f32_16x16x32_bf16 v[98:101], v[152:155], v[224:227], v[98:101]
	v_mfma_f32_16x16x32_bf16 v[86:89], v[144:147], v[232:235], v[86:89]
	v_mfma_f32_16x16x32_bf16 v[82:85], v[152:155], v[232:235], v[82:85]
	s_setprio 0
	s_setprio 1
	v_mfma_f32_16x16x32_bf16 v[126:129], v[148:151], v[212:215], v[126:129]
	v_mfma_f32_16x16x32_bf16 v[122:125], v[158:161], v[212:215], v[122:125]
	v_mfma_f32_16x16x32_bf16 v[118:121], v[148:151], v[220:223], v[118:121]
	v_mfma_f32_16x16x32_bf16 v[114:117], v[158:161], v[220:223], v[114:117]
	v_mfma_f32_16x16x32_bf16 v[102:105], v[148:151], v[228:231], v[102:105]
	v_mfma_f32_16x16x32_bf16 v[98:101], v[158:161], v[228:231], v[98:101]
	v_mfma_f32_16x16x32_bf16 v[86:89], v[148:151], v[236:239], v[86:89]
	v_mfma_f32_16x16x32_bf16 v[82:85], v[158:161], v[236:239], v[82:85]
	s_setprio 0
	s_setprio 1
	v_mfma_f32_16x16x32_bf16 v[110:113], v[162:165], v[208:211], v[110:113]
	v_mfma_f32_16x16x32_bf16 v[106:109], v[200:203], v[208:211], v[106:109]
	v_mfma_f32_16x16x32_bf16 v[94:97], v[162:165], v[216:219], v[94:97]
	v_mfma_f32_16x16x32_bf16 v[90:93], v[200:203], v[216:219], v[90:93]
	v_mfma_f32_16x16x32_bf16 v[78:81], v[162:165], v[224:227], v[78:81]
	v_mfma_f32_16x16x32_bf16 v[74:77], v[200:203], v[224:227], v[74:77]
	v_mfma_f32_16x16x32_bf16 v[70:73], v[162:165], v[232:235], v[70:73]
	v_mfma_f32_16x16x32_bf16 v[66:69], v[200:203], v[232:235], v[66:69]
	s_setprio 0
	s_setprio 1
	v_mfma_f32_16x16x32_bf16 v[110:113], v[196:199], v[212:215], v[110:113]
	v_mfma_f32_16x16x32_bf16 v[106:109], v[204:207], v[212:215], v[106:109]
	v_mfma_f32_16x16x32_bf16 v[94:97], v[196:199], v[220:223], v[94:97]
	v_mfma_f32_16x16x32_bf16 v[90:93], v[204:207], v[220:223], v[90:93]
	v_mfma_f32_16x16x32_bf16 v[78:81], v[196:199], v[228:231], v[78:81]
	v_mfma_f32_16x16x32_bf16 v[74:77], v[204:207], v[228:231], v[74:77]
	v_mfma_f32_16x16x32_bf16 v[70:73], v[196:199], v[236:239], v[70:73]
	v_mfma_f32_16x16x32_bf16 v[66:69], v[204:207], v[236:239], v[66:69]
	s_setprio 0
	s_barrier
	s_add_i32 s20, s20, s3
	v_lshl_add_u64 v[176:177], v[176:177], 0, s[24:25]
	s_mov_b32 m0, s20
	ds_read_b128 v[208:211], v142 offset:49152
	ds_read_b128 v[212:215], v142 offset:50176
	ds_read_b128 v[216:219], v142 offset:51200
	ds_read_b128 v[220:223], v142 offset:52224
	ds_read_b128 v[224:227], v142 offset:53248
	ds_read_b128 v[228:231], v142 offset:54272
	ds_read_b128 v[232:235], v142 offset:55296
	ds_read_b128 v[236:239], v142 offset:56320
	global_load_lds_dwordx4 v[176:177], off
	s_add_i32 m0, s20, 0x2000
	s_add_u32 s82, s96, 0x580080
	v_lshl_add_u64 v[176:177], v[178:179], 0, s[24:25]
	s_addc_u32 s83, s97, 0
	s_add_i32 s20, s59, s3
	global_load_lds_dwordx4 v[176:177], off
	v_lshl_add_u64 v[176:177], s[82:83], 0, v[0:1]
	s_mov_b32 m0, s20
	s_nop 0
	global_load_lds_dwordx4 v[176:177], off
	v_lshl_add_u64 v[176:177], s[82:83], 0, v[134:135]
	s_add_i32 m0, s20, 0x2000
	s_nop 0
	global_load_lds_dwordx4 v[176:177], off
	v_lshl_add_u64 v[176:177], v[194:195], 0, s[24:25]
	s_mov_b32 m0, s86
	s_nop 0
	global_load_lds_dwordx4 v[176:177], off
	v_lshl_add_u64 v[176:177], v[240:241], 0, s[24:25]
	s_mov_b32 m0, s87
	s_nop 0
	global_load_lds_dwordx4 v[176:177], off
	s_waitcnt vmcnt(8)
	s_waitcnt lgkmcnt(0)
	s_barrier
	s_setprio 1
	v_mfma_f32_16x16x32_bf16 v[62:65], v[144:147], v[208:211], v[62:65]
	v_mfma_f32_16x16x32_bf16 v[58:61], v[152:155], v[208:211], v[58:61]
	v_mfma_f32_16x16x32_bf16 v[54:57], v[144:147], v[216:219], v[54:57]
	v_mfma_f32_16x16x32_bf16 v[50:53], v[152:155], v[216:219], v[50:53]
	v_mfma_f32_16x16x32_bf16 v[38:41], v[144:147], v[224:227], v[38:41]
	v_mfma_f32_16x16x32_bf16 v[34:37], v[152:155], v[224:227], v[34:37]
	v_mfma_f32_16x16x32_bf16 v[22:25], v[144:147], v[232:235], v[22:25]
	v_mfma_f32_16x16x32_bf16 v[18:21], v[152:155], v[232:235], v[18:21]
	s_setprio 0
	s_setprio 1
	v_mfma_f32_16x16x32_bf16 v[62:65], v[148:151], v[212:215], v[62:65]
	v_mfma_f32_16x16x32_bf16 v[58:61], v[158:161], v[212:215], v[58:61]
	v_mfma_f32_16x16x32_bf16 v[54:57], v[148:151], v[220:223], v[54:57]
	v_mfma_f32_16x16x32_bf16 v[50:53], v[158:161], v[220:223], v[50:53]
	v_mfma_f32_16x16x32_bf16 v[38:41], v[148:151], v[228:231], v[38:41]
	v_mfma_f32_16x16x32_bf16 v[34:37], v[158:161], v[228:231], v[34:37]
	v_mfma_f32_16x16x32_bf16 v[22:25], v[148:151], v[236:239], v[22:25]
	v_mfma_f32_16x16x32_bf16 v[18:21], v[158:161], v[236:239], v[18:21]
	s_setprio 0
	s_setprio 1
	v_mfma_f32_16x16x32_bf16 v[46:49], v[162:165], v[208:211], v[46:49]
	v_mfma_f32_16x16x32_bf16 v[42:45], v[200:203], v[208:211], v[42:45]
	v_mfma_f32_16x16x32_bf16 v[30:33], v[162:165], v[216:219], v[30:33]
	v_mfma_f32_16x16x32_bf16 v[26:29], v[200:203], v[216:219], v[26:29]
	v_mfma_f32_16x16x32_bf16 v[14:17], v[162:165], v[224:227], v[14:17]
	v_mfma_f32_16x16x32_bf16 v[10:13], v[200:203], v[224:227], v[10:13]
	v_mfma_f32_16x16x32_bf16 v[6:9], v[162:165], v[232:235], v[6:9]
	v_mfma_f32_16x16x32_bf16 v[2:5], v[200:203], v[232:235], v[2:5]
	s_setprio 0
	s_setprio 1
	v_mfma_f32_16x16x32_bf16 v[46:49], v[196:199], v[212:215], v[46:49]
	v_mfma_f32_16x16x32_bf16 v[42:45], v[204:207], v[212:215], v[42:45]
	v_mfma_f32_16x16x32_bf16 v[30:33], v[196:199], v[220:223], v[30:33]
	v_mfma_f32_16x16x32_bf16 v[26:29], v[204:207], v[220:223], v[26:29]
	v_mfma_f32_16x16x32_bf16 v[14:17], v[196:199], v[228:231], v[14:17]
	v_mfma_f32_16x16x32_bf16 v[10:13], v[204:207], v[228:231], v[10:13]
	v_mfma_f32_16x16x32_bf16 v[6:9], v[196:199], v[236:239], v[6:9]
	v_mfma_f32_16x16x32_bf16 v[2:5], v[204:207], v[236:239], v[2:5]
	s_setprio 0
	s_barrier
	s_add_i32 s58, s58, 2
	s_add_u32 s94, s94, 0x100
	s_addc_u32 s95, s95, 0
	s_cmp_gt_u32 s58, 13
	s_cbranch_scc0 .LBB0_81
	s_waitcnt vmcnt(0)
	s_cmpk_lt_u32 s1, 0x100
	s_cbranch_scc0 .LBB0_84
	s_barrier

.LBB0_173:
	s_add_u32 s20, s18, 0xf5678080
	s_addc_u32 s40, s19, -1
	s_cmp_lg_u32 s47, 12
	s_cselect_b32 s20, s20, 0
	s_cselect_b32 s41, s40, 0
	s_add_u32 s42, s2, s20
	s_addc_u32 s43, s3, s41
	s_add_i32 s52, 0, 0x10000
	s_add_u32 s40, s8, s20
	v_add_u32_e32 v143, s52, v141
	s_addc_u32 s41, s9, s41
	s_add_i32 s20, 0, 0x14000
	ds_read_b128 v[144:147], v143
	ds_read_b128 v[148:151], v143 offset:1024
	ds_read_b128 v[152:155], v143 offset:2048
	ds_read_b128 v[158:161], v143 offset:3072
	v_add_u32_e32 v143, s20, v141
	ds_read_b128 v[162:165], v143
	ds_read_b128 v[196:199], v143 offset:1024
	ds_read_b128 v[200:203], v143 offset:2048
	ds_read_b128 v[204:207], v143 offset:3072
	v_lshl_add_u64 v[176:177], v[138:139], 0, s[18:19]
	s_add_i32 m0, s12, 0xc000
	ds_read_b128 v[208:211], v142
	ds_read_b128 v[212:215], v142 offset:1024
	ds_read_b128 v[216:219], v142 offset:2048
	ds_read_b128 v[220:223], v142 offset:3072
	ds_read_b128 v[224:227], v142 offset:4096
	ds_read_b128 v[228:231], v142 offset:5120
	ds_read_b128 v[232:235], v142 offset:6144
	ds_read_b128 v[236:239], v142 offset:7168
	global_load_lds_dwordx4 v[176:177], off
	v_lshl_add_u64 v[176:177], v[136:137], 0, s[18:19]
	s_add_i32 m0, s12, 0xe000
	s_nop 0
	global_load_lds_dwordx4 v[176:177], off
	s_waitcnt vmcnt(8)
	s_waitcnt lgkmcnt(0)
	s_barrier
	s_setprio 1
	v_mfma_f32_16x16x32_bf16 v[126:129], v[144:147], v[208:211], v[126:129]
	v_mfma_f32_16x16x32_bf16 v[122:125], v[152:155], v[208:211], v[122:125]
	v_mfma_f32_16x16x32_bf16 v[118:121], v[144:147], v[216:219], v[118:121]
	v_mfma_f32_16x16x32_bf16 v[114:117], v[152:155], v[216:219], v[114:117]
	v_mfma_f32_16x16x32_bf16 v[102:105], v[144:147], v[224:227], v[102:105]
	v_mfma_f32_16x16x32_bf16 v[98:101], v[152:155], v[224:227], v[98:101]
	v_mfma_f32_16x16x32_bf16 v[86:89], v[144:147], v[232:235], v[86:89]
	v_mfma_f32_16x16x32_bf16 v[82:85], v[152:155], v[232:235], v[82:85]
	s_setprio 0
	s_setprio 1
	v_mfma_f32_16x16x32_bf16 v[126:129], v[148:151], v[212:215], v[126:129]
	v_mfma_f32_16x16x32_bf16 v[122:125], v[158:161], v[212:215], v[122:125]
	v_mfma_f32_16x16x32_bf16 v[118:121], v[148:151], v[220:223], v[118:121]
	v_mfma_f32_16x16x32_bf16 v[114:117], v[158:161], v[220:223], v[114:117]
	v_mfma_f32_16x16x32_bf16 v[102:105], v[148:151], v[228:231], v[102:105]
	v_mfma_f32_16x16x32_bf16 v[98:101], v[158:161], v[228:231], v[98:101]
	v_mfma_f32_16x16x32_bf16 v[86:89], v[148:151], v[236:239], v[86:89]
	v_mfma_f32_16x16x32_bf16 v[82:85], v[158:161], v[236:239], v[82:85]
	s_setprio 0
	s_setprio 1
	v_mfma_f32_16x16x32_bf16 v[110:113], v[162:165], v[208:211], v[110:113]
	v_mfma_f32_16x16x32_bf16 v[106:109], v[200:203], v[208:211], v[106:109]
	v_mfma_f32_16x16x32_bf16 v[94:97], v[162:165], v[216:219], v[94:97]
	v_mfma_f32_16x16x32_bf16 v[90:93], v[200:203], v[216:219], v[90:93]
	v_mfma_f32_16x16x32_bf16 v[78:81], v[162:165], v[224:227], v[78:81]
	v_mfma_f32_16x16x32_bf16 v[74:77], v[200:203], v[224:227], v[74:77]
	v_mfma_f32_16x16x32_bf16 v[70:73], v[162:165], v[232:235], v[70:73]
	v_mfma_f32_16x16x32_bf16 v[66:69], v[200:203], v[232:235], v[66:69]
	s_setprio 0
	s_setprio 1
	v_mfma_f32_16x16x32_bf16 v[110:113], v[196:199], v[212:215], v[110:113]
	v_mfma_f32_16x16x32_bf16 v[106:109], v[204:207], v[212:215], v[106:109]
	v_mfma_f32_16x16x32_bf16 v[94:97], v[196:199], v[220:223], v[94:97]
	v_mfma_f32_16x16x32_bf16 v[90:93], v[204:207], v[220:223], v[90:93]
	v_mfma_f32_16x16x32_bf16 v[78:81], v[196:199], v[228:231], v[78:81]
	v_mfma_f32_16x16x32_bf16 v[74:77], v[204:207], v[228:231], v[74:77]
	v_mfma_f32_16x16x32_bf16 v[70:73], v[196:199], v[236:239], v[70:73]
	v_mfma_f32_16x16x32_bf16 v[66:69], v[204:207], v[236:239], v[66:69]
	s_setprio 0
	s_barrier
	s_add_i32 s52, s52, s11
	v_lshl_add_u64 v[176:177], s[40:41], 0, v[0:1]
	s_mov_b32 m0, s52
	ds_read_b128 v[208:211], v142 offset:16384
	ds_read_b128 v[212:215], v142 offset:17408
	ds_read_b128 v[216:219], v142 offset:18432
	ds_read_b128 v[220:223], v142 offset:19456
	ds_read_b128 v[224:227], v142 offset:20480
	ds_read_b128 v[228:231], v142 offset:21504
	ds_read_b128 v[232:235], v142 offset:22528
	ds_read_b128 v[236:239], v142 offset:23552
	global_load_lds_dwordx4 v[176:177], off
	s_add_i32 m0, s52, 0x2000
	s_add_u32 s52, s40, 0x40000
	v_lshl_add_u64 v[178:179], s[40:41], 0, v[134:135]
	s_addc_u32 s53, s41, 0
	s_add_i32 s20, s20, s11
	global_load_lds_dwordx4 v[178:179], off
	v_lshl_add_u64 v[194:195], s[52:53], 0, v[0:1]
	s_mov_b32 m0, s20
	v_lshl_add_u64 v[240:241], s[42:43], 0, v[132:133]
	global_load_lds_dwordx4 v[194:195], off
	v_lshl_add_u64 v[194:195], s[52:53], 0, v[134:135]
	s_add_i32 m0, s20, 0x2000
	s_nop 0
	global_load_lds_dwordx4 v[194:195], off
	v_lshl_add_u64 v[194:195], s[42:43], 0, v[130:131]
	s_mov_b32 m0, s12
	s_nop 0
	global_load_lds_dwordx4 v[194:195], off
	s_mov_b32 m0, s13
	s_nop 0
	global_load_lds_dwordx4 v[240:241], off
	s_waitcnt vmcnt(8)
	s_waitcnt lgkmcnt(0)
	s_barrier
	s_setprio 1
	v_mfma_f32_16x16x32_bf16 v[62:65], v[144:147], v[208:211], v[62:65]
	v_mfma_f32_16x16x32_bf16 v[58:61], v[152:155], v[208:211], v[58:61]
	v_mfma_f32_16x16x32_bf16 v[54:57], v[144:147], v[216:219], v[54:57]
	v_mfma_f32_16x16x32_bf16 v[50:53], v[152:155], v[216:219], v[50:53]
	v_mfma_f32_16x16x32_bf16 v[38:41], v[144:147], v[224:227], v[38:41]
	v_mfma_f32_16x16x32_bf16 v[34:37], v[152:155], v[224:227], v[34:37]
	v_mfma_f32_16x16x32_bf16 v[22:25], v[144:147], v[232:235], v[22:25]
	v_mfma_f32_16x16x32_bf16 v[18:21], v[152:155], v[232:235], v[18:21]
	s_setprio 0
	s_setprio 1
	v_mfma_f32_16x16x32_bf16 v[62:65], v[148:151], v[212:215], v[62:65]
	v_mfma_f32_16x16x32_bf16 v[58:61], v[158:161], v[212:215], v[58:61]
	v_mfma_f32_16x16x32_bf16 v[54:57], v[148:151], v[220:223], v[54:57]
	v_mfma_f32_16x16x32_bf16 v[50:53], v[158:161], v[220:223], v[50:53]
	v_mfma_f32_16x16x32_bf16 v[38:41], v[148:151], v[228:231], v[38:41]
	v_mfma_f32_16x16x32_bf16 v[34:37], v[158:161], v[228:231], v[34:37]
	v_mfma_f32_16x16x32_bf16 v[22:25], v[148:151], v[236:239], v[22:25]
	v_mfma_f32_16x16x32_bf16 v[18:21], v[158:161], v[236:239], v[18:21]
	s_setprio 0
	s_setprio 1
	v_mfma_f32_16x16x32_bf16 v[46:49], v[162:165], v[208:211], v[46:49]
	v_mfma_f32_16x16x32_bf16 v[42:45], v[200:203], v[208:211], v[42:45]
	v_mfma_f32_16x16x32_bf16 v[30:33], v[162:165], v[216:219], v[30:33]
	v_mfma_f32_16x16x32_bf16 v[26:29], v[200:203], v[216:219], v[26:29]
	v_mfma_f32_16x16x32_bf16 v[14:17], v[162:165], v[224:227], v[14:17]
	v_mfma_f32_16x16x32_bf16 v[10:13], v[200:203], v[224:227], v[10:13]
	v_mfma_f32_16x16x32_bf16 v[6:9], v[162:165], v[232:235], v[6:9]
	v_mfma_f32_16x16x32_bf16 v[2:5], v[200:203], v[232:235], v[2:5]
	s_setprio 0
	s_setprio 1
	v_mfma_f32_16x16x32_bf16 v[46:49], v[196:199], v[212:215], v[46:49]
	v_mfma_f32_16x16x32_bf16 v[42:45], v[204:207], v[212:215], v[42:45]
	v_mfma_f32_16x16x32_bf16 v[30:33], v[196:199], v[220:223], v[30:33]
	v_mfma_f32_16x16x32_bf16 v[26:29], v[204:207], v[220:223], v[26:29]
	v_mfma_f32_16x16x32_bf16 v[14:17], v[196:199], v[228:231], v[14:17]
	v_mfma_f32_16x16x32_bf16 v[10:13], v[204:207], v[228:231], v[10:13]
	v_mfma_f32_16x16x32_bf16 v[6:9], v[196:199], v[236:239], v[6:9]
	v_mfma_f32_16x16x32_bf16 v[2:5], v[204:207], v[236:239], v[2:5]
	s_setprio 0
	s_barrier
	s_add_i32 s20, 0, 0x18000
	v_add_u32_e32 v143, s20, v141
	s_add_i32 s52, 0, 0x1c000
	ds_read_b128 v[144:147], v143
	ds_read_b128 v[148:151], v143 offset:1024
	ds_read_b128 v[152:155], v143 offset:2048
	ds_read_b128 v[158:161], v143 offset:3072
	v_add_u32_e32 v143, s52, v141
	ds_read_b128 v[162:165], v143
	ds_read_b128 v[196:199], v143 offset:1024
	ds_read_b128 v[200:203], v143 offset:2048
	ds_read_b128 v[204:207], v143 offset:3072
	s_add_u32 s42, s42, 0x40000
	s_addc_u32 s43, s43, 0
	s_mov_b32 m0, s16
	v_lshl_add_u64 v[242:243], s[42:43], 0, v[130:131]
	ds_read_b128 v[208:211], v142 offset:32768
	ds_read_b128 v[212:215], v142 offset:33792
	ds_read_b128 v[216:219], v142 offset:34816
	ds_read_b128 v[220:223], v142 offset:35840
	ds_read_b128 v[224:227], v142 offset:36864
	ds_read_b128 v[228:231], v142 offset:37888
	ds_read_b128 v[232:235], v142 offset:38912
	ds_read_b128 v[236:239], v142 offset:39936
	global_load_lds_dwordx4 v[242:243], off
	v_lshl_add_u64 v[242:243], s[42:43], 0, v[132:133]
	s_mov_b32 m0, s17
	s_nop 0
	global_load_lds_dwordx4 v[242:243], off
	s_waitcnt vmcnt(8)
	s_waitcnt lgkmcnt(0)
	s_barrier
	s_setprio 1
	v_mfma_f32_16x16x32_bf16 v[126:129], v[144:147], v[208:211], v[126:129]
	v_mfma_f32_16x16x32_bf16 v[122:125], v[152:155], v[208:211], v[122:125]
	v_mfma_f32_16x16x32_bf16 v[118:121], v[144:147], v[216:219], v[118:121]
	v_mfma_f32_16x16x32_bf16 v[114:117], v[152:155], v[216:219], v[114:117]
	v_mfma_f32_16x16x32_bf16 v[102:105], v[144:147], v[224:227], v[102:105]
	v_mfma_f32_16x16x32_bf16 v[98:101], v[152:155], v[224:227], v[98:101]
	v_mfma_f32_16x16x32_bf16 v[86:89], v[144:147], v[232:235], v[86:89]
	v_mfma_f32_16x16x32_bf16 v[82:85], v[152:155], v[232:235], v[82:85]
	s_setprio 0
	s_setprio 1
	v_mfma_f32_16x16x32_bf16 v[126:129], v[148:151], v[212:215], v[126:129]
	v_mfma_f32_16x16x32_bf16 v[122:125], v[158:161], v[212:215], v[122:125]
	v_mfma_f32_16x16x32_bf16 v[118:121], v[148:151], v[220:223], v[118:121]
	v_mfma_f32_16x16x32_bf16 v[114:117], v[158:161], v[220:223], v[114:117]
	v_mfma_f32_16x16x32_bf16 v[102:105], v[148:151], v[228:231], v[102:105]
	v_mfma_f32_16x16x32_bf16 v[98:101], v[158:161], v[228:231], v[98:101]
	v_mfma_f32_16x16x32_bf16 v[86:89], v[148:151], v[236:239], v[86:89]
	v_mfma_f32_16x16x32_bf16 v[82:85], v[158:161], v[236:239], v[82:85]
	s_setprio 0
	s_setprio 1
	v_mfma_f32_16x16x32_bf16 v[110:113], v[162:165], v[208:211], v[110:113]
	v_mfma_f32_16x16x32_bf16 v[106:109], v[200:203], v[208:211], v[106:109]
	v_mfma_f32_16x16x32_bf16 v[94:97], v[162:165], v[216:219], v[94:97]
	v_mfma_f32_16x16x32_bf16 v[90:93], v[200:203], v[216:219], v[90:93]
	v_mfma_f32_16x16x32_bf16 v[78:81], v[162:165], v[224:227], v[78:81]
	v_mfma_f32_16x16x32_bf16 v[74:77], v[200:203], v[224:227], v[74:77]
	v_mfma_f32_16x16x32_bf16 v[70:73], v[162:165], v[232:235], v[70:73]
	v_mfma_f32_16x16x32_bf16 v[66:69], v[200:203], v[232:235], v[66:69]
	s_setprio 0
	s_setprio 1
	v_mfma_f32_16x16x32_bf16 v[110:113], v[196:199], v[212:215], v[110:113]
	v_mfma_f32_16x16x32_bf16 v[106:109], v[204:207], v[212:215], v[106:109]
	v_mfma_f32_16x16x32_bf16 v[94:97], v[196:199], v[220:223], v[94:97]
	v_mfma_f32_16x16x32_bf16 v[90:93], v[204:207], v[220:223], v[90:93]
	v_mfma_f32_16x16x32_bf16 v[78:81], v[196:199], v[228:231], v[78:81]
	v_mfma_f32_16x16x32_bf16 v[74:77], v[204:207], v[228:231], v[74:77]
	v_mfma_f32_16x16x32_bf16 v[70:73], v[196:199], v[236:239], v[70:73]
	v_mfma_f32_16x16x32_bf16 v[66:69], v[204:207], v[236:239], v[66:69]
	s_setprio 0
	s_barrier
	s_add_i32 s20, s20, s11
	v_lshl_add_u64 v[176:177], v[176:177], 0, s[24:25]
	s_mov_b32 m0, s20
	ds_read_b128 v[208:211], v142 offset:49152
	ds_read_b128 v[212:215], v142 offset:50176
	ds_read_b128 v[216:219], v142 offset:51200
	ds_read_b128 v[220:223], v142 offset:52224
	ds_read_b128 v[224:227], v142 offset:53248
	ds_read_b128 v[228:231], v142 offset:54272
	ds_read_b128 v[232:235], v142 offset:55296
	ds_read_b128 v[236:239], v142 offset:56320
	global_load_lds_dwordx4 v[176:177], off
	s_add_i32 m0, s20, 0x2000
	s_add_u32 s40, s40, 0x40080
	v_lshl_add_u64 v[176:177], v[178:179], 0, s[24:25]
	s_addc_u32 s41, s41, 0
	s_add_i32 s20, s52, s11
	global_load_lds_dwordx4 v[176:177], off
	v_lshl_add_u64 v[176:177], s[40:41], 0, v[0:1]
	s_mov_b32 m0, s20
	s_nop 0
	global_load_lds_dwordx4 v[176:177], off
	v_lshl_add_u64 v[176:177], s[40:41], 0, v[134:135]
	s_add_i32 m0, s20, 0x2000
	s_nop 0
	global_load_lds_dwordx4 v[176:177], off
	v_lshl_add_u64 v[176:177], v[194:195], 0, s[24:25]
	s_mov_b32 m0, s28
	s_nop 0
	global_load_lds_dwordx4 v[176:177], off
	v_lshl_add_u64 v[176:177], v[240:241], 0, s[24:25]
	s_mov_b32 m0, s46
	s_nop 0
	global_load_lds_dwordx4 v[176:177], off
	s_waitcnt vmcnt(8)
	s_waitcnt lgkmcnt(0)
	s_barrier
	s_setprio 1
	v_mfma_f32_16x16x32_bf16 v[62:65], v[144:147], v[208:211], v[62:65]
	v_mfma_f32_16x16x32_bf16 v[58:61], v[152:155], v[208:211], v[58:61]
	v_mfma_f32_16x16x32_bf16 v[54:57], v[144:147], v[216:219], v[54:57]
	v_mfma_f32_16x16x32_bf16 v[50:53], v[152:155], v[216:219], v[50:53]
	v_mfma_f32_16x16x32_bf16 v[38:41], v[144:147], v[224:227], v[38:41]
	v_mfma_f32_16x16x32_bf16 v[34:37], v[152:155], v[224:227], v[34:37]
	v_mfma_f32_16x16x32_bf16 v[22:25], v[144:147], v[232:235], v[22:25]
	v_mfma_f32_16x16x32_bf16 v[18:21], v[152:155], v[232:235], v[18:21]
	s_setprio 0
	s_setprio 1
	v_mfma_f32_16x16x32_bf16 v[62:65], v[148:151], v[212:215], v[62:65]
	v_mfma_f32_16x16x32_bf16 v[58:61], v[158:161], v[212:215], v[58:61]
	v_mfma_f32_16x16x32_bf16 v[54:57], v[148:151], v[220:223], v[54:57]
	v_mfma_f32_16x16x32_bf16 v[50:53], v[158:161], v[220:223], v[50:53]
	v_mfma_f32_16x16x32_bf16 v[38:41], v[148:151], v[228:231], v[38:41]
	v_mfma_f32_16x16x32_bf16 v[34:37], v[158:161], v[228:231], v[34:37]
	v_mfma_f32_16x16x32_bf16 v[22:25], v[148:151], v[236:239], v[22:25]
	v_mfma_f32_16x16x32_bf16 v[18:21], v[158:161], v[236:239], v[18:21]
	s_setprio 0
	s_setprio 1
	v_mfma_f32_16x16x32_bf16 v[46:49], v[162:165], v[208:211], v[46:49]
	v_mfma_f32_16x16x32_bf16 v[42:45], v[200:203], v[208:211], v[42:45]
	v_mfma_f32_16x16x32_bf16 v[30:33], v[162:165], v[216:219], v[30:33]
	v_mfma_f32_16x16x32_bf16 v[26:29], v[200:203], v[216:219], v[26:29]
	v_mfma_f32_16x16x32_bf16 v[14:17], v[162:165], v[224:227], v[14:17]
	v_mfma_f32_16x16x32_bf16 v[10:13], v[200:203], v[224:227], v[10:13]
	v_mfma_f32_16x16x32_bf16 v[6:9], v[162:165], v[232:235], v[6:9]
	v_mfma_f32_16x16x32_bf16 v[2:5], v[200:203], v[232:235], v[2:5]
	s_setprio 0
	s_setprio 1
	v_mfma_f32_16x16x32_bf16 v[46:49], v[196:199], v[212:215], v[46:49]
	v_mfma_f32_16x16x32_bf16 v[42:45], v[204:207], v[212:215], v[42:45]
	v_mfma_f32_16x16x32_bf16 v[30:33], v[196:199], v[220:223], v[30:33]
	v_mfma_f32_16x16x32_bf16 v[26:29], v[204:207], v[220:223], v[26:29]
	v_mfma_f32_16x16x32_bf16 v[14:17], v[196:199], v[228:231], v[14:17]
	v_mfma_f32_16x16x32_bf16 v[10:13], v[204:207], v[228:231], v[10:13]
	v_mfma_f32_16x16x32_bf16 v[6:9], v[196:199], v[236:239], v[6:9]
	v_mfma_f32_16x16x32_bf16 v[2:5], v[204:207], v[236:239], v[2:5]
	s_setprio 0
	s_barrier
	s_add_i32 s47, s47, 2
	s_add_u32 s18, s18, 0x100
	s_addc_u32 s19, s19, 0
	s_cmp_gt_u32 s47, 13
	s_cbranch_scc0 .LBB0_173
	s_waitcnt vmcnt(0)
	s_cmpk_lt_u32 s1, 0x100
	s_cbranch_scc0 .LBB0_169
	s_barrier
	s_branch .LBB0_169

.LBB0_336:
	s_add_u32 s20, s12, s56
	s_addc_u32 s58, s13, s57
	s_cmpk_eq_i32 s56, 0x700
	s_cselect_b64 s[6:7], -1, 0
	s_and_b64 s[10:11], s[6:7], exec
	s_cselect_b32 s62, vcc_lo, s20
	s_cselect_b32 s63, s97, s58
	s_and_b64 s[66:67], s[2:3], s[6:7]
	s_and_b64 s[6:7], s[66:67], exec
	s_cselect_b32 s10, s86, s40
	s_add_u32 s6, s16, s56
	s_addc_u32 s7, s17, s57
	s_add_u32 s11, s6, 0x3148100
	s_addc_u32 s20, s7, 0
	s_cmpk_eq_i32 s56, 0x700
	s_cselect_b64 s[6:7], -1, 0
	s_and_b64 s[6:7], s[6:7], exec
	s_cselect_b32 s58, s10, s11
	s_and_b64 s[6:7], s[66:67], exec
	s_cselect_b32 s10, s93, s41
	s_cmpk_eq_i32 s56, 0x700
	s_cselect_b64 s[84:85], -1, 0
	s_and_b64 s[6:7], s[84:85], exec
	s_cselect_b32 s59, s10, s20
	s_and_b64 s[6:7], s[66:67], exec
	s_mov_b32 s6, 0x20000
	s_cselect_b32 s66, s6, 0x40000
	s_cselect_b32 s10, 9, 10
	s_add_i32 s6, 0, 0x10000
	v_add_u32_e32 v154, s6, v143
	s_add_i32 s7, 0, 0x14000
	ds_read_b128 v[146:149], v154
	ds_read_b128 v[150:153], v154 offset:1024
	ds_read_b128 v[158:161], v154 offset:2048
	ds_read_b128 v[162:165], v154 offset:3072
	v_add_u32_e32 v154, s7, v143
	ds_read_b128 v[196:199], v154
	ds_read_b128 v[200:203], v154 offset:1024
	ds_read_b128 v[204:207], v154 offset:2048
	ds_read_b128 v[208:211], v154 offset:3072
	v_lshlrev_b32_e32 v0, s10, v134
	v_lshlrev_b32_e32 v145, s10, v136
	v_lshlrev_b32_e32 v155, s10, v138
	v_lshlrev_b32_e32 v157, s10, v139
	v_add_lshl_u32 v154, v0, v135, 1
	v_add_lshl_u32 v0, v155, v135, 1
	v_add_lshl_u32 v244, v145, v137, 1
	s_add_i32 s20, s87, 0
	v_lshl_add_u64 v[246:247], v[132:133], 0, s[56:57]
	s_add_i32 m0, s20, 0xc000
	ds_read_b128 v[212:215], v144
	ds_read_b128 v[216:219], v144 offset:1024
	ds_read_b128 v[220:223], v144 offset:2048
	ds_read_b128 v[224:227], v144 offset:3072
	ds_read_b128 v[228:231], v144 offset:4096
	ds_read_b128 v[232:235], v144 offset:5120
	ds_read_b128 v[236:239], v144 offset:6144
	ds_read_b128 v[240:243], v144 offset:7168
	global_load_lds_dwordx4 v[246:247], off
	v_lshl_add_u64 v[246:247], v[130:131], 0, s[56:57]
	s_add_i32 m0, s20, 0xe000
	s_nop 0
	global_load_lds_dwordx4 v[246:247], off
	s_waitcnt vmcnt(8)
	s_waitcnt lgkmcnt(0)
	s_barrier
	s_setprio 1
	v_mfma_f32_16x16x32_bf16 v[126:129], v[146:149], v[212:215], v[126:129]
	v_mfma_f32_16x16x32_bf16 v[122:125], v[158:161], v[212:215], v[122:125]
	v_mfma_f32_16x16x32_bf16 v[110:113], v[146:149], v[220:223], v[110:113]
	v_mfma_f32_16x16x32_bf16 v[106:109], v[158:161], v[220:223], v[106:109]
	v_mfma_f32_16x16x32_bf16 v[94:97], v[146:149], v[228:231], v[94:97]
	v_mfma_f32_16x16x32_bf16 v[90:93], v[158:161], v[228:231], v[90:93]
	v_mfma_f32_16x16x32_bf16 v[78:81], v[146:149], v[236:239], v[78:81]
	v_mfma_f32_16x16x32_bf16 v[74:77], v[158:161], v[236:239], v[74:77]
	s_setprio 0
	s_setprio 1
	v_mfma_f32_16x16x32_bf16 v[126:129], v[150:153], v[216:219], v[126:129]
	v_mfma_f32_16x16x32_bf16 v[122:125], v[162:165], v[216:219], v[122:125]
	v_mfma_f32_16x16x32_bf16 v[110:113], v[150:153], v[224:227], v[110:113]
	v_mfma_f32_16x16x32_bf16 v[106:109], v[162:165], v[224:227], v[106:109]
	v_mfma_f32_16x16x32_bf16 v[94:97], v[150:153], v[232:235], v[94:97]
	v_mfma_f32_16x16x32_bf16 v[90:93], v[162:165], v[232:235], v[90:93]
	v_mfma_f32_16x16x32_bf16 v[78:81], v[150:153], v[240:243], v[78:81]
	v_mfma_f32_16x16x32_bf16 v[74:77], v[162:165], v[240:243], v[74:77]
	s_setprio 0
	s_setprio 1
	v_mfma_f32_16x16x32_bf16 v[118:121], v[196:199], v[212:215], v[118:121]
	v_mfma_f32_16x16x32_bf16 v[114:117], v[204:207], v[212:215], v[114:117]
	v_mfma_f32_16x16x32_bf16 v[102:105], v[196:199], v[220:223], v[102:105]
	v_mfma_f32_16x16x32_bf16 v[98:101], v[204:207], v[220:223], v[98:101]
	v_mfma_f32_16x16x32_bf16 v[86:89], v[196:199], v[228:231], v[86:89]
	v_mfma_f32_16x16x32_bf16 v[82:85], v[204:207], v[228:231], v[82:85]
	v_mfma_f32_16x16x32_bf16 v[70:73], v[196:199], v[236:239], v[70:73]
	v_mfma_f32_16x16x32_bf16 v[66:69], v[204:207], v[236:239], v[66:69]
	s_setprio 0
	s_setprio 1
	v_mfma_f32_16x16x32_bf16 v[118:121], v[200:203], v[216:219], v[118:121]
	v_mfma_f32_16x16x32_bf16 v[114:117], v[208:211], v[216:219], v[114:117]
	v_mfma_f32_16x16x32_bf16 v[102:105], v[200:203], v[224:227], v[102:105]
	v_mfma_f32_16x16x32_bf16 v[98:101], v[208:211], v[224:227], v[98:101]
	v_mfma_f32_16x16x32_bf16 v[86:89], v[200:203], v[232:235], v[86:89]
	v_mfma_f32_16x16x32_bf16 v[82:85], v[208:211], v[232:235], v[82:85]
	v_mfma_f32_16x16x32_bf16 v[70:73], v[200:203], v[240:243], v[70:73]
	v_mfma_f32_16x16x32_bf16 v[66:69], v[208:211], v[240:243], v[66:69]
	s_setprio 0
	s_barrier
	s_add_i32 s10, s6, s87
	s_mov_b32 m0, s10
	ds_read_b128 v[212:215], v144 offset:16384
	ds_read_b128 v[216:219], v144 offset:17408
	ds_read_b128 v[220:223], v144 offset:18432
	ds_read_b128 v[224:227], v144 offset:19456
	ds_read_b128 v[228:231], v144 offset:20480
	ds_read_b128 v[232:235], v144 offset:21504
	ds_read_b128 v[236:239], v144 offset:22528
	ds_read_b128 v[240:243], v144 offset:23552
	global_load_lds_dwordx4 v0, s[62:63]
	s_add_i32 m0, s10, 0x2000
	v_add_lshl_u32 v246, v157, v137, 1
	v_mov_b32_e32 v247, v1
	s_add_u32 s10, s62, s66
	v_lshl_add_u64 v[248:249], s[62:63], 0, v[0:1]
	v_lshl_add_u64 v[250:251], s[62:63], 0, v[246:247]
	global_load_lds_dwordx4 v246, s[62:63]
	s_addc_u32 s11, s63, 0
	s_add_i32 s62, s7, s87
	s_mov_b32 m0, s62
	v_mov_b32_e32 v155, v1
	global_load_lds_dwordx4 v0, s[10:11]
	s_add_i32 m0, s62, 0x2000
	v_mov_b32_e32 v245, v1
	global_load_lds_dwordx4 v246, s[10:11]
	s_mov_b32 m0, s20
	v_lshl_add_u64 v[194:195], s[10:11], 0, v[0:1]
	global_load_lds_dwordx4 v154, s[58:59]
	s_add_i32 m0, s20, 0x2000
	v_lshl_add_u64 v[176:177], s[10:11], 0, v[246:247]
	global_load_lds_dwordx4 v244, s[58:59]
	s_waitcnt vmcnt(8)
	s_waitcnt lgkmcnt(0)
	v_lshl_add_u64 v[246:247], s[58:59], 0, v[154:155]
	v_lshl_add_u64 v[178:179], s[58:59], 0, v[244:245]
	s_barrier
	s_setprio 1
	s_waitcnt lgkmcnt(0)
	v_mfma_f32_16x16x32_bf16 v[62:65], v[146:149], v[212:215], v[62:65]
	v_mfma_f32_16x16x32_bf16 v[58:61], v[158:161], v[212:215], v[58:61]
	v_mfma_f32_16x16x32_bf16 v[46:49], v[146:149], v[220:223], v[46:49]
	v_mfma_f32_16x16x32_bf16 v[42:45], v[158:161], v[220:223], v[42:45]
	v_mfma_f32_16x16x32_bf16 v[30:33], v[146:149], v[228:231], v[30:33]
	v_mfma_f32_16x16x32_bf16 v[26:29], v[158:161], v[228:231], v[26:29]
	v_mfma_f32_16x16x32_bf16 v[14:17], v[146:149], v[236:239], v[14:17]
	v_mfma_f32_16x16x32_bf16 v[10:13], v[158:161], v[236:239], v[10:13]
	s_setprio 0
	s_setprio 1
	v_mfma_f32_16x16x32_bf16 v[62:65], v[150:153], v[216:219], v[62:65]
	v_mfma_f32_16x16x32_bf16 v[58:61], v[162:165], v[216:219], v[58:61]
	v_mfma_f32_16x16x32_bf16 v[46:49], v[150:153], v[224:227], v[46:49]
	v_mfma_f32_16x16x32_bf16 v[42:45], v[162:165], v[224:227], v[42:45]
	v_mfma_f32_16x16x32_bf16 v[30:33], v[150:153], v[232:235], v[30:33]
	v_mfma_f32_16x16x32_bf16 v[26:29], v[162:165], v[232:235], v[26:29]
	v_mfma_f32_16x16x32_bf16 v[14:17], v[150:153], v[240:243], v[14:17]
	v_mfma_f32_16x16x32_bf16 v[10:13], v[162:165], v[240:243], v[10:13]
	s_setprio 0
	s_setprio 1
	v_mfma_f32_16x16x32_bf16 v[54:57], v[196:199], v[212:215], v[54:57]
	v_mfma_f32_16x16x32_bf16 v[50:53], v[204:207], v[212:215], v[50:53]
	v_mfma_f32_16x16x32_bf16 v[38:41], v[196:199], v[220:223], v[38:41]
	v_mfma_f32_16x16x32_bf16 v[34:37], v[204:207], v[220:223], v[34:37]
	v_mfma_f32_16x16x32_bf16 v[22:25], v[196:199], v[228:231], v[22:25]
	v_mfma_f32_16x16x32_bf16 v[18:21], v[204:207], v[228:231], v[18:21]
	v_mfma_f32_16x16x32_bf16 v[6:9], v[196:199], v[236:239], v[6:9]
	v_mfma_f32_16x16x32_bf16 v[2:5], v[204:207], v[236:239], v[2:5]
	s_setprio 0
	s_setprio 1
	v_mfma_f32_16x16x32_bf16 v[54:57], v[200:203], v[216:219], v[54:57]
	v_mfma_f32_16x16x32_bf16 v[50:53], v[208:211], v[216:219], v[50:53]
	v_mfma_f32_16x16x32_bf16 v[38:41], v[200:203], v[224:227], v[38:41]
	v_mfma_f32_16x16x32_bf16 v[34:37], v[208:211], v[224:227], v[34:37]
	v_mfma_f32_16x16x32_bf16 v[22:25], v[200:203], v[232:235], v[22:25]
	v_mfma_f32_16x16x32_bf16 v[18:21], v[208:211], v[232:235], v[18:21]
	v_mfma_f32_16x16x32_bf16 v[6:9], v[200:203], v[240:243], v[6:9]
	v_mfma_f32_16x16x32_bf16 v[2:5], v[208:211], v[240:243], v[2:5]
	s_setprio 0
	s_barrier
	s_add_i32 s10, 0, 0x18000
	v_add_u32_e32 v0, s10, v143
	s_add_i32 s11, 0, 0x1c000
	ds_read_b128 v[146:149], v0
	ds_read_b128 v[150:153], v0 offset:1024
	ds_read_b128 v[158:161], v0 offset:2048
	ds_read_b128 v[162:165], v0 offset:3072
	v_add_u32_e32 v0, s11, v143
	ds_read_b128 v[196:199], v0
	ds_read_b128 v[200:203], v0 offset:1024
	ds_read_b128 v[204:207], v0 offset:2048
	ds_read_b128 v[208:211], v0 offset:3072
	s_add_u32 s58, s58, s66
	s_addc_u32 s59, s59, 0
	s_add_i32 m0, s20, 0x4000
	ds_read_b128 v[212:215], v144 offset:32768
	ds_read_b128 v[216:219], v144 offset:33792
	ds_read_b128 v[220:223], v144 offset:34816
	ds_read_b128 v[224:227], v144 offset:35840
	ds_read_b128 v[228:231], v144 offset:36864
	ds_read_b128 v[232:235], v144 offset:37888
	ds_read_b128 v[236:239], v144 offset:38912
	ds_read_b128 v[240:243], v144 offset:39936
	global_load_lds_dwordx4 v154, s[58:59]
	s_add_i32 m0, s20, 0x6000
	s_nop 0
	global_load_lds_dwordx4 v244, s[58:59]
	s_waitcnt vmcnt(8)
	s_waitcnt lgkmcnt(0)
	s_barrier
	s_setprio 1
	v_mfma_f32_16x16x32_bf16 v[126:129], v[146:149], v[212:215], v[126:129]
	v_mfma_f32_16x16x32_bf16 v[122:125], v[158:161], v[212:215], v[122:125]
	v_mfma_f32_16x16x32_bf16 v[110:113], v[146:149], v[220:223], v[110:113]
	v_mfma_f32_16x16x32_bf16 v[106:109], v[158:161], v[220:223], v[106:109]
	v_mfma_f32_16x16x32_bf16 v[94:97], v[146:149], v[228:231], v[94:97]
	v_mfma_f32_16x16x32_bf16 v[90:93], v[158:161], v[228:231], v[90:93]
	v_mfma_f32_16x16x32_bf16 v[78:81], v[146:149], v[236:239], v[78:81]
	v_mfma_f32_16x16x32_bf16 v[74:77], v[158:161], v[236:239], v[74:77]
	s_setprio 0
	s_setprio 1
	v_mfma_f32_16x16x32_bf16 v[126:129], v[150:153], v[216:219], v[126:129]
	v_mfma_f32_16x16x32_bf16 v[122:125], v[162:165], v[216:219], v[122:125]
	v_mfma_f32_16x16x32_bf16 v[110:113], v[150:153], v[224:227], v[110:113]
	v_mfma_f32_16x16x32_bf16 v[106:109], v[162:165], v[224:227], v[106:109]
	v_mfma_f32_16x16x32_bf16 v[94:97], v[150:153], v[232:235], v[94:97]
	v_mfma_f32_16x16x32_bf16 v[90:93], v[162:165], v[232:235], v[90:93]
	v_mfma_f32_16x16x32_bf16 v[78:81], v[150:153], v[240:243], v[78:81]
	v_mfma_f32_16x16x32_bf16 v[74:77], v[162:165], v[240:243], v[74:77]
	s_setprio 0
	s_setprio 1
	v_mfma_f32_16x16x32_bf16 v[118:121], v[196:199], v[212:215], v[118:121]
	v_mfma_f32_16x16x32_bf16 v[114:117], v[204:207], v[212:215], v[114:117]
	v_mfma_f32_16x16x32_bf16 v[102:105], v[196:199], v[220:223], v[102:105]
	v_mfma_f32_16x16x32_bf16 v[98:101], v[204:207], v[220:223], v[98:101]
	v_mfma_f32_16x16x32_bf16 v[86:89], v[196:199], v[228:231], v[86:89]
	v_mfma_f32_16x16x32_bf16 v[82:85], v[204:207], v[228:231], v[82:85]
	v_mfma_f32_16x16x32_bf16 v[70:73], v[196:199], v[236:239], v[70:73]
	v_mfma_f32_16x16x32_bf16 v[66:69], v[204:207], v[236:239], v[66:69]
	s_setprio 0
	s_setprio 1
	v_mfma_f32_16x16x32_bf16 v[118:121], v[200:203], v[216:219], v[118:121]
	v_mfma_f32_16x16x32_bf16 v[114:117], v[208:211], v[216:219], v[114:117]
	v_mfma_f32_16x16x32_bf16 v[102:105], v[200:203], v[224:227], v[102:105]
	v_mfma_f32_16x16x32_bf16 v[98:101], v[208:211], v[224:227], v[98:101]
	v_mfma_f32_16x16x32_bf16 v[86:89], v[200:203], v[232:235], v[86:89]
	v_mfma_f32_16x16x32_bf16 v[82:85], v[208:211], v[232:235], v[82:85]
	v_mfma_f32_16x16x32_bf16 v[70:73], v[200:203], v[240:243], v[70:73]
	v_mfma_f32_16x16x32_bf16 v[66:69], v[208:211], v[240:243], v[66:69]
	s_setprio 0
	s_barrier
	s_add_i32 s58, s10, s87
	v_lshl_add_u64 v[154:155], v[248:249], 0, s[24:25]
	s_mov_b32 m0, s58
	ds_read_b128 v[212:215], v144 offset:49152
	ds_read_b128 v[216:219], v144 offset:50176
	ds_read_b128 v[220:223], v144 offset:51200
	ds_read_b128 v[224:227], v144 offset:52224
	ds_read_b128 v[228:231], v144 offset:53248
	ds_read_b128 v[232:235], v144 offset:54272
	ds_read_b128 v[236:239], v144 offset:55296
	ds_read_b128 v[240:243], v144 offset:56320
	global_load_lds_dwordx4 v[154:155], off
	v_lshl_add_u64 v[154:155], v[250:251], 0, s[24:25]
	s_add_i32 m0, s58, 0x2000
	s_add_i32 s58, s11, s87
	global_load_lds_dwordx4 v[154:155], off
	v_lshl_add_u64 v[154:155], v[194:195], 0, s[24:25]
	s_mov_b32 m0, s58
	s_nop 0
	global_load_lds_dwordx4 v[154:155], off
	v_lshl_add_u64 v[154:155], v[176:177], 0, s[24:25]
	s_add_i32 m0, s58, 0x2000
	s_nop 0
	global_load_lds_dwordx4 v[154:155], off
	v_lshl_add_u64 v[154:155], v[246:247], 0, s[24:25]
	s_add_i32 m0, s20, 0x8000
	s_nop 0
	global_load_lds_dwordx4 v[154:155], off
	v_lshl_add_u64 v[154:155], v[178:179], 0, s[24:25]
	s_add_i32 m0, s20, 0xa000
	s_nop 0
	global_load_lds_dwordx4 v[154:155], off
	s_waitcnt vmcnt(8)
	s_waitcnt lgkmcnt(0)
	s_barrier
	s_setprio 1
	v_mfma_f32_16x16x32_bf16 v[62:65], v[146:149], v[212:215], v[62:65]
	v_mfma_f32_16x16x32_bf16 v[58:61], v[158:161], v[212:215], v[58:61]
	v_mfma_f32_16x16x32_bf16 v[46:49], v[146:149], v[220:223], v[46:49]
	v_mfma_f32_16x16x32_bf16 v[42:45], v[158:161], v[220:223], v[42:45]
	v_mfma_f32_16x16x32_bf16 v[30:33], v[146:149], v[228:231], v[30:33]
	v_mfma_f32_16x16x32_bf16 v[26:29], v[158:161], v[228:231], v[26:29]
	v_mfma_f32_16x16x32_bf16 v[14:17], v[146:149], v[236:239], v[14:17]
	v_mfma_f32_16x16x32_bf16 v[10:13], v[158:161], v[236:239], v[10:13]
	s_setprio 0
	s_setprio 1
	v_mfma_f32_16x16x32_bf16 v[62:65], v[150:153], v[216:219], v[62:65]
	v_mfma_f32_16x16x32_bf16 v[58:61], v[162:165], v[216:219], v[58:61]
	v_mfma_f32_16x16x32_bf16 v[46:49], v[150:153], v[224:227], v[46:49]
	v_mfma_f32_16x16x32_bf16 v[42:45], v[162:165], v[224:227], v[42:45]
	v_mfma_f32_16x16x32_bf16 v[30:33], v[150:153], v[232:235], v[30:33]
	v_mfma_f32_16x16x32_bf16 v[26:29], v[162:165], v[232:235], v[26:29]
	v_mfma_f32_16x16x32_bf16 v[14:17], v[150:153], v[240:243], v[14:17]
	v_mfma_f32_16x16x32_bf16 v[10:13], v[162:165], v[240:243], v[10:13]
	s_setprio 0
	s_setprio 1
	v_mfma_f32_16x16x32_bf16 v[54:57], v[196:199], v[212:215], v[54:57]
	v_mfma_f32_16x16x32_bf16 v[50:53], v[204:207], v[212:215], v[50:53]
	v_mfma_f32_16x16x32_bf16 v[38:41], v[196:199], v[220:223], v[38:41]
	v_mfma_f32_16x16x32_bf16 v[34:37], v[204:207], v[220:223], v[34:37]
	v_mfma_f32_16x16x32_bf16 v[22:25], v[196:199], v[228:231], v[22:25]
	v_mfma_f32_16x16x32_bf16 v[18:21], v[204:207], v[228:231], v[18:21]
	v_mfma_f32_16x16x32_bf16 v[6:9], v[196:199], v[236:239], v[6:9]
	v_mfma_f32_16x16x32_bf16 v[2:5], v[204:207], v[236:239], v[2:5]
	s_setprio 0
	s_setprio 1
	v_mfma_f32_16x16x32_bf16 v[54:57], v[200:203], v[216:219], v[54:57]
	v_mfma_f32_16x16x32_bf16 v[50:53], v[208:211], v[216:219], v[50:53]
	v_mfma_f32_16x16x32_bf16 v[38:41], v[200:203], v[224:227], v[38:41]
	v_mfma_f32_16x16x32_bf16 v[34:37], v[208:211], v[224:227], v[34:37]
	v_mfma_f32_16x16x32_bf16 v[22:25], v[200:203], v[232:235], v[22:25]
	v_mfma_f32_16x16x32_bf16 v[18:21], v[208:211], v[232:235], v[18:21]
	v_mfma_f32_16x16x32_bf16 v[6:9], v[200:203], v[240:243], v[6:9]
	v_mfma_f32_16x16x32_bf16 v[2:5], v[208:211], v[240:243], v[2:5]
	s_setprio 0
	s_barrier
	s_add_i32 vcc_hi, vcc_hi, 2
	s_add_u32 s56, s56, 0x100
	s_addc_u32 s57, s57, 0
	s_cmp_lt_u32 vcc_hi, 14
	s_cbranch_scc1 .LBB0_336
	v_mul_f32_e32 v0, 0xbfb8aa3b, v126
	v_exp_f32_e32 v0, v0
	v_mul_f32_e32 v126, 0xbfb8aa3b, v127
	v_exp_f32_e32 v132, v126
	v_mul_f32_e32 v128, 0xbfb8aa3b, v128
	v_exp_f32_e32 v128, v128
	v_lshl_add_u32 v130, s96, 16, v142
	v_mul_f32_e32 v129, 0xbfb8aa3b, v129
	v_add_f32_e32 v0, 1.0, v0
	v_ashrrev_i32_e32 v131, 31, v130
	v_exp_f32_e32 v129, v129
	v_rcp_f32_e32 v0, v0
	v_lshl_add_u64 v[126:127], s[0:1], 0, v[130:131]
	v_add_f32_e32 v130, 1.0, v132
	v_rcp_f32_e32 v130, v130
	v_add_f32_e32 v128, 1.0, v128
	v_rcp_f32_e32 v128, v128
	v_add_f32_e32 v129, 1.0, v129
	v_fma_f32 v0, v0, s21, 0.5
	v_rcp_f32_e32 v129, v129
	v_max_f32_e32 v0, 1.0, v0
	v_fma_f32 v130, v130, s21, 0.5
	v_mul_f32_e32 v122, 0xbfb8aa3b, v122
	v_cvt_pk_u8_f32 v0, v0, 0, 0
	v_max_f32_e32 v130, 1.0, v130
	v_fma_f32 v128, v128, s21, 0.5
	v_exp_f32_e32 v122, v122
	v_mul_f32_e32 v123, 0xbfb8aa3b, v123
	v_cvt_pk_u8_f32 v0, v130, 1, v0
	v_max_f32_e32 v128, 1.0, v128
	v_exp_f32_e32 v123, v123
	v_cvt_pk_u8_f32 v0, v128, 2, v0
	v_fma_f32 v128, v129, s21, 0.5
	v_max_f32_e32 v128, 1.0, v128
	v_cvt_pk_u8_f32 v0, v128, 3, v0
	v_add_f32_e32 v122, 1.0, v122
	v_rcp_f32_e32 v122, v122
	global_store_dword v[126:127], v0, off
	v_add_f32_e32 v0, 1.0, v123
	v_rcp_f32_e32 v0, v0
	v_mul_f32_e32 v123, 0xbfb8aa3b, v124
	v_exp_f32_e32 v123, v123
	v_mul_f32_e32 v124, 0xbfb8aa3b, v125
	v_exp_f32_e32 v124, v124
	v_fma_f32 v122, v122, s21, 0.5
	v_max_f32_e32 v122, 1.0, v122
	v_fma_f32 v0, v0, s21, 0.5
	v_cvt_pk_u8_f32 v122, v122, 0, 0
	v_max_f32_e32 v0, 1.0, v0
	v_add_f32_e32 v123, 1.0, v123
	v_rcp_f32_e32 v123, v123
	v_cvt_pk_u8_f32 v0, v0, 1, v122
	v_add_f32_e32 v122, 1.0, v124
	v_rcp_f32_e32 v122, v122
	v_mul_f32_e32 v118, 0xbfb8aa3b, v118
	v_exp_f32_e32 v118, v118
	v_mul_f32_e32 v119, 0xbfb8aa3b, v119
	v_fma_f32 v123, v123, s21, 0.5
	v_exp_f32_e32 v119, v119
	v_max_f32_e32 v123, 1.0, v123
	v_fma_f32 v122, v122, s21, 0.5
	v_cvt_pk_u8_f32 v0, v123, 2, v0
	v_max_f32_e32 v122, 1.0, v122
	v_cvt_pk_u8_f32 v0, v122, 3, v0
	v_add_f32_e32 v118, 1.0, v118
	v_rcp_f32_e32 v118, v118
	global_store_dword v[126:127], v0, off offset:256
	v_add_f32_e32 v0, 1.0, v119
	v_rcp_f32_e32 v0, v0
	v_mul_f32_e32 v119, 0xbfb8aa3b, v120
	v_exp_f32_e32 v119, v119
	v_mul_f32_e32 v120, 0xbfb8aa3b, v121
	v_exp_f32_e32 v120, v120
	v_fma_f32 v118, v118, s21, 0.5
	v_max_f32_e32 v118, 1.0, v118
	v_fma_f32 v0, v0, s21, 0.5
	v_cvt_pk_u8_f32 v118, v118, 0, 0
	v_max_f32_e32 v0, 1.0, v0
	v_add_f32_e32 v119, 1.0, v119
	v_rcp_f32_e32 v119, v119
	v_cvt_pk_u8_f32 v0, v0, 1, v118
	v_add_f32_e32 v118, 1.0, v120
	v_rcp_f32_e32 v118, v118
	v_mul_f32_e32 v114, 0xbfb8aa3b, v114
	v_exp_f32_e32 v114, v114
	v_mul_f32_e32 v115, 0xbfb8aa3b, v115
	v_fma_f32 v119, v119, s21, 0.5
	v_exp_f32_e32 v115, v115
	v_max_f32_e32 v119, 1.0, v119
	v_fma_f32 v118, v118, s21, 0.5
	v_cvt_pk_u8_f32 v0, v119, 2, v0
	v_max_f32_e32 v118, 1.0, v118
	v_cvt_pk_u8_f32 v0, v118, 3, v0
	v_add_f32_e32 v114, 1.0, v114
	v_rcp_f32_e32 v114, v114
	global_store_dword v[126:127], v0, off offset:512
	v_add_f32_e32 v0, 1.0, v115
	v_rcp_f32_e32 v0, v0
	v_mul_f32_e32 v115, 0xbfb8aa3b, v116
	v_exp_f32_e32 v115, v115
	v_mul_f32_e32 v116, 0xbfb8aa3b, v117
	v_exp_f32_e32 v116, v116
	v_fma_f32 v114, v114, s21, 0.5
	v_max_f32_e32 v114, 1.0, v114
	v_fma_f32 v0, v0, s21, 0.5
	v_cvt_pk_u8_f32 v114, v114, 0, 0
	v_max_f32_e32 v0, 1.0, v0
	v_add_f32_e32 v115, 1.0, v115
	v_rcp_f32_e32 v115, v115
	v_cvt_pk_u8_f32 v0, v0, 1, v114
	v_add_f32_e32 v114, 1.0, v116
	v_rcp_f32_e32 v114, v114
	v_mul_f32_e32 v110, 0xbfb8aa3b, v110
	v_exp_f32_e32 v110, v110
	v_mul_f32_e32 v111, 0xbfb8aa3b, v111
	v_fma_f32 v115, v115, s21, 0.5
	v_exp_f32_e32 v111, v111
	v_max_f32_e32 v115, 1.0, v115
	v_fma_f32 v114, v114, s21, 0.5
	v_cvt_pk_u8_f32 v0, v115, 2, v0
	v_max_f32_e32 v114, 1.0, v114
	v_cvt_pk_u8_f32 v0, v114, 3, v0
	v_add_f32_e32 v110, 1.0, v110
	v_rcp_f32_e32 v110, v110
	global_store_dword v[126:127], v0, off offset:768
	v_add_f32_e32 v0, 1.0, v111
	v_rcp_f32_e32 v0, v0
	v_mul_f32_e32 v111, 0xbfb8aa3b, v112
	v_exp_f32_e32 v111, v111
	v_mul_f32_e32 v112, 0xbfb8aa3b, v113
	v_exp_f32_e32 v112, v112
	v_fma_f32 v110, v110, s21, 0.5
	v_max_f32_e32 v110, 1.0, v110
	v_fma_f32 v0, v0, s21, 0.5
	v_cvt_pk_u8_f32 v110, v110, 0, 0
	v_max_f32_e32 v0, 1.0, v0
	v_add_f32_e32 v111, 1.0, v111
	v_rcp_f32_e32 v111, v111
	v_cvt_pk_u8_f32 v0, v0, 1, v110
	v_add_f32_e32 v110, 1.0, v112
	v_rcp_f32_e32 v110, v110
	v_mul_f32_e32 v106, 0xbfb8aa3b, v106
	v_exp_f32_e32 v106, v106
	v_mul_f32_e32 v107, 0xbfb8aa3b, v107
	v_fma_f32 v111, v111, s21, 0.5
	v_exp_f32_e32 v107, v107
	v_max_f32_e32 v111, 1.0, v111
	v_fma_f32 v110, v110, s21, 0.5
	v_cvt_pk_u8_f32 v0, v111, 2, v0
	v_max_f32_e32 v110, 1.0, v110
	v_cvt_pk_u8_f32 v0, v110, 3, v0
	v_add_f32_e32 v106, 1.0, v106
	v_rcp_f32_e32 v106, v106
	global_store_dword v[126:127], v0, off offset:1024
	v_add_f32_e32 v0, 1.0, v107
	v_rcp_f32_e32 v0, v0
	v_mul_f32_e32 v107, 0xbfb8aa3b, v108
	v_exp_f32_e32 v107, v107
	v_mul_f32_e32 v108, 0xbfb8aa3b, v109
	v_exp_f32_e32 v108, v108
	v_fma_f32 v106, v106, s21, 0.5
	v_max_f32_e32 v106, 1.0, v106
	v_fma_f32 v0, v0, s21, 0.5
	v_cvt_pk_u8_f32 v106, v106, 0, 0
	v_max_f32_e32 v0, 1.0, v0
	v_add_f32_e32 v107, 1.0, v107
	v_rcp_f32_e32 v107, v107
	v_cvt_pk_u8_f32 v0, v0, 1, v106
	v_add_f32_e32 v106, 1.0, v108
	v_rcp_f32_e32 v106, v106
	v_mul_f32_e32 v102, 0xbfb8aa3b, v102
	v_exp_f32_e32 v102, v102
	v_mul_f32_e32 v103, 0xbfb8aa3b, v103
	v_fma_f32 v107, v107, s21, 0.5
	v_exp_f32_e32 v103, v103
	v_max_f32_e32 v107, 1.0, v107
	v_fma_f32 v106, v106, s21, 0.5
	v_cvt_pk_u8_f32 v0, v107, 2, v0
	v_max_f32_e32 v106, 1.0, v106
	v_cvt_pk_u8_f32 v0, v106, 3, v0
	v_add_f32_e32 v102, 1.0, v102
	v_rcp_f32_e32 v102, v102
	global_store_dword v[126:127], v0, off offset:1280
	v_add_f32_e32 v0, 1.0, v103
	v_rcp_f32_e32 v0, v0
	v_mul_f32_e32 v103, 0xbfb8aa3b, v104
	v_exp_f32_e32 v103, v103
	v_mul_f32_e32 v104, 0xbfb8aa3b, v105
	v_exp_f32_e32 v104, v104
	v_fma_f32 v102, v102, s21, 0.5
	v_max_f32_e32 v102, 1.0, v102
	v_fma_f32 v0, v0, s21, 0.5
	v_cvt_pk_u8_f32 v102, v102, 0, 0
	v_max_f32_e32 v0, 1.0, v0
	v_add_f32_e32 v103, 1.0, v103
	v_rcp_f32_e32 v103, v103
	v_cvt_pk_u8_f32 v0, v0, 1, v102
	v_add_f32_e32 v102, 1.0, v104
	v_rcp_f32_e32 v102, v102
	v_mul_f32_e32 v98, 0xbfb8aa3b, v98
	v_exp_f32_e32 v98, v98
	v_mul_f32_e32 v99, 0xbfb8aa3b, v99
	v_fma_f32 v103, v103, s21, 0.5
	v_exp_f32_e32 v99, v99
	v_max_f32_e32 v103, 1.0, v103
	v_fma_f32 v102, v102, s21, 0.5
	v_cvt_pk_u8_f32 v0, v103, 2, v0
	v_max_f32_e32 v102, 1.0, v102
	v_cvt_pk_u8_f32 v0, v102, 3, v0
	v_add_f32_e32 v98, 1.0, v98
	v_rcp_f32_e32 v98, v98
	global_store_dword v[126:127], v0, off offset:1536
	v_add_f32_e32 v0, 1.0, v99
	v_rcp_f32_e32 v0, v0
	v_mul_f32_e32 v99, 0xbfb8aa3b, v100
	v_exp_f32_e32 v99, v99
	v_mul_f32_e32 v100, 0xbfb8aa3b, v101
	v_exp_f32_e32 v100, v100
	v_fma_f32 v98, v98, s21, 0.5
	v_max_f32_e32 v98, 1.0, v98
	v_fma_f32 v0, v0, s21, 0.5
	v_cvt_pk_u8_f32 v98, v98, 0, 0
	v_max_f32_e32 v0, 1.0, v0
	v_add_f32_e32 v99, 1.0, v99
	v_rcp_f32_e32 v99, v99
	v_cvt_pk_u8_f32 v0, v0, 1, v98
	v_add_f32_e32 v98, 1.0, v100
	v_rcp_f32_e32 v98, v98
	v_mul_f32_e32 v94, 0xbfb8aa3b, v94
	v_exp_f32_e32 v94, v94
	v_mul_f32_e32 v95, 0xbfb8aa3b, v95
	v_fma_f32 v99, v99, s21, 0.5
	v_exp_f32_e32 v95, v95
	v_max_f32_e32 v99, 1.0, v99
	v_fma_f32 v98, v98, s21, 0.5
	v_cvt_pk_u8_f32 v0, v99, 2, v0
	v_max_f32_e32 v98, 1.0, v98
	v_cvt_pk_u8_f32 v0, v98, 3, v0
	v_add_f32_e32 v94, 1.0, v94
	v_rcp_f32_e32 v94, v94
	global_store_dword v[126:127], v0, off offset:1792
	v_add_f32_e32 v0, 1.0, v95
	v_rcp_f32_e32 v0, v0
	v_mul_f32_e32 v95, 0xbfb8aa3b, v96
	v_exp_f32_e32 v95, v95
	v_mul_f32_e32 v96, 0xbfb8aa3b, v97
	v_exp_f32_e32 v96, v96
	v_fma_f32 v94, v94, s21, 0.5
	v_max_f32_e32 v94, 1.0, v94
	v_fma_f32 v0, v0, s21, 0.5
	v_cvt_pk_u8_f32 v94, v94, 0, 0
	v_max_f32_e32 v0, 1.0, v0
	v_add_f32_e32 v95, 1.0, v95
	v_rcp_f32_e32 v95, v95
	v_cvt_pk_u8_f32 v0, v0, 1, v94
	v_add_f32_e32 v94, 1.0, v96
	v_rcp_f32_e32 v94, v94
	v_mul_f32_e32 v90, 0xbfb8aa3b, v90
	v_exp_f32_e32 v90, v90
	v_mul_f32_e32 v91, 0xbfb8aa3b, v91
	v_fma_f32 v95, v95, s21, 0.5
	v_exp_f32_e32 v91, v91
	v_max_f32_e32 v95, 1.0, v95
	v_fma_f32 v94, v94, s21, 0.5
	v_cvt_pk_u8_f32 v0, v95, 2, v0
	v_max_f32_e32 v94, 1.0, v94
	v_cvt_pk_u8_f32 v0, v94, 3, v0
	v_add_f32_e32 v90, 1.0, v90
	v_rcp_f32_e32 v90, v90
	global_store_dword v[126:127], v0, off offset:2048
	v_add_f32_e32 v0, 1.0, v91
	v_rcp_f32_e32 v0, v0
	v_mul_f32_e32 v91, 0xbfb8aa3b, v92
	v_exp_f32_e32 v91, v91
	v_mul_f32_e32 v92, 0xbfb8aa3b, v93
	v_exp_f32_e32 v92, v92
	v_fma_f32 v90, v90, s21, 0.5
	v_max_f32_e32 v90, 1.0, v90
	v_fma_f32 v0, v0, s21, 0.5
	v_cvt_pk_u8_f32 v90, v90, 0, 0
	v_max_f32_e32 v0, 1.0, v0
	v_add_f32_e32 v91, 1.0, v91
	v_rcp_f32_e32 v91, v91
	v_cvt_pk_u8_f32 v0, v0, 1, v90
	v_add_f32_e32 v90, 1.0, v92
	v_rcp_f32_e32 v90, v90
	v_mul_f32_e32 v86, 0xbfb8aa3b, v86
	v_exp_f32_e32 v86, v86
	v_mul_f32_e32 v87, 0xbfb8aa3b, v87
	v_fma_f32 v91, v91, s21, 0.5
	v_exp_f32_e32 v87, v87
	v_max_f32_e32 v91, 1.0, v91
	v_fma_f32 v90, v90, s21, 0.5
	v_cvt_pk_u8_f32 v0, v91, 2, v0
	v_max_f32_e32 v90, 1.0, v90
	v_cvt_pk_u8_f32 v0, v90, 3, v0
	v_add_f32_e32 v86, 1.0, v86
	v_rcp_f32_e32 v86, v86
	global_store_dword v[126:127], v0, off offset:2304
	v_add_f32_e32 v0, 1.0, v87
	v_rcp_f32_e32 v0, v0
	v_mul_f32_e32 v87, 0xbfb8aa3b, v88
	v_exp_f32_e32 v87, v87
	v_mul_f32_e32 v88, 0xbfb8aa3b, v89
	v_exp_f32_e32 v88, v88
	v_fma_f32 v86, v86, s21, 0.5
	v_max_f32_e32 v86, 1.0, v86
	v_fma_f32 v0, v0, s21, 0.5
	v_cvt_pk_u8_f32 v86, v86, 0, 0
	v_max_f32_e32 v0, 1.0, v0
	v_add_f32_e32 v87, 1.0, v87
	v_rcp_f32_e32 v87, v87
	v_cvt_pk_u8_f32 v0, v0, 1, v86
	v_add_f32_e32 v86, 1.0, v88
	v_rcp_f32_e32 v86, v86
	v_mul_f32_e32 v82, 0xbfb8aa3b, v82
	v_exp_f32_e32 v82, v82
	v_mul_f32_e32 v83, 0xbfb8aa3b, v83
	v_fma_f32 v87, v87, s21, 0.5
	v_exp_f32_e32 v83, v83
	v_max_f32_e32 v87, 1.0, v87
	v_fma_f32 v86, v86, s21, 0.5
	v_cvt_pk_u8_f32 v0, v87, 2, v0
	v_max_f32_e32 v86, 1.0, v86
	v_cvt_pk_u8_f32 v0, v86, 3, v0
	v_add_f32_e32 v82, 1.0, v82
	v_rcp_f32_e32 v82, v82
	global_store_dword v[126:127], v0, off offset:2560
	v_add_f32_e32 v0, 1.0, v83
	v_rcp_f32_e32 v0, v0
	v_mul_f32_e32 v83, 0xbfb8aa3b, v84
	v_exp_f32_e32 v83, v83
	v_mul_f32_e32 v84, 0xbfb8aa3b, v85
	v_exp_f32_e32 v84, v84
	v_fma_f32 v82, v82, s21, 0.5
	v_max_f32_e32 v82, 1.0, v82
	v_fma_f32 v0, v0, s21, 0.5
	v_cvt_pk_u8_f32 v82, v82, 0, 0
	v_max_f32_e32 v0, 1.0, v0
	v_add_f32_e32 v83, 1.0, v83
	v_rcp_f32_e32 v83, v83
	v_cvt_pk_u8_f32 v0, v0, 1, v82
	v_add_f32_e32 v82, 1.0, v84
	v_rcp_f32_e32 v82, v82
	v_mul_f32_e32 v78, 0xbfb8aa3b, v78
	v_exp_f32_e32 v78, v78
	v_mul_f32_e32 v79, 0xbfb8aa3b, v79
	v_fma_f32 v83, v83, s21, 0.5
	v_exp_f32_e32 v79, v79
	v_max_f32_e32 v83, 1.0, v83
	v_fma_f32 v82, v82, s21, 0.5
	v_cvt_pk_u8_f32 v0, v83, 2, v0
	v_max_f32_e32 v82, 1.0, v82
	v_cvt_pk_u8_f32 v0, v82, 3, v0
	v_add_f32_e32 v78, 1.0, v78
	v_rcp_f32_e32 v78, v78
	global_store_dword v[126:127], v0, off offset:2816
	v_add_f32_e32 v0, 1.0, v79
	v_rcp_f32_e32 v0, v0
	v_mul_f32_e32 v79, 0xbfb8aa3b, v80
	v_exp_f32_e32 v79, v79
	v_mul_f32_e32 v80, 0xbfb8aa3b, v81
	v_exp_f32_e32 v80, v80
	v_fma_f32 v78, v78, s21, 0.5
	v_max_f32_e32 v78, 1.0, v78
	v_fma_f32 v0, v0, s21, 0.5
	v_cvt_pk_u8_f32 v78, v78, 0, 0
	v_max_f32_e32 v0, 1.0, v0
	v_add_f32_e32 v79, 1.0, v79
	v_rcp_f32_e32 v79, v79
	v_cvt_pk_u8_f32 v0, v0, 1, v78
	v_add_f32_e32 v78, 1.0, v80
	v_rcp_f32_e32 v78, v78
	v_mul_f32_e32 v74, 0xbfb8aa3b, v74
	v_exp_f32_e32 v74, v74
	v_mul_f32_e32 v75, 0xbfb8aa3b, v75
	v_fma_f32 v79, v79, s21, 0.5
	v_exp_f32_e32 v75, v75
	v_max_f32_e32 v79, 1.0, v79
	v_fma_f32 v78, v78, s21, 0.5
	v_cvt_pk_u8_f32 v0, v79, 2, v0
	v_max_f32_e32 v78, 1.0, v78
	v_cvt_pk_u8_f32 v0, v78, 3, v0
	v_add_f32_e32 v74, 1.0, v74
	v_rcp_f32_e32 v74, v74
	global_store_dword v[126:127], v0, off offset:3072
	v_add_f32_e32 v0, 1.0, v75
	v_rcp_f32_e32 v0, v0
	v_mul_f32_e32 v75, 0xbfb8aa3b, v76
	v_exp_f32_e32 v75, v75
	v_mul_f32_e32 v76, 0xbfb8aa3b, v77
	v_exp_f32_e32 v76, v76
	v_fma_f32 v74, v74, s21, 0.5
	v_max_f32_e32 v74, 1.0, v74
	v_fma_f32 v0, v0, s21, 0.5
	v_cvt_pk_u8_f32 v74, v74, 0, 0
	v_max_f32_e32 v0, 1.0, v0
	v_add_f32_e32 v75, 1.0, v75
	v_rcp_f32_e32 v75, v75
	v_cvt_pk_u8_f32 v0, v0, 1, v74
	v_add_f32_e32 v74, 1.0, v76
	v_rcp_f32_e32 v74, v74
	v_mul_f32_e32 v70, 0xbfb8aa3b, v70
	v_exp_f32_e32 v70, v70
	v_mul_f32_e32 v71, 0xbfb8aa3b, v71
	v_fma_f32 v75, v75, s21, 0.5
	v_exp_f32_e32 v71, v71
	v_max_f32_e32 v75, 1.0, v75
	v_fma_f32 v74, v74, s21, 0.5
	v_cvt_pk_u8_f32 v0, v75, 2, v0
	v_max_f32_e32 v74, 1.0, v74
	v_cvt_pk_u8_f32 v0, v74, 3, v0
	v_add_f32_e32 v70, 1.0, v70
	v_rcp_f32_e32 v70, v70
	global_store_dword v[126:127], v0, off offset:3328
	v_add_f32_e32 v0, 1.0, v71
	v_rcp_f32_e32 v0, v0
	v_mul_f32_e32 v71, 0xbfb8aa3b, v72
	v_exp_f32_e32 v71, v71
	v_mul_f32_e32 v72, 0xbfb8aa3b, v73
	v_exp_f32_e32 v72, v72
	v_fma_f32 v70, v70, s21, 0.5
	v_max_f32_e32 v70, 1.0, v70
	v_fma_f32 v0, v0, s21, 0.5
	v_cvt_pk_u8_f32 v70, v70, 0, 0
	v_max_f32_e32 v0, 1.0, v0
	v_add_f32_e32 v71, 1.0, v71
	v_rcp_f32_e32 v71, v71
	v_cvt_pk_u8_f32 v0, v0, 1, v70
	v_add_f32_e32 v70, 1.0, v72
	v_rcp_f32_e32 v70, v70
	v_mul_f32_e32 v66, 0xbfb8aa3b, v66
	v_exp_f32_e32 v66, v66
	v_mul_f32_e32 v67, 0xbfb8aa3b, v67
	v_fma_f32 v71, v71, s21, 0.5
	v_exp_f32_e32 v67, v67
	v_max_f32_e32 v71, 1.0, v71
	v_fma_f32 v70, v70, s21, 0.5
	v_cvt_pk_u8_f32 v0, v71, 2, v0
	v_max_f32_e32 v70, 1.0, v70
	v_cvt_pk_u8_f32 v0, v70, 3, v0
	v_add_f32_e32 v66, 1.0, v66
	v_rcp_f32_e32 v66, v66
	global_store_dword v[126:127], v0, off offset:3584
	v_add_f32_e32 v0, 1.0, v67
	v_rcp_f32_e32 v0, v0
	v_mul_f32_e32 v67, 0xbfb8aa3b, v68
	v_exp_f32_e32 v67, v67
	v_mul_f32_e32 v68, 0xbfb8aa3b, v69
	v_exp_f32_e32 v68, v68
	v_fma_f32 v66, v66, s21, 0.5
	v_max_f32_e32 v66, 1.0, v66
	v_fma_f32 v0, v0, s21, 0.5
	v_cvt_pk_u8_f32 v66, v66, 0, 0
	v_max_f32_e32 v0, 1.0, v0
	v_add_f32_e32 v67, 1.0, v67
	v_rcp_f32_e32 v67, v67
	v_cvt_pk_u8_f32 v0, v0, 1, v66
	v_add_f32_e32 v66, 1.0, v68
	v_rcp_f32_e32 v66, v66
	v_mul_f32_e32 v62, 0xbfb8aa3b, v62
	v_exp_f32_e32 v62, v62
	v_mul_f32_e32 v63, 0xbfb8aa3b, v63
	v_fma_f32 v67, v67, s21, 0.5
	v_exp_f32_e32 v63, v63
	v_max_f32_e32 v67, 1.0, v67
	v_fma_f32 v66, v66, s21, 0.5
	v_cvt_pk_u8_f32 v0, v67, 2, v0
	v_max_f32_e32 v66, 1.0, v66
	v_cvt_pk_u8_f32 v0, v66, 3, v0
	v_add_f32_e32 v62, 1.0, v62
	v_rcp_f32_e32 v62, v62
	global_store_dword v[126:127], v0, off offset:3840
	v_add_f32_e32 v0, 1.0, v63
	v_rcp_f32_e32 v0, v0
	v_mul_f32_e32 v63, 0xbfb8aa3b, v64
	v_exp_f32_e32 v63, v63
	v_mul_f32_e32 v64, 0xbfb8aa3b, v65
	v_exp_f32_e32 v64, v64
	v_fma_f32 v62, v62, s21, 0.5
	v_max_f32_e32 v62, 1.0, v62
	v_fma_f32 v0, v0, s21, 0.5
	v_cvt_pk_u8_f32 v62, v62, 0, 0
	v_max_f32_e32 v0, 1.0, v0
	v_add_f32_e32 v63, 1.0, v63
	v_rcp_f32_e32 v63, v63
	v_cvt_pk_u8_f32 v0, v0, 1, v62
	v_add_f32_e32 v62, 1.0, v64
	v_rcp_f32_e32 v62, v62
	v_mul_f32_e32 v58, 0xbfb8aa3b, v58
	v_fma_f32 v63, v63, s21, 0.5
	v_exp_f32_e32 v58, v58
	v_mul_f32_e32 v59, 0xbfb8aa3b, v59
	v_max_f32_e32 v63, 1.0, v63
	v_fma_f32 v62, v62, s21, 0.5
	v_exp_f32_e32 v59, v59
	v_cvt_pk_u8_f32 v0, v63, 2, v0
	v_max_f32_e32 v62, 1.0, v62
	v_cvt_pk_u8_f32 v0, v62, 3, v0
	v_add_co_u32_e32 v62, vcc, s77, v126
	v_add_f32_e32 v58, 1.0, v58
	s_nop 0
	v_addc_co_u32_e32 v63, vcc, 0, v127, vcc
	v_rcp_f32_e32 v58, v58
	global_store_dword v[62:63], v0, off
	v_add_f32_e32 v0, 1.0, v59
	v_rcp_f32_e32 v0, v0
	v_mul_f32_e32 v59, 0xbfb8aa3b, v60
	v_exp_f32_e32 v59, v59
	v_mul_f32_e32 v60, 0xbfb8aa3b, v61
	v_exp_f32_e32 v60, v60
	v_fma_f32 v58, v58, s21, 0.5
	v_max_f32_e32 v58, 1.0, v58
	v_fma_f32 v0, v0, s21, 0.5
	v_cvt_pk_u8_f32 v58, v58, 0, 0
	v_max_f32_e32 v0, 1.0, v0
	v_add_f32_e32 v59, 1.0, v59
	v_rcp_f32_e32 v59, v59
	v_cvt_pk_u8_f32 v0, v0, 1, v58
	v_add_f32_e32 v58, 1.0, v60
	v_rcp_f32_e32 v58, v58
	v_mul_f32_e32 v54, 0xbfb8aa3b, v54
	v_exp_f32_e32 v54, v54
	v_mul_f32_e32 v55, 0xbfb8aa3b, v55
	v_fma_f32 v59, v59, s21, 0.5
	v_exp_f32_e32 v55, v55
	v_max_f32_e32 v59, 1.0, v59
	v_fma_f32 v58, v58, s21, 0.5
	v_cvt_pk_u8_f32 v0, v59, 2, v0
	v_max_f32_e32 v58, 1.0, v58
	v_cvt_pk_u8_f32 v0, v58, 3, v0
	v_add_f32_e32 v54, 1.0, v54
	v_rcp_f32_e32 v54, v54
	global_store_dword v[62:63], v0, off offset:256
	v_add_f32_e32 v0, 1.0, v55
	v_rcp_f32_e32 v0, v0
	v_mul_f32_e32 v55, 0xbfb8aa3b, v56
	v_exp_f32_e32 v55, v55
	v_mul_f32_e32 v56, 0xbfb8aa3b, v57
	v_exp_f32_e32 v56, v56
	v_fma_f32 v54, v54, s21, 0.5
	v_max_f32_e32 v54, 1.0, v54
	v_fma_f32 v0, v0, s21, 0.5
	v_cvt_pk_u8_f32 v54, v54, 0, 0
	v_max_f32_e32 v0, 1.0, v0
	v_add_f32_e32 v55, 1.0, v55
	v_rcp_f32_e32 v55, v55
	v_cvt_pk_u8_f32 v0, v0, 1, v54
	v_add_f32_e32 v54, 1.0, v56
	v_rcp_f32_e32 v54, v54
	v_mul_f32_e32 v50, 0xbfb8aa3b, v50
	v_exp_f32_e32 v50, v50
	v_mul_f32_e32 v51, 0xbfb8aa3b, v51
	v_fma_f32 v55, v55, s21, 0.5
	v_exp_f32_e32 v51, v51
	v_max_f32_e32 v55, 1.0, v55
	v_fma_f32 v54, v54, s21, 0.5
	v_cvt_pk_u8_f32 v0, v55, 2, v0
	v_max_f32_e32 v54, 1.0, v54
	v_cvt_pk_u8_f32 v0, v54, 3, v0
	v_add_f32_e32 v50, 1.0, v50
	v_rcp_f32_e32 v50, v50
	global_store_dword v[62:63], v0, off offset:512
	v_add_f32_e32 v0, 1.0, v51
	v_rcp_f32_e32 v0, v0
	v_mul_f32_e32 v51, 0xbfb8aa3b, v52
	v_exp_f32_e32 v51, v51
	v_mul_f32_e32 v52, 0xbfb8aa3b, v53
	v_exp_f32_e32 v52, v52
	v_fma_f32 v50, v50, s21, 0.5
	v_max_f32_e32 v50, 1.0, v50
	v_fma_f32 v0, v0, s21, 0.5
	v_cvt_pk_u8_f32 v50, v50, 0, 0
	v_max_f32_e32 v0, 1.0, v0
	v_add_f32_e32 v51, 1.0, v51
	v_rcp_f32_e32 v51, v51
	v_cvt_pk_u8_f32 v0, v0, 1, v50
	v_add_f32_e32 v50, 1.0, v52
	v_rcp_f32_e32 v50, v50
	v_mul_f32_e32 v46, 0xbfb8aa3b, v46
	v_exp_f32_e32 v46, v46
	v_mul_f32_e32 v47, 0xbfb8aa3b, v47
	v_fma_f32 v51, v51, s21, 0.5
	v_exp_f32_e32 v47, v47
	v_max_f32_e32 v51, 1.0, v51
	v_fma_f32 v50, v50, s21, 0.5
	v_cvt_pk_u8_f32 v0, v51, 2, v0
	v_max_f32_e32 v50, 1.0, v50
	v_cvt_pk_u8_f32 v0, v50, 3, v0
	v_add_f32_e32 v46, 1.0, v46
	v_rcp_f32_e32 v46, v46
	global_store_dword v[62:63], v0, off offset:768
	v_add_f32_e32 v0, 1.0, v47
	v_rcp_f32_e32 v0, v0
	v_mul_f32_e32 v47, 0xbfb8aa3b, v48
	v_exp_f32_e32 v47, v47
	v_mul_f32_e32 v48, 0xbfb8aa3b, v49
	v_exp_f32_e32 v48, v48
	v_fma_f32 v46, v46, s21, 0.5
	v_max_f32_e32 v46, 1.0, v46
	v_fma_f32 v0, v0, s21, 0.5
	v_cvt_pk_u8_f32 v46, v46, 0, 0
	v_max_f32_e32 v0, 1.0, v0
	v_add_f32_e32 v47, 1.0, v47
	v_rcp_f32_e32 v47, v47
	v_cvt_pk_u8_f32 v0, v0, 1, v46
	v_add_f32_e32 v46, 1.0, v48
	v_rcp_f32_e32 v46, v46
	v_mul_f32_e32 v42, 0xbfb8aa3b, v42
	v_exp_f32_e32 v42, v42
	v_mul_f32_e32 v43, 0xbfb8aa3b, v43
	v_fma_f32 v47, v47, s21, 0.5
	v_exp_f32_e32 v43, v43
	v_max_f32_e32 v47, 1.0, v47
	v_fma_f32 v46, v46, s21, 0.5
	v_cvt_pk_u8_f32 v0, v47, 2, v0
	v_max_f32_e32 v46, 1.0, v46
	v_cvt_pk_u8_f32 v0, v46, 3, v0
	v_add_f32_e32 v42, 1.0, v42
	v_rcp_f32_e32 v42, v42
	global_store_dword v[62:63], v0, off offset:1024
	v_add_f32_e32 v0, 1.0, v43
	v_rcp_f32_e32 v0, v0
	v_mul_f32_e32 v43, 0xbfb8aa3b, v44
	v_exp_f32_e32 v43, v43
	v_mul_f32_e32 v44, 0xbfb8aa3b, v45
	v_exp_f32_e32 v44, v44
	v_fma_f32 v42, v42, s21, 0.5
	v_max_f32_e32 v42, 1.0, v42
	v_fma_f32 v0, v0, s21, 0.5
	v_cvt_pk_u8_f32 v42, v42, 0, 0
	v_max_f32_e32 v0, 1.0, v0
	v_add_f32_e32 v43, 1.0, v43
	v_rcp_f32_e32 v43, v43
	v_cvt_pk_u8_f32 v0, v0, 1, v42
	v_add_f32_e32 v42, 1.0, v44
	v_rcp_f32_e32 v42, v42
	v_mul_f32_e32 v38, 0xbfb8aa3b, v38
	v_exp_f32_e32 v38, v38
	v_mul_f32_e32 v39, 0xbfb8aa3b, v39
	v_fma_f32 v43, v43, s21, 0.5
	v_exp_f32_e32 v39, v39
	v_max_f32_e32 v43, 1.0, v43
	v_fma_f32 v42, v42, s21, 0.5
	v_cvt_pk_u8_f32 v0, v43, 2, v0
	v_max_f32_e32 v42, 1.0, v42
	v_cvt_pk_u8_f32 v0, v42, 3, v0
	v_add_f32_e32 v38, 1.0, v38
	v_rcp_f32_e32 v38, v38
	global_store_dword v[62:63], v0, off offset:1280
	v_add_f32_e32 v0, 1.0, v39
	v_rcp_f32_e32 v0, v0
	v_mul_f32_e32 v39, 0xbfb8aa3b, v40
	v_exp_f32_e32 v39, v39
	v_mul_f32_e32 v40, 0xbfb8aa3b, v41
	v_exp_f32_e32 v40, v40
	v_fma_f32 v38, v38, s21, 0.5
	v_max_f32_e32 v38, 1.0, v38
	v_fma_f32 v0, v0, s21, 0.5
	v_cvt_pk_u8_f32 v38, v38, 0, 0
	v_max_f32_e32 v0, 1.0, v0
	v_add_f32_e32 v39, 1.0, v39
	v_rcp_f32_e32 v39, v39
	v_cvt_pk_u8_f32 v0, v0, 1, v38
	v_add_f32_e32 v38, 1.0, v40
	v_rcp_f32_e32 v38, v38
	v_mul_f32_e32 v34, 0xbfb8aa3b, v34
	v_exp_f32_e32 v34, v34
	v_mul_f32_e32 v35, 0xbfb8aa3b, v35
	v_fma_f32 v39, v39, s21, 0.5
	v_exp_f32_e32 v35, v35
	v_max_f32_e32 v39, 1.0, v39
	v_fma_f32 v38, v38, s21, 0.5
	v_cvt_pk_u8_f32 v0, v39, 2, v0
	v_max_f32_e32 v38, 1.0, v38
	v_cvt_pk_u8_f32 v0, v38, 3, v0
	v_add_f32_e32 v34, 1.0, v34
	v_rcp_f32_e32 v34, v34
	global_store_dword v[62:63], v0, off offset:1536
	v_add_f32_e32 v0, 1.0, v35
	v_rcp_f32_e32 v0, v0
	v_mul_f32_e32 v35, 0xbfb8aa3b, v36
	v_exp_f32_e32 v35, v35
	v_mul_f32_e32 v36, 0xbfb8aa3b, v37
	v_exp_f32_e32 v36, v36
	v_fma_f32 v34, v34, s21, 0.5
	v_max_f32_e32 v34, 1.0, v34
	v_fma_f32 v0, v0, s21, 0.5
	v_cvt_pk_u8_f32 v34, v34, 0, 0
	v_max_f32_e32 v0, 1.0, v0
	v_add_f32_e32 v35, 1.0, v35
	v_rcp_f32_e32 v35, v35
	v_cvt_pk_u8_f32 v0, v0, 1, v34
	v_add_f32_e32 v34, 1.0, v36
	v_rcp_f32_e32 v34, v34
	v_mul_f32_e32 v30, 0xbfb8aa3b, v30
	v_exp_f32_e32 v30, v30
	v_mul_f32_e32 v31, 0xbfb8aa3b, v31
	v_fma_f32 v35, v35, s21, 0.5
	v_exp_f32_e32 v31, v31
	v_max_f32_e32 v35, 1.0, v35
	v_fma_f32 v34, v34, s21, 0.5
	v_cvt_pk_u8_f32 v0, v35, 2, v0
	v_max_f32_e32 v34, 1.0, v34
	v_cvt_pk_u8_f32 v0, v34, 3, v0
	v_add_f32_e32 v30, 1.0, v30
	v_rcp_f32_e32 v30, v30
	global_store_dword v[62:63], v0, off offset:1792
	v_add_f32_e32 v0, 1.0, v31
	v_rcp_f32_e32 v0, v0
	v_mul_f32_e32 v31, 0xbfb8aa3b, v32
	v_exp_f32_e32 v31, v31
	v_mul_f32_e32 v32, 0xbfb8aa3b, v33
	v_exp_f32_e32 v32, v32
	v_fma_f32 v30, v30, s21, 0.5
	v_max_f32_e32 v30, 1.0, v30
	v_fma_f32 v0, v0, s21, 0.5
	v_cvt_pk_u8_f32 v30, v30, 0, 0
	v_max_f32_e32 v0, 1.0, v0
	v_add_f32_e32 v31, 1.0, v31
	v_rcp_f32_e32 v31, v31
	v_cvt_pk_u8_f32 v0, v0, 1, v30
	v_add_f32_e32 v30, 1.0, v32
	v_rcp_f32_e32 v30, v30
	v_mul_f32_e32 v26, 0xbfb8aa3b, v26
	v_exp_f32_e32 v26, v26
	v_mul_f32_e32 v27, 0xbfb8aa3b, v27
	v_fma_f32 v31, v31, s21, 0.5
	v_exp_f32_e32 v27, v27
	v_max_f32_e32 v31, 1.0, v31
	v_fma_f32 v30, v30, s21, 0.5
	v_cvt_pk_u8_f32 v0, v31, 2, v0
	v_max_f32_e32 v30, 1.0, v30
	v_cvt_pk_u8_f32 v0, v30, 3, v0
	v_add_f32_e32 v26, 1.0, v26
	v_rcp_f32_e32 v26, v26
	global_store_dword v[62:63], v0, off offset:2048
	v_add_f32_e32 v0, 1.0, v27
	v_rcp_f32_e32 v0, v0
	v_mul_f32_e32 v27, 0xbfb8aa3b, v28
	v_exp_f32_e32 v27, v27
	v_mul_f32_e32 v28, 0xbfb8aa3b, v29
	v_exp_f32_e32 v28, v28
	v_fma_f32 v26, v26, s21, 0.5
	v_max_f32_e32 v26, 1.0, v26
	v_fma_f32 v0, v0, s21, 0.5
	v_cvt_pk_u8_f32 v26, v26, 0, 0
	v_max_f32_e32 v0, 1.0, v0
	v_add_f32_e32 v27, 1.0, v27
	v_rcp_f32_e32 v27, v27
	v_cvt_pk_u8_f32 v0, v0, 1, v26
	v_add_f32_e32 v26, 1.0, v28
	v_rcp_f32_e32 v26, v26
	v_mul_f32_e32 v22, 0xbfb8aa3b, v22
	v_exp_f32_e32 v22, v22
	v_mul_f32_e32 v23, 0xbfb8aa3b, v23
	v_fma_f32 v27, v27, s21, 0.5
	v_exp_f32_e32 v23, v23
	v_max_f32_e32 v27, 1.0, v27
	v_fma_f32 v26, v26, s21, 0.5
	v_cvt_pk_u8_f32 v0, v27, 2, v0
	v_max_f32_e32 v26, 1.0, v26
	v_cvt_pk_u8_f32 v0, v26, 3, v0
	v_add_f32_e32 v22, 1.0, v22
	v_rcp_f32_e32 v22, v22
	global_store_dword v[62:63], v0, off offset:2304
	v_add_f32_e32 v0, 1.0, v23
	v_rcp_f32_e32 v0, v0
	v_mul_f32_e32 v23, 0xbfb8aa3b, v24
	v_exp_f32_e32 v23, v23
	v_mul_f32_e32 v24, 0xbfb8aa3b, v25
	v_exp_f32_e32 v24, v24
	v_fma_f32 v22, v22, s21, 0.5
	v_max_f32_e32 v22, 1.0, v22
	v_fma_f32 v0, v0, s21, 0.5
	v_cvt_pk_u8_f32 v22, v22, 0, 0
	v_max_f32_e32 v0, 1.0, v0
	v_add_f32_e32 v23, 1.0, v23
	v_rcp_f32_e32 v23, v23
	v_cvt_pk_u8_f32 v0, v0, 1, v22
	v_add_f32_e32 v22, 1.0, v24
	v_rcp_f32_e32 v22, v22
	v_mul_f32_e32 v18, 0xbfb8aa3b, v18
	v_exp_f32_e32 v18, v18
	v_mul_f32_e32 v19, 0xbfb8aa3b, v19
	v_fma_f32 v23, v23, s21, 0.5
	v_exp_f32_e32 v19, v19
	v_max_f32_e32 v23, 1.0, v23
	v_fma_f32 v22, v22, s21, 0.5
	v_cvt_pk_u8_f32 v0, v23, 2, v0
	v_max_f32_e32 v22, 1.0, v22
	v_cvt_pk_u8_f32 v0, v22, 3, v0
	v_add_f32_e32 v18, 1.0, v18
	v_rcp_f32_e32 v18, v18
	global_store_dword v[62:63], v0, off offset:2560
	v_add_f32_e32 v0, 1.0, v19
	v_rcp_f32_e32 v0, v0
	v_mul_f32_e32 v19, 0xbfb8aa3b, v20
	v_exp_f32_e32 v19, v19
	v_mul_f32_e32 v20, 0xbfb8aa3b, v21
	v_exp_f32_e32 v20, v20
	v_fma_f32 v18, v18, s21, 0.5
	v_max_f32_e32 v18, 1.0, v18
	v_fma_f32 v0, v0, s21, 0.5
	v_cvt_pk_u8_f32 v18, v18, 0, 0
	v_max_f32_e32 v0, 1.0, v0
	v_add_f32_e32 v19, 1.0, v19
	v_rcp_f32_e32 v19, v19
	v_cvt_pk_u8_f32 v0, v0, 1, v18
	v_add_f32_e32 v18, 1.0, v20
	v_rcp_f32_e32 v18, v18
	v_mul_f32_e32 v14, 0xbfb8aa3b, v14
	v_exp_f32_e32 v14, v14
	v_mul_f32_e32 v15, 0xbfb8aa3b, v15
	v_fma_f32 v19, v19, s21, 0.5
	v_exp_f32_e32 v15, v15
	v_max_f32_e32 v19, 1.0, v19
	v_fma_f32 v18, v18, s21, 0.5
	v_cvt_pk_u8_f32 v0, v19, 2, v0
	v_max_f32_e32 v18, 1.0, v18
	v_cvt_pk_u8_f32 v0, v18, 3, v0
	v_add_f32_e32 v14, 1.0, v14
	v_rcp_f32_e32 v14, v14
	global_store_dword v[62:63], v0, off offset:2816
	v_add_f32_e32 v0, 1.0, v15
	v_rcp_f32_e32 v0, v0
	v_mul_f32_e32 v15, 0xbfb8aa3b, v16
	v_exp_f32_e32 v15, v15
	v_mul_f32_e32 v16, 0xbfb8aa3b, v17
	v_exp_f32_e32 v16, v16
	v_fma_f32 v14, v14, s21, 0.5
	v_max_f32_e32 v14, 1.0, v14
	v_fma_f32 v0, v0, s21, 0.5
	v_cvt_pk_u8_f32 v14, v14, 0, 0
	v_max_f32_e32 v0, 1.0, v0
	v_add_f32_e32 v15, 1.0, v15
	v_rcp_f32_e32 v15, v15
	v_cvt_pk_u8_f32 v0, v0, 1, v14
	v_add_f32_e32 v14, 1.0, v16
	v_rcp_f32_e32 v14, v14
	v_mul_f32_e32 v10, 0xbfb8aa3b, v10
	v_exp_f32_e32 v10, v10
	v_mul_f32_e32 v11, 0xbfb8aa3b, v11
	v_fma_f32 v15, v15, s21, 0.5
	v_exp_f32_e32 v11, v11
	v_max_f32_e32 v15, 1.0, v15
	v_fma_f32 v14, v14, s21, 0.5
	v_cvt_pk_u8_f32 v0, v15, 2, v0
	v_max_f32_e32 v14, 1.0, v14
	v_cvt_pk_u8_f32 v0, v14, 3, v0
	v_add_f32_e32 v10, 1.0, v10
	v_rcp_f32_e32 v10, v10
	global_store_dword v[62:63], v0, off offset:3072
	v_add_f32_e32 v0, 1.0, v11
	v_rcp_f32_e32 v0, v0
	v_mul_f32_e32 v11, 0xbfb8aa3b, v12
	v_exp_f32_e32 v11, v11
	v_mul_f32_e32 v12, 0xbfb8aa3b, v13
	v_exp_f32_e32 v12, v12
	v_fma_f32 v10, v10, s21, 0.5
	v_max_f32_e32 v10, 1.0, v10
	v_fma_f32 v0, v0, s21, 0.5
	v_cvt_pk_u8_f32 v10, v10, 0, 0
	v_max_f32_e32 v0, 1.0, v0
	v_add_f32_e32 v11, 1.0, v11
	v_rcp_f32_e32 v11, v11
	v_cvt_pk_u8_f32 v0, v0, 1, v10
	v_add_f32_e32 v10, 1.0, v12
	v_rcp_f32_e32 v10, v10
	v_mul_f32_e32 v6, 0xbfb8aa3b, v6
	v_exp_f32_e32 v6, v6
	v_mul_f32_e32 v7, 0xbfb8aa3b, v7
	v_fma_f32 v11, v11, s21, 0.5
	v_exp_f32_e32 v7, v7
	v_max_f32_e32 v11, 1.0, v11
	v_fma_f32 v10, v10, s21, 0.5
	v_cvt_pk_u8_f32 v0, v11, 2, v0
	v_max_f32_e32 v10, 1.0, v10
	v_cvt_pk_u8_f32 v0, v10, 3, v0
	v_add_f32_e32 v6, 1.0, v6
	v_rcp_f32_e32 v6, v6
	global_store_dword v[62:63], v0, off offset:3328
	v_add_f32_e32 v0, 1.0, v7
	v_rcp_f32_e32 v0, v0
	v_mul_f32_e32 v7, 0xbfb8aa3b, v8
	v_exp_f32_e32 v7, v7
	v_mul_f32_e32 v8, 0xbfb8aa3b, v9
	v_exp_f32_e32 v8, v8
	v_fma_f32 v6, v6, s21, 0.5
	v_max_f32_e32 v6, 1.0, v6
	v_fma_f32 v0, v0, s21, 0.5
	v_cvt_pk_u8_f32 v6, v6, 0, 0
	v_max_f32_e32 v0, 1.0, v0
	v_add_f32_e32 v7, 1.0, v7
	v_rcp_f32_e32 v7, v7
	v_cvt_pk_u8_f32 v0, v0, 1, v6
	v_add_f32_e32 v6, 1.0, v8
	v_rcp_f32_e32 v6, v6
	v_mul_f32_e32 v2, 0xbfb8aa3b, v2
	v_exp_f32_e32 v2, v2
	v_mul_f32_e32 v3, 0xbfb8aa3b, v3
	v_fma_f32 v7, v7, s21, 0.5
	v_exp_f32_e32 v3, v3
	v_max_f32_e32 v7, 1.0, v7
	v_fma_f32 v6, v6, s21, 0.5
	v_cvt_pk_u8_f32 v0, v7, 2, v0
	v_max_f32_e32 v6, 1.0, v6
	v_cvt_pk_u8_f32 v0, v6, 3, v0
	v_add_f32_e32 v2, 1.0, v2
	v_rcp_f32_e32 v2, v2
	global_store_dword v[62:63], v0, off offset:3584
	v_add_f32_e32 v0, 1.0, v3
	v_rcp_f32_e32 v0, v0
	v_mul_f32_e32 v3, 0xbfb8aa3b, v4
	v_exp_f32_e32 v3, v3
	v_mul_f32_e32 v4, 0xbfb8aa3b, v5
	v_exp_f32_e32 v4, v4
	v_fma_f32 v2, v2, s21, 0.5
	v_max_f32_e32 v2, 1.0, v2
	v_fma_f32 v0, v0, s21, 0.5
	v_cvt_pk_u8_f32 v2, v2, 0, 0
	v_max_f32_e32 v0, 1.0, v0
	v_add_f32_e32 v3, 1.0, v3
	v_rcp_f32_e32 v3, v3
	v_cvt_pk_u8_f32 v0, v0, 1, v2
	v_add_f32_e32 v2, 1.0, v4
	v_rcp_f32_e32 v2, v2
	v_fma_f32 v3, v3, s21, 0.5
	s_add_i32 s96, s96, 1
	v_max_f32_e32 v3, 1.0, v3
	v_fma_f32 v2, v2, s21, 0.5
	s_add_u32 s12, s12, 0x200000
	v_cvt_pk_u8_f32 v0, v3, 2, v0
	v_max_f32_e32 v2, 1.0, v2
	s_addc_u32 s13, s13, 0
	v_cvt_pk_u8_f32 v0, v2, 3, v0
	s_cmp_lg_u32 s96, 3
	s_mov_b32 s97, 0x12000
	global_store_dword v[62:63], v0, off offset:3840
	s_cbranch_scc1 .LBB0_328
	s_lshl_b64 s[2:3], s[8:9], 10
	s_add_u32 s12, s72, s18
	s_addc_u32 s13, s73, s19
	v_mov_b32_e32 v2, v1
	v_mov_b32_e32 v3, v1
	s_add_u32 s16, s72, s2
	v_mov_b32_e32 v0, v1
	v_mov_b64_e32 v[6:7], v[2:3]
	v_mov_b64_e32 v[10:11], v[2:3]
	v_mov_b64_e32 v[22:23], v[2:3]
	v_mov_b64_e32 v[26:27], v[2:3]
	v_mov_b64_e32 v[38:39], v[2:3]
	v_mov_b64_e32 v[42:43], v[2:3]
	v_mov_b64_e32 v[54:55], v[2:3]
	v_mov_b64_e32 v[58:59], v[2:3]
	v_mov_b64_e32 v[14:15], v[2:3]
	v_mov_b64_e32 v[18:19], v[2:3]
	v_mov_b64_e32 v[30:31], v[2:3]
	v_mov_b64_e32 v[34:35], v[2:3]
	v_mov_b64_e32 v[46:47], v[2:3]
	v_mov_b64_e32 v[50:51], v[2:3]
	v_mov_b64_e32 v[62:63], v[2:3]
	v_mov_b64_e32 v[66:67], v[2:3]
	v_mov_b64_e32 v[70:71], v[2:3]
	v_mov_b64_e32 v[74:75], v[2:3]
	v_mov_b64_e32 v[86:87], v[2:3]
	v_mov_b64_e32 v[90:91], v[2:3]
	v_mov_b64_e32 v[102:103], v[2:3]
	v_mov_b64_e32 v[106:107], v[2:3]
	v_mov_b64_e32 v[118:119], v[2:3]
	v_mov_b64_e32 v[122:123], v[2:3]
	v_mov_b64_e32 v[78:79], v[2:3]
	v_mov_b64_e32 v[82:83], v[2:3]
	v_mov_b64_e32 v[94:95], v[2:3]
	v_mov_b64_e32 v[98:99], v[2:3]
	v_mov_b64_e32 v[110:111], v[2:3]
	v_mov_b64_e32 v[114:115], v[2:3]
	v_mov_b64_e32 v[126:127], v[2:3]
	v_mov_b64_e32 v[130:131], v[2:3]
	s_addc_u32 s17, s73, s3
	s_mov_b32 s56, 0
	v_mov_b64_e32 v[4:5], v[0:1]
	v_mov_b64_e32 v[8:9], v[0:1]
	v_mov_b64_e32 v[20:21], v[0:1]
	v_mov_b64_e32 v[24:25], v[0:1]
	v_mov_b64_e32 v[36:37], v[0:1]
	v_mov_b64_e32 v[40:41], v[0:1]
	v_mov_b64_e32 v[52:53], v[0:1]
	v_mov_b64_e32 v[56:57], v[0:1]
	v_mov_b64_e32 v[12:13], v[0:1]
	v_mov_b64_e32 v[16:17], v[0:1]
	v_mov_b64_e32 v[28:29], v[0:1]
	v_mov_b64_e32 v[32:33], v[0:1]
	v_mov_b64_e32 v[44:45], v[0:1]
	v_mov_b64_e32 v[48:49], v[0:1]
	v_mov_b64_e32 v[60:61], v[0:1]
	v_mov_b64_e32 v[64:65], v[0:1]
	v_mov_b64_e32 v[68:69], v[0:1]
	v_mov_b64_e32 v[72:73], v[0:1]
	v_mov_b64_e32 v[84:85], v[0:1]
	v_mov_b64_e32 v[88:89], v[0:1]
	v_mov_b64_e32 v[100:101], v[0:1]
	v_mov_b64_e32 v[104:105], v[0:1]
	v_mov_b64_e32 v[116:117], v[0:1]
	v_mov_b64_e32 v[120:121], v[0:1]
	v_mov_b64_e32 v[76:77], v[0:1]
	v_mov_b64_e32 v[80:81], v[0:1]
	v_mov_b64_e32 v[92:93], v[0:1]
	v_mov_b64_e32 v[96:97], v[0:1]
	v_mov_b64_e32 v[108:109], v[0:1]
	v_mov_b64_e32 v[112:113], v[0:1]
	v_mov_b64_e32 v[124:125], v[0:1]
	v_mov_b64_e32 v[128:129], v[0:1]
	s_movk_i32 s96, 0x5000
	s_branch .LBB0_340

.LBB0_341:
	s_cmpk_eq_i32 s40, 0x400
	s_cselect_b64 s[52:53], -1, 0
	s_and_b64 s[52:53], s[2:3], s[52:53]
	s_and_b64 s[54:55], s[52:53], exec
	s_cselect_b32 s82, s63, s57
	s_add_u32 s83, s18, s40
	s_addc_u32 s87, s19, s41
	s_cmpk_eq_i32 s40, 0x400
	s_cselect_b64 s[54:55], -1, 0
	s_and_b64 s[54:55], s[54:55], exec
	s_cselect_b32 s54, s82, s83
	s_and_b64 s[82:83], s[52:53], exec
	s_cselect_b32 s55, s66, s58
	s_cmpk_eq_i32 s40, 0x400
	v_add_u32_e32 v145, s6, v143
	s_cselect_b64 s[82:83], -1, 0
	ds_read_b128 v[146:149], v145
	ds_read_b128 v[150:153], v145 offset:1024
	ds_read_b128 v[158:161], v145 offset:2048
	ds_read_b128 v[162:165], v145 offset:3072
	v_add_u32_e32 v145, s7, v143
	s_and_b64 s[94:95], s[82:83], exec
	ds_read_b128 v[196:199], v145
	ds_read_b128 v[200:203], v145 offset:1024
	ds_read_b128 v[204:207], v145 offset:2048
	ds_read_b128 v[208:211], v145 offset:3072
	s_cselect_b32 s55, s55, s87
	s_and_b64 s[82:83], s[82:83], s[8:9]
	s_and_b64 s[82:83], s[82:83], exec
	s_cselect_b32 s83, 0, s40
	s_cselect_b32 s82, 0, s41
	s_add_u32 s83, s59, s83
	s_addc_u32 s82, s62, s82
	s_and_b64 s[52:53], s[52:53], exec
	s_cselect_b32 s53, s84, s82
	s_cselect_b32 s52, s70, s83
	v_lshl_add_u64 v[154:155], v[138:139], 0, s[40:41]
	s_add_i32 s87, s85, 0
	v_lshl_add_u64 v[154:155], v[154:155], 0, s[78:79]
	s_add_i32 m0, s87, 0xc000
	ds_read_b128 v[212:215], v144
	ds_read_b128 v[216:219], v144 offset:1024
	ds_read_b128 v[220:223], v144 offset:2048
	ds_read_b128 v[224:227], v144 offset:3072
	ds_read_b128 v[228:231], v144 offset:4096
	ds_read_b128 v[232:235], v144 offset:5120
	ds_read_b128 v[236:239], v144 offset:6144
	ds_read_b128 v[240:243], v144 offset:7168
	global_load_lds_dwordx4 v[154:155], off
	v_lshl_add_u64 v[154:155], v[136:137], 0, s[40:41]
	v_lshl_add_u64 v[154:155], v[154:155], 0, s[78:79]
	s_add_i32 m0, s87, 0xe000
	s_nop 0
	global_load_lds_dwordx4 v[154:155], off
	s_waitcnt vmcnt(8)
	s_waitcnt lgkmcnt(0)
	s_barrier
	s_setprio 1
	v_mfma_f32_16x16x32_bf16 v[128:131], v[146:149], v[212:215], v[128:131]
	v_mfma_f32_16x16x32_bf16 v[124:127], v[158:161], v[212:215], v[124:127]
	v_mfma_f32_16x16x32_bf16 v[112:115], v[146:149], v[220:223], v[112:115]
	v_mfma_f32_16x16x32_bf16 v[108:111], v[158:161], v[220:223], v[108:111]
	v_mfma_f32_16x16x32_bf16 v[96:99], v[146:149], v[228:231], v[96:99]
	v_mfma_f32_16x16x32_bf16 v[92:95], v[158:161], v[228:231], v[92:95]
	v_mfma_f32_16x16x32_bf16 v[80:83], v[146:149], v[236:239], v[80:83]
	v_mfma_f32_16x16x32_bf16 v[76:79], v[158:161], v[236:239], v[76:79]
	s_setprio 0
	s_setprio 1
	v_mfma_f32_16x16x32_bf16 v[128:131], v[150:153], v[216:219], v[128:131]
	v_mfma_f32_16x16x32_bf16 v[124:127], v[162:165], v[216:219], v[124:127]
	v_mfma_f32_16x16x32_bf16 v[112:115], v[150:153], v[224:227], v[112:115]
	v_mfma_f32_16x16x32_bf16 v[108:111], v[162:165], v[224:227], v[108:111]
	v_mfma_f32_16x16x32_bf16 v[96:99], v[150:153], v[232:235], v[96:99]
	v_mfma_f32_16x16x32_bf16 v[92:95], v[162:165], v[232:235], v[92:95]
	v_mfma_f32_16x16x32_bf16 v[80:83], v[150:153], v[240:243], v[80:83]
	v_mfma_f32_16x16x32_bf16 v[76:79], v[162:165], v[240:243], v[76:79]
	s_setprio 0
	s_setprio 1
	v_mfma_f32_16x16x32_bf16 v[120:123], v[196:199], v[212:215], v[120:123]
	v_mfma_f32_16x16x32_bf16 v[116:119], v[204:207], v[212:215], v[116:119]
	v_mfma_f32_16x16x32_bf16 v[104:107], v[196:199], v[220:223], v[104:107]
	v_mfma_f32_16x16x32_bf16 v[100:103], v[204:207], v[220:223], v[100:103]
	v_mfma_f32_16x16x32_bf16 v[88:91], v[196:199], v[228:231], v[88:91]
	v_mfma_f32_16x16x32_bf16 v[84:87], v[204:207], v[228:231], v[84:87]
	v_mfma_f32_16x16x32_bf16 v[72:75], v[196:199], v[236:239], v[72:75]
	v_mfma_f32_16x16x32_bf16 v[68:71], v[204:207], v[236:239], v[68:71]
	s_setprio 0
	s_setprio 1
	v_mfma_f32_16x16x32_bf16 v[120:123], v[200:203], v[216:219], v[120:123]
	v_mfma_f32_16x16x32_bf16 v[116:119], v[208:211], v[216:219], v[116:119]
	v_mfma_f32_16x16x32_bf16 v[104:107], v[200:203], v[224:227], v[104:107]
	v_mfma_f32_16x16x32_bf16 v[100:103], v[208:211], v[224:227], v[100:103]
	v_mfma_f32_16x16x32_bf16 v[88:91], v[200:203], v[232:235], v[88:91]
	v_mfma_f32_16x16x32_bf16 v[84:87], v[208:211], v[232:235], v[84:87]
	v_mfma_f32_16x16x32_bf16 v[72:75], v[200:203], v[240:243], v[72:75]
	v_mfma_f32_16x16x32_bf16 v[68:71], v[208:211], v[240:243], v[68:71]
	s_setprio 0
	s_barrier
	s_add_i32 s82, s6, s85
	v_lshl_add_u64 v[154:155], s[52:53], 0, v[132:133]
	s_mov_b32 m0, s82
	ds_read_b128 v[212:215], v144 offset:16384
	ds_read_b128 v[216:219], v144 offset:17408
	ds_read_b128 v[220:223], v144 offset:18432
	ds_read_b128 v[224:227], v144 offset:19456
	ds_read_b128 v[228:231], v144 offset:20480
	ds_read_b128 v[232:235], v144 offset:21504
	ds_read_b128 v[236:239], v144 offset:22528
	ds_read_b128 v[240:243], v144 offset:23552
	global_load_lds_dwordx4 v[154:155], off
	s_add_i32 m0, s82, 0x2000
	s_add_u32 s82, s52, 0x20000
	v_lshl_add_u64 v[176:177], s[52:53], 0, v[134:135]
	s_addc_u32 s83, s53, 0
	s_add_i32 s93, s7, s85
	global_load_lds_dwordx4 v[176:177], off
	v_lshl_add_u64 v[178:179], s[82:83], 0, v[132:133]
	s_mov_b32 m0, s93
	v_lshl_add_u64 v[194:195], s[54:55], 0, v[2:3]
	global_load_lds_dwordx4 v[178:179], off
	v_lshl_add_u64 v[178:179], s[82:83], 0, v[134:135]
	s_add_i32 m0, s93, 0x2000
	s_nop 0
	global_load_lds_dwordx4 v[178:179], off
	v_lshl_add_u64 v[178:179], s[54:55], 0, v[0:1]
	s_mov_b32 m0, s87
	s_nop 0
	global_load_lds_dwordx4 v[178:179], off
	s_add_i32 m0, s87, 0x2000
	s_nop 0
	global_load_lds_dwordx4 v[194:195], off
	s_waitcnt vmcnt(8)
	s_waitcnt lgkmcnt(0)
	s_barrier
	s_setprio 1
	v_mfma_f32_16x16x32_bf16 v[64:67], v[146:149], v[212:215], v[64:67]
	v_mfma_f32_16x16x32_bf16 v[60:63], v[158:161], v[212:215], v[60:63]
	v_mfma_f32_16x16x32_bf16 v[48:51], v[146:149], v[220:223], v[48:51]
	v_mfma_f32_16x16x32_bf16 v[44:47], v[158:161], v[220:223], v[44:47]
	v_mfma_f32_16x16x32_bf16 v[32:35], v[146:149], v[228:231], v[32:35]
	v_mfma_f32_16x16x32_bf16 v[28:31], v[158:161], v[228:231], v[28:31]
	v_mfma_f32_16x16x32_bf16 v[16:19], v[146:149], v[236:239], v[16:19]
	v_mfma_f32_16x16x32_bf16 v[12:15], v[158:161], v[236:239], v[12:15]
	s_setprio 0
	s_setprio 1
	v_mfma_f32_16x16x32_bf16 v[64:67], v[150:153], v[216:219], v[64:67]
	v_mfma_f32_16x16x32_bf16 v[60:63], v[162:165], v[216:219], v[60:63]
	v_mfma_f32_16x16x32_bf16 v[48:51], v[150:153], v[224:227], v[48:51]
	v_mfma_f32_16x16x32_bf16 v[44:47], v[162:165], v[224:227], v[44:47]
	v_mfma_f32_16x16x32_bf16 v[32:35], v[150:153], v[232:235], v[32:35]
	v_mfma_f32_16x16x32_bf16 v[28:31], v[162:165], v[232:235], v[28:31]
	v_mfma_f32_16x16x32_bf16 v[16:19], v[150:153], v[240:243], v[16:19]
	v_mfma_f32_16x16x32_bf16 v[12:15], v[162:165], v[240:243], v[12:15]
	s_setprio 0
	s_setprio 1
	v_mfma_f32_16x16x32_bf16 v[56:59], v[196:199], v[212:215], v[56:59]
	v_mfma_f32_16x16x32_bf16 v[52:55], v[204:207], v[212:215], v[52:55]
	v_mfma_f32_16x16x32_bf16 v[40:43], v[196:199], v[220:223], v[40:43]
	v_mfma_f32_16x16x32_bf16 v[36:39], v[204:207], v[220:223], v[36:39]
	v_mfma_f32_16x16x32_bf16 v[24:27], v[196:199], v[228:231], v[24:27]
	v_mfma_f32_16x16x32_bf16 v[20:23], v[204:207], v[228:231], v[20:23]
	v_mfma_f32_16x16x32_bf16 v[8:11], v[196:199], v[236:239], v[8:11]
	v_mfma_f32_16x16x32_bf16 v[4:7], v[204:207], v[236:239], v[4:7]
	s_setprio 0
	s_setprio 1
	v_mfma_f32_16x16x32_bf16 v[56:59], v[200:203], v[216:219], v[56:59]
	v_mfma_f32_16x16x32_bf16 v[52:55], v[208:211], v[216:219], v[52:55]
	v_mfma_f32_16x16x32_bf16 v[40:43], v[200:203], v[224:227], v[40:43]
	v_mfma_f32_16x16x32_bf16 v[36:39], v[208:211], v[224:227], v[36:39]
	v_mfma_f32_16x16x32_bf16 v[24:27], v[200:203], v[232:235], v[24:27]
	v_mfma_f32_16x16x32_bf16 v[20:23], v[208:211], v[232:235], v[20:23]
	v_mfma_f32_16x16x32_bf16 v[8:11], v[200:203], v[240:243], v[8:11]
	v_mfma_f32_16x16x32_bf16 v[4:7], v[208:211], v[240:243], v[4:7]
	s_setprio 0
	s_barrier
	v_add_u32_e32 v145, s10, v143
	ds_read_b128 v[146:149], v145
	ds_read_b128 v[150:153], v145 offset:1024
	ds_read_b128 v[158:161], v145 offset:2048
	ds_read_b128 v[162:165], v145 offset:3072
	v_add_u32_e32 v145, s11, v143
	ds_read_b128 v[196:199], v145
	ds_read_b128 v[200:203], v145 offset:1024
	ds_read_b128 v[204:207], v145 offset:2048
	ds_read_b128 v[208:211], v145 offset:3072
	s_add_u32 s54, s54, 0x20000
	s_addc_u32 s55, s55, 0
	v_lshl_add_u64 v[244:245], s[54:55], 0, v[0:1]
	s_add_i32 m0, s87, 0x4000
	ds_read_b128 v[212:215], v144 offset:32768
	ds_read_b128 v[216:219], v144 offset:33792
	ds_read_b128 v[220:223], v144 offset:34816
	ds_read_b128 v[224:227], v144 offset:35840
	ds_read_b128 v[228:231], v144 offset:36864
	ds_read_b128 v[232:235], v144 offset:37888
	ds_read_b128 v[236:239], v144 offset:38912
	ds_read_b128 v[240:243], v144 offset:39936
	global_load_lds_dwordx4 v[244:245], off
	v_lshl_add_u64 v[244:245], s[54:55], 0, v[2:3]
	s_add_i32 m0, s87, 0x6000
	s_nop 0
	global_load_lds_dwordx4 v[244:245], off
	s_waitcnt vmcnt(8)
	s_waitcnt lgkmcnt(0)
	s_barrier
	s_setprio 1
	v_mfma_f32_16x16x32_bf16 v[128:131], v[146:149], v[212:215], v[128:131]
	v_mfma_f32_16x16x32_bf16 v[124:127], v[158:161], v[212:215], v[124:127]
	v_mfma_f32_16x16x32_bf16 v[112:115], v[146:149], v[220:223], v[112:115]
	v_mfma_f32_16x16x32_bf16 v[108:111], v[158:161], v[220:223], v[108:111]
	v_mfma_f32_16x16x32_bf16 v[96:99], v[146:149], v[228:231], v[96:99]
	v_mfma_f32_16x16x32_bf16 v[92:95], v[158:161], v[228:231], v[92:95]
	v_mfma_f32_16x16x32_bf16 v[80:83], v[146:149], v[236:239], v[80:83]
	v_mfma_f32_16x16x32_bf16 v[76:79], v[158:161], v[236:239], v[76:79]
	s_setprio 0
	s_setprio 1
	v_mfma_f32_16x16x32_bf16 v[128:131], v[150:153], v[216:219], v[128:131]
	v_mfma_f32_16x16x32_bf16 v[124:127], v[162:165], v[216:219], v[124:127]
	v_mfma_f32_16x16x32_bf16 v[112:115], v[150:153], v[224:227], v[112:115]
	v_mfma_f32_16x16x32_bf16 v[108:111], v[162:165], v[224:227], v[108:111]
	v_mfma_f32_16x16x32_bf16 v[96:99], v[150:153], v[232:235], v[96:99]
	v_mfma_f32_16x16x32_bf16 v[92:95], v[162:165], v[232:235], v[92:95]
	v_mfma_f32_16x16x32_bf16 v[80:83], v[150:153], v[240:243], v[80:83]
	v_mfma_f32_16x16x32_bf16 v[76:79], v[162:165], v[240:243], v[76:79]
	s_setprio 0
	s_setprio 1
	v_mfma_f32_16x16x32_bf16 v[120:123], v[196:199], v[212:215], v[120:123]
	v_mfma_f32_16x16x32_bf16 v[116:119], v[204:207], v[212:215], v[116:119]
	v_mfma_f32_16x16x32_bf16 v[104:107], v[196:199], v[220:223], v[104:107]
	v_mfma_f32_16x16x32_bf16 v[100:103], v[204:207], v[220:223], v[100:103]
	v_mfma_f32_16x16x32_bf16 v[88:91], v[196:199], v[228:231], v[88:91]
	v_mfma_f32_16x16x32_bf16 v[84:87], v[204:207], v[228:231], v[84:87]
	v_mfma_f32_16x16x32_bf16 v[72:75], v[196:199], v[236:239], v[72:75]
	v_mfma_f32_16x16x32_bf16 v[68:71], v[204:207], v[236:239], v[68:71]
	s_setprio 0
	s_setprio 1
	v_mfma_f32_16x16x32_bf16 v[120:123], v[200:203], v[216:219], v[120:123]
	v_mfma_f32_16x16x32_bf16 v[116:119], v[208:211], v[216:219], v[116:119]
	v_mfma_f32_16x16x32_bf16 v[104:107], v[200:203], v[224:227], v[104:107]
	v_mfma_f32_16x16x32_bf16 v[100:103], v[208:211], v[224:227], v[100:103]
	v_mfma_f32_16x16x32_bf16 v[88:91], v[200:203], v[232:235], v[88:91]
	v_mfma_f32_16x16x32_bf16 v[84:87], v[208:211], v[232:235], v[84:87]
	v_mfma_f32_16x16x32_bf16 v[72:75], v[200:203], v[240:243], v[72:75]
	v_mfma_f32_16x16x32_bf16 v[68:71], v[208:211], v[240:243], v[68:71]
	s_setprio 0
	s_barrier
	s_add_i32 s54, s10, s85
	v_lshl_add_u64 v[154:155], v[154:155], 0, s[24:25]
	s_mov_b32 m0, s54
	ds_read_b128 v[212:215], v144 offset:49152
	ds_read_b128 v[216:219], v144 offset:50176
	ds_read_b128 v[220:223], v144 offset:51200
	ds_read_b128 v[224:227], v144 offset:52224
	ds_read_b128 v[228:231], v144 offset:53248
	ds_read_b128 v[232:235], v144 offset:54272
	ds_read_b128 v[236:239], v144 offset:55296
	ds_read_b128 v[240:243], v144 offset:56320
	global_load_lds_dwordx4 v[154:155], off
	s_add_i32 m0, s54, 0x2000
	s_add_u32 s52, s52, 0x20080
	v_lshl_add_u64 v[154:155], v[176:177], 0, s[24:25]
	s_addc_u32 s53, s53, 0
	s_add_i32 s54, s11, s85
	global_load_lds_dwordx4 v[154:155], off
	v_lshl_add_u64 v[154:155], s[52:53], 0, v[132:133]
	s_mov_b32 m0, s54
	s_nop 0
	global_load_lds_dwordx4 v[154:155], off
	v_lshl_add_u64 v[154:155], s[52:53], 0, v[134:135]
	s_add_i32 m0, s54, 0x2000
	s_nop 0
	global_load_lds_dwordx4 v[154:155], off
	v_lshl_add_u64 v[154:155], v[178:179], 0, s[24:25]
	s_add_i32 m0, s87, 0x8000
	s_nop 0
	global_load_lds_dwordx4 v[154:155], off
	v_lshl_add_u64 v[154:155], v[194:195], 0, s[24:25]
	s_add_i32 m0, s87, 0xa000
	s_nop 0
	global_load_lds_dwordx4 v[154:155], off
	s_waitcnt vmcnt(8)
	s_waitcnt lgkmcnt(0)
	s_barrier
	s_setprio 1
	v_mfma_f32_16x16x32_bf16 v[64:67], v[146:149], v[212:215], v[64:67]
	v_mfma_f32_16x16x32_bf16 v[60:63], v[158:161], v[212:215], v[60:63]
	v_mfma_f32_16x16x32_bf16 v[48:51], v[146:149], v[220:223], v[48:51]
	v_mfma_f32_16x16x32_bf16 v[44:47], v[158:161], v[220:223], v[44:47]
	v_mfma_f32_16x16x32_bf16 v[32:35], v[146:149], v[228:231], v[32:35]
	v_mfma_f32_16x16x32_bf16 v[28:31], v[158:161], v[228:231], v[28:31]
	v_mfma_f32_16x16x32_bf16 v[16:19], v[146:149], v[236:239], v[16:19]
	v_mfma_f32_16x16x32_bf16 v[12:15], v[158:161], v[236:239], v[12:15]
	s_setprio 0
	s_setprio 1
	v_mfma_f32_16x16x32_bf16 v[64:67], v[150:153], v[216:219], v[64:67]
	v_mfma_f32_16x16x32_bf16 v[60:63], v[162:165], v[216:219], v[60:63]
	v_mfma_f32_16x16x32_bf16 v[48:51], v[150:153], v[224:227], v[48:51]
	v_mfma_f32_16x16x32_bf16 v[44:47], v[162:165], v[224:227], v[44:47]
	v_mfma_f32_16x16x32_bf16 v[32:35], v[150:153], v[232:235], v[32:35]
	v_mfma_f32_16x16x32_bf16 v[28:31], v[162:165], v[232:235], v[28:31]
	v_mfma_f32_16x16x32_bf16 v[16:19], v[150:153], v[240:243], v[16:19]
	v_mfma_f32_16x16x32_bf16 v[12:15], v[162:165], v[240:243], v[12:15]
	s_setprio 0
	s_setprio 1
	v_mfma_f32_16x16x32_bf16 v[56:59], v[196:199], v[212:215], v[56:59]
	v_mfma_f32_16x16x32_bf16 v[52:55], v[204:207], v[212:215], v[52:55]
	v_mfma_f32_16x16x32_bf16 v[40:43], v[196:199], v[220:223], v[40:43]
	v_mfma_f32_16x16x32_bf16 v[36:39], v[204:207], v[220:223], v[36:39]
	v_mfma_f32_16x16x32_bf16 v[24:27], v[196:199], v[228:231], v[24:27]
	v_mfma_f32_16x16x32_bf16 v[20:23], v[204:207], v[228:231], v[20:23]
	v_mfma_f32_16x16x32_bf16 v[8:11], v[196:199], v[236:239], v[8:11]
	v_mfma_f32_16x16x32_bf16 v[4:7], v[204:207], v[236:239], v[4:7]
	s_setprio 0
	s_setprio 1
	v_mfma_f32_16x16x32_bf16 v[56:59], v[200:203], v[216:219], v[56:59]
	v_mfma_f32_16x16x32_bf16 v[52:55], v[208:211], v[216:219], v[52:55]
	v_mfma_f32_16x16x32_bf16 v[40:43], v[200:203], v[224:227], v[40:43]
	v_mfma_f32_16x16x32_bf16 v[36:39], v[208:211], v[224:227], v[36:39]
	v_mfma_f32_16x16x32_bf16 v[24:27], v[200:203], v[232:235], v[24:27]
	v_mfma_f32_16x16x32_bf16 v[20:23], v[208:211], v[232:235], v[20:23]
	v_mfma_f32_16x16x32_bf16 v[8:11], v[200:203], v[240:243], v[8:11]
	v_mfma_f32_16x16x32_bf16 v[4:7], v[208:211], v[240:243], v[4:7]
	s_setprio 0
	s_barrier
	s_add_i32 s86, s86, 2
	s_add_u32 s40, s40, 0x100
	s_addc_u32 s41, s41, 0
	s_cmp_gt_u32 s86, 5
	s_cbranch_scc0 .LBB0_341
	s_cmp_eq_u32 s20, 2
	s_movk_i32 s58, 0x21ff
	s_mov_b64 s[8:9], 0x800
	s_mov_b64 s[18:19], 0x200
	s_cbranch_scc0 .LBB0_346
	s_waitcnt vmcnt(0)
	s_cmpk_gt_u32 s67, 0xff
	s_cbranch_scc1 .LBB0_345
	s_barrier

.LBB0_465:
	s_add_u32 s17, s18, 0xf1598080
	s_addc_u32 s20, s19, -1
	s_cmp_lg_u32 s16, 4
	s_cselect_b32 s17, s17, 0
	s_cselect_b32 s20, s20, 0
	s_add_u32 s42, s2, s17
	s_addc_u32 s43, s3, s20
	s_add_i32 s48, 0, 0x10000
	s_add_u32 s40, s8, s17
	v_add_u32_e32 v143, s48, v141
	s_addc_u32 s41, s9, s20
	s_add_i32 s17, 0, 0x14000
	ds_read_b128 v[144:147], v143
	ds_read_b128 v[148:151], v143 offset:1024
	ds_read_b128 v[152:155], v143 offset:2048
	ds_read_b128 v[158:161], v143 offset:3072
	v_add_u32_e32 v143, s17, v141
	ds_read_b128 v[162:165], v143
	ds_read_b128 v[196:199], v143 offset:1024
	ds_read_b128 v[200:203], v143 offset:2048
	ds_read_b128 v[204:207], v143 offset:3072
	v_lshl_add_u64 v[240:241], v[138:139], 0, s[18:19]
	s_add_i32 m0, s6, 0xc000
	ds_read_b128 v[208:211], v142
	ds_read_b128 v[212:215], v142 offset:1024
	ds_read_b128 v[216:219], v142 offset:2048
	ds_read_b128 v[220:223], v142 offset:3072
	ds_read_b128 v[224:227], v142 offset:4096
	ds_read_b128 v[228:231], v142 offset:5120
	ds_read_b128 v[232:235], v142 offset:6144
	ds_read_b128 v[236:239], v142 offset:7168
	global_load_lds_dwordx4 v[240:241], off
	v_lshl_add_u64 v[240:241], v[136:137], 0, s[18:19]
	s_add_i32 m0, s6, 0xe000
	s_nop 0
	global_load_lds_dwordx4 v[240:241], off
	s_waitcnt vmcnt(8)
	s_waitcnt lgkmcnt(0)
	s_barrier
	s_setprio 1
	v_mfma_f32_16x16x32_bf16 v[126:129], v[144:147], v[208:211], v[126:129]
	v_mfma_f32_16x16x32_bf16 v[122:125], v[152:155], v[208:211], v[122:125]
	v_mfma_f32_16x16x32_bf16 v[110:113], v[144:147], v[216:219], v[110:113]
	v_mfma_f32_16x16x32_bf16 v[106:109], v[152:155], v[216:219], v[106:109]
	v_mfma_f32_16x16x32_bf16 v[94:97], v[144:147], v[224:227], v[94:97]
	v_mfma_f32_16x16x32_bf16 v[90:93], v[152:155], v[224:227], v[90:93]
	v_mfma_f32_16x16x32_bf16 v[78:81], v[144:147], v[232:235], v[78:81]
	v_mfma_f32_16x16x32_bf16 v[74:77], v[152:155], v[232:235], v[74:77]
	s_setprio 0
	s_setprio 1
	v_mfma_f32_16x16x32_bf16 v[126:129], v[148:151], v[212:215], v[126:129]
	v_mfma_f32_16x16x32_bf16 v[122:125], v[158:161], v[212:215], v[122:125]
	v_mfma_f32_16x16x32_bf16 v[110:113], v[148:151], v[220:223], v[110:113]
	v_mfma_f32_16x16x32_bf16 v[106:109], v[158:161], v[220:223], v[106:109]
	v_mfma_f32_16x16x32_bf16 v[94:97], v[148:151], v[228:231], v[94:97]
	v_mfma_f32_16x16x32_bf16 v[90:93], v[158:161], v[228:231], v[90:93]
	v_mfma_f32_16x16x32_bf16 v[78:81], v[148:151], v[236:239], v[78:81]
	v_mfma_f32_16x16x32_bf16 v[74:77], v[158:161], v[236:239], v[74:77]
	s_setprio 0
	s_setprio 1
	v_mfma_f32_16x16x32_bf16 v[118:121], v[162:165], v[208:211], v[118:121]
	v_mfma_f32_16x16x32_bf16 v[114:117], v[200:203], v[208:211], v[114:117]
	v_mfma_f32_16x16x32_bf16 v[102:105], v[162:165], v[216:219], v[102:105]
	v_mfma_f32_16x16x32_bf16 v[98:101], v[200:203], v[216:219], v[98:101]
	v_mfma_f32_16x16x32_bf16 v[86:89], v[162:165], v[224:227], v[86:89]
	v_mfma_f32_16x16x32_bf16 v[82:85], v[200:203], v[224:227], v[82:85]
	v_mfma_f32_16x16x32_bf16 v[70:73], v[162:165], v[232:235], v[70:73]
	v_mfma_f32_16x16x32_bf16 v[66:69], v[200:203], v[232:235], v[66:69]
	s_setprio 0
	s_setprio 1
	v_mfma_f32_16x16x32_bf16 v[118:121], v[196:199], v[212:215], v[118:121]
	v_mfma_f32_16x16x32_bf16 v[114:117], v[204:207], v[212:215], v[114:117]
	v_mfma_f32_16x16x32_bf16 v[102:105], v[196:199], v[220:223], v[102:105]
	v_mfma_f32_16x16x32_bf16 v[98:101], v[204:207], v[220:223], v[98:101]
	v_mfma_f32_16x16x32_bf16 v[86:89], v[196:199], v[228:231], v[86:89]
	v_mfma_f32_16x16x32_bf16 v[82:85], v[204:207], v[228:231], v[82:85]
	v_mfma_f32_16x16x32_bf16 v[70:73], v[196:199], v[236:239], v[70:73]
	v_mfma_f32_16x16x32_bf16 v[66:69], v[204:207], v[236:239], v[66:69]
	s_setprio 0
	s_barrier
	s_add_i32 s20, s48, s5
	v_lshl_add_u64 v[240:241], s[40:41], 0, v[0:1]
	s_mov_b32 m0, s20
	ds_read_b128 v[208:211], v142 offset:16384
	ds_read_b128 v[212:215], v142 offset:17408
	ds_read_b128 v[216:219], v142 offset:18432
	ds_read_b128 v[220:223], v142 offset:19456
	ds_read_b128 v[224:227], v142 offset:20480
	ds_read_b128 v[228:231], v142 offset:21504
	ds_read_b128 v[232:235], v142 offset:22528
	ds_read_b128 v[236:239], v142 offset:23552
	global_load_lds_dwordx4 v[240:241], off
	s_add_i32 m0, s20, 0x2000
	s_add_u32 s48, s40, 0x20000
	v_lshl_add_u64 v[242:243], s[40:41], 0, v[134:135]
	s_addc_u32 s49, s41, 0
	s_add_i32 s17, s17, s5
	global_load_lds_dwordx4 v[242:243], off
	v_lshl_add_u64 v[244:245], s[48:49], 0, v[0:1]
	s_mov_b32 m0, s17
	v_lshl_add_u64 v[246:247], s[42:43], 0, v[132:133]
	global_load_lds_dwordx4 v[244:245], off
	v_lshl_add_u64 v[244:245], s[48:49], 0, v[134:135]
	s_add_i32 m0, s17, 0x2000
	s_nop 0
	global_load_lds_dwordx4 v[244:245], off
	v_lshl_add_u64 v[244:245], s[42:43], 0, v[130:131]
	s_mov_b32 m0, s6
	s_nop 0
	global_load_lds_dwordx4 v[244:245], off
	s_mov_b32 m0, s7
	s_nop 0
	global_load_lds_dwordx4 v[246:247], off
	s_waitcnt vmcnt(8)
	s_waitcnt lgkmcnt(0)
	s_barrier
	s_setprio 1
	v_mfma_f32_16x16x32_bf16 v[62:65], v[144:147], v[208:211], v[62:65]
	v_mfma_f32_16x16x32_bf16 v[58:61], v[152:155], v[208:211], v[58:61]
	v_mfma_f32_16x16x32_bf16 v[46:49], v[144:147], v[216:219], v[46:49]
	v_mfma_f32_16x16x32_bf16 v[42:45], v[152:155], v[216:219], v[42:45]
	v_mfma_f32_16x16x32_bf16 v[30:33], v[144:147], v[224:227], v[30:33]
	v_mfma_f32_16x16x32_bf16 v[26:29], v[152:155], v[224:227], v[26:29]
	v_mfma_f32_16x16x32_bf16 v[14:17], v[144:147], v[232:235], v[14:17]
	v_mfma_f32_16x16x32_bf16 v[10:13], v[152:155], v[232:235], v[10:13]
	s_setprio 0
	s_setprio 1
	v_mfma_f32_16x16x32_bf16 v[62:65], v[148:151], v[212:215], v[62:65]
	v_mfma_f32_16x16x32_bf16 v[58:61], v[158:161], v[212:215], v[58:61]
	v_mfma_f32_16x16x32_bf16 v[46:49], v[148:151], v[220:223], v[46:49]
	v_mfma_f32_16x16x32_bf16 v[42:45], v[158:161], v[220:223], v[42:45]
	v_mfma_f32_16x16x32_bf16 v[30:33], v[148:151], v[228:231], v[30:33]
	v_mfma_f32_16x16x32_bf16 v[26:29], v[158:161], v[228:231], v[26:29]
	v_mfma_f32_16x16x32_bf16 v[14:17], v[148:151], v[236:239], v[14:17]
	v_mfma_f32_16x16x32_bf16 v[10:13], v[158:161], v[236:239], v[10:13]
	s_setprio 0
	s_setprio 1
	v_mfma_f32_16x16x32_bf16 v[54:57], v[162:165], v[208:211], v[54:57]
	v_mfma_f32_16x16x32_bf16 v[50:53], v[200:203], v[208:211], v[50:53]
	v_mfma_f32_16x16x32_bf16 v[38:41], v[162:165], v[216:219], v[38:41]
	v_mfma_f32_16x16x32_bf16 v[34:37], v[200:203], v[216:219], v[34:37]
	v_mfma_f32_16x16x32_bf16 v[22:25], v[162:165], v[224:227], v[22:25]
	v_mfma_f32_16x16x32_bf16 v[18:21], v[200:203], v[224:227], v[18:21]
	v_mfma_f32_16x16x32_bf16 v[6:9], v[162:165], v[232:235], v[6:9]
	v_mfma_f32_16x16x32_bf16 v[2:5], v[200:203], v[232:235], v[2:5]
	s_setprio 0
	s_setprio 1
	v_mfma_f32_16x16x32_bf16 v[54:57], v[196:199], v[212:215], v[54:57]
	v_mfma_f32_16x16x32_bf16 v[50:53], v[204:207], v[212:215], v[50:53]
	v_mfma_f32_16x16x32_bf16 v[38:41], v[196:199], v[220:223], v[38:41]
	v_mfma_f32_16x16x32_bf16 v[34:37], v[204:207], v[220:223], v[34:37]
	v_mfma_f32_16x16x32_bf16 v[22:25], v[196:199], v[228:231], v[22:25]
	v_mfma_f32_16x16x32_bf16 v[18:21], v[204:207], v[228:231], v[18:21]
	v_mfma_f32_16x16x32_bf16 v[6:9], v[196:199], v[236:239], v[6:9]
	v_mfma_f32_16x16x32_bf16 v[2:5], v[204:207], v[236:239], v[2:5]
	s_setprio 0
	s_barrier
	s_add_i32 s17, 0, 0x18000
	v_add_u32_e32 v143, s17, v141
	s_add_i32 s20, 0, 0x1c000
	ds_read_b128 v[144:147], v143
	ds_read_b128 v[148:151], v143 offset:1024
	ds_read_b128 v[152:155], v143 offset:2048
	ds_read_b128 v[158:161], v143 offset:3072
	v_add_u32_e32 v143, s20, v141
	ds_read_b128 v[162:165], v143
	ds_read_b128 v[196:199], v143 offset:1024
	ds_read_b128 v[200:203], v143 offset:2048
	ds_read_b128 v[204:207], v143 offset:3072
	s_add_u32 s42, s42, 0x20000
	s_addc_u32 s43, s43, 0
	s_mov_b32 m0, s10
	v_lshl_add_u64 v[248:249], s[42:43], 0, v[130:131]
	ds_read_b128 v[208:211], v142 offset:32768
	ds_read_b128 v[212:215], v142 offset:33792
	ds_read_b128 v[216:219], v142 offset:34816
	ds_read_b128 v[220:223], v142 offset:35840
	ds_read_b128 v[224:227], v142 offset:36864
	ds_read_b128 v[228:231], v142 offset:37888
	ds_read_b128 v[232:235], v142 offset:38912
	ds_read_b128 v[236:239], v142 offset:39936
	global_load_lds_dwordx4 v[248:249], off
	v_lshl_add_u64 v[248:249], s[42:43], 0, v[132:133]
	s_mov_b32 m0, s11
	s_nop 0
	global_load_lds_dwordx4 v[248:249], off
	s_waitcnt vmcnt(8)
	s_waitcnt lgkmcnt(0)
	s_barrier
	s_setprio 1
	v_mfma_f32_16x16x32_bf16 v[126:129], v[144:147], v[208:211], v[126:129]
	v_mfma_f32_16x16x32_bf16 v[122:125], v[152:155], v[208:211], v[122:125]
	v_mfma_f32_16x16x32_bf16 v[110:113], v[144:147], v[216:219], v[110:113]
	v_mfma_f32_16x16x32_bf16 v[106:109], v[152:155], v[216:219], v[106:109]
	v_mfma_f32_16x16x32_bf16 v[94:97], v[144:147], v[224:227], v[94:97]
	v_mfma_f32_16x16x32_bf16 v[90:93], v[152:155], v[224:227], v[90:93]
	v_mfma_f32_16x16x32_bf16 v[78:81], v[144:147], v[232:235], v[78:81]
	v_mfma_f32_16x16x32_bf16 v[74:77], v[152:155], v[232:235], v[74:77]
	s_setprio 0
	s_setprio 1
	v_mfma_f32_16x16x32_bf16 v[126:129], v[148:151], v[212:215], v[126:129]
	v_mfma_f32_16x16x32_bf16 v[122:125], v[158:161], v[212:215], v[122:125]
	v_mfma_f32_16x16x32_bf16 v[110:113], v[148:151], v[220:223], v[110:113]
	v_mfma_f32_16x16x32_bf16 v[106:109], v[158:161], v[220:223], v[106:109]
	v_mfma_f32_16x16x32_bf16 v[94:97], v[148:151], v[228:231], v[94:97]
	v_mfma_f32_16x16x32_bf16 v[90:93], v[158:161], v[228:231], v[90:93]
	v_mfma_f32_16x16x32_bf16 v[78:81], v[148:151], v[236:239], v[78:81]
	v_mfma_f32_16x16x32_bf16 v[74:77], v[158:161], v[236:239], v[74:77]
	s_setprio 0
	s_setprio 1
	v_mfma_f32_16x16x32_bf16 v[118:121], v[162:165], v[208:211], v[118:121]
	v_mfma_f32_16x16x32_bf16 v[114:117], v[200:203], v[208:211], v[114:117]
	v_mfma_f32_16x16x32_bf16 v[102:105], v[162:165], v[216:219], v[102:105]
	v_mfma_f32_16x16x32_bf16 v[98:101], v[200:203], v[216:219], v[98:101]
	v_mfma_f32_16x16x32_bf16 v[86:89], v[162:165], v[224:227], v[86:89]
	v_mfma_f32_16x16x32_bf16 v[82:85], v[200:203], v[224:227], v[82:85]
	v_mfma_f32_16x16x32_bf16 v[70:73], v[162:165], v[232:235], v[70:73]
	v_mfma_f32_16x16x32_bf16 v[66:69], v[200:203], v[232:235], v[66:69]
	s_setprio 0
	s_setprio 1
	v_mfma_f32_16x16x32_bf16 v[118:121], v[196:199], v[212:215], v[118:121]
	v_mfma_f32_16x16x32_bf16 v[114:117], v[204:207], v[212:215], v[114:117]
	v_mfma_f32_16x16x32_bf16 v[102:105], v[196:199], v[220:223], v[102:105]
	v_mfma_f32_16x16x32_bf16 v[98:101], v[204:207], v[220:223], v[98:101]
	v_mfma_f32_16x16x32_bf16 v[86:89], v[196:199], v[228:231], v[86:89]
	v_mfma_f32_16x16x32_bf16 v[82:85], v[204:207], v[228:231], v[82:85]
	v_mfma_f32_16x16x32_bf16 v[70:73], v[196:199], v[236:239], v[70:73]
	v_mfma_f32_16x16x32_bf16 v[66:69], v[204:207], v[236:239], v[66:69]
	s_setprio 0
	s_barrier
	s_add_i32 s17, s17, s5
	v_lshl_add_u64 v[240:241], v[240:241], 0, s[24:25]
	s_mov_b32 m0, s17
	ds_read_b128 v[208:211], v142 offset:49152
	ds_read_b128 v[212:215], v142 offset:50176
	ds_read_b128 v[216:219], v142 offset:51200
	ds_read_b128 v[220:223], v142 offset:52224
	ds_read_b128 v[224:227], v142 offset:53248
	ds_read_b128 v[228:231], v142 offset:54272
	ds_read_b128 v[232:235], v142 offset:55296
	ds_read_b128 v[236:239], v142 offset:56320
	global_load_lds_dwordx4 v[240:241], off
	s_add_i32 m0, s17, 0x2000
	s_add_u32 s40, s40, 0x20080
	v_lshl_add_u64 v[240:241], v[242:243], 0, s[24:25]
	s_addc_u32 s41, s41, 0
	s_add_i32 s17, s20, s5
	global_load_lds_dwordx4 v[240:241], off
	v_lshl_add_u64 v[240:241], s[40:41], 0, v[0:1]
	s_mov_b32 m0, s17
	s_nop 0
	global_load_lds_dwordx4 v[240:241], off
	v_lshl_add_u64 v[240:241], s[40:41], 0, v[134:135]
	s_add_i32 m0, s17, 0x2000
	s_nop 0
	global_load_lds_dwordx4 v[240:241], off
	v_lshl_add_u64 v[240:241], v[244:245], 0, s[24:25]
	s_mov_b32 m0, s12
	s_nop 0
	global_load_lds_dwordx4 v[240:241], off
	v_lshl_add_u64 v[240:241], v[246:247], 0, s[24:25]
	s_mov_b32 m0, s13
	s_nop 0
	global_load_lds_dwordx4 v[240:241], off
	s_waitcnt vmcnt(8)
	s_waitcnt lgkmcnt(0)
	s_barrier
	s_setprio 1
	v_mfma_f32_16x16x32_bf16 v[62:65], v[144:147], v[208:211], v[62:65]
	v_mfma_f32_16x16x32_bf16 v[58:61], v[152:155], v[208:211], v[58:61]
	v_mfma_f32_16x16x32_bf16 v[46:49], v[144:147], v[216:219], v[46:49]
	v_mfma_f32_16x16x32_bf16 v[42:45], v[152:155], v[216:219], v[42:45]
	v_mfma_f32_16x16x32_bf16 v[30:33], v[144:147], v[224:227], v[30:33]
	v_mfma_f32_16x16x32_bf16 v[26:29], v[152:155], v[224:227], v[26:29]
	v_mfma_f32_16x16x32_bf16 v[14:17], v[144:147], v[232:235], v[14:17]
	v_mfma_f32_16x16x32_bf16 v[10:13], v[152:155], v[232:235], v[10:13]
	s_setprio 0
	s_setprio 1
	v_mfma_f32_16x16x32_bf16 v[62:65], v[148:151], v[212:215], v[62:65]
	v_mfma_f32_16x16x32_bf16 v[58:61], v[158:161], v[212:215], v[58:61]
	v_mfma_f32_16x16x32_bf16 v[46:49], v[148:151], v[220:223], v[46:49]
	v_mfma_f32_16x16x32_bf16 v[42:45], v[158:161], v[220:223], v[42:45]
	v_mfma_f32_16x16x32_bf16 v[30:33], v[148:151], v[228:231], v[30:33]
	v_mfma_f32_16x16x32_bf16 v[26:29], v[158:161], v[228:231], v[26:29]
	v_mfma_f32_16x16x32_bf16 v[14:17], v[148:151], v[236:239], v[14:17]
	v_mfma_f32_16x16x32_bf16 v[10:13], v[158:161], v[236:239], v[10:13]
	s_setprio 0
	s_setprio 1
	v_mfma_f32_16x16x32_bf16 v[54:57], v[162:165], v[208:211], v[54:57]
	v_mfma_f32_16x16x32_bf16 v[50:53], v[200:203], v[208:211], v[50:53]
	v_mfma_f32_16x16x32_bf16 v[38:41], v[162:165], v[216:219], v[38:41]
	v_mfma_f32_16x16x32_bf16 v[34:37], v[200:203], v[216:219], v[34:37]
	v_mfma_f32_16x16x32_bf16 v[22:25], v[162:165], v[224:227], v[22:25]
	v_mfma_f32_16x16x32_bf16 v[18:21], v[200:203], v[224:227], v[18:21]
	v_mfma_f32_16x16x32_bf16 v[6:9], v[162:165], v[232:235], v[6:9]
	v_mfma_f32_16x16x32_bf16 v[2:5], v[200:203], v[232:235], v[2:5]
	s_setprio 0
	s_setprio 1
	v_mfma_f32_16x16x32_bf16 v[54:57], v[196:199], v[212:215], v[54:57]
	v_mfma_f32_16x16x32_bf16 v[50:53], v[204:207], v[212:215], v[50:53]
	v_mfma_f32_16x16x32_bf16 v[38:41], v[196:199], v[220:223], v[38:41]
	v_mfma_f32_16x16x32_bf16 v[34:37], v[204:207], v[220:223], v[34:37]
	v_mfma_f32_16x16x32_bf16 v[22:25], v[196:199], v[228:231], v[22:25]
	v_mfma_f32_16x16x32_bf16 v[18:21], v[204:207], v[228:231], v[18:21]
	v_mfma_f32_16x16x32_bf16 v[6:9], v[196:199], v[236:239], v[6:9]
	v_mfma_f32_16x16x32_bf16 v[2:5], v[204:207], v[236:239], v[2:5]
	s_setprio 0
	s_barrier
	s_add_i32 s16, s16, 2
	s_add_u32 s18, s18, 0x100
	s_addc_u32 s19, s19, 0
	s_cmp_gt_u32 s16, 5
	s_cbranch_scc0 .LBB0_465
	s_waitcnt vmcnt(0)
	s_cmpk_lt_u32 s1, 0x100
	s_cbranch_scc0 .LBB0_461
	s_barrier
	s_branch .LBB0_461

.LBB0_476:
	s_add_i32 s6, s20, 0x100
	s_and_b64 s[4:5], s[46:47], exec
	s_cselect_b32 s6, 0, s6
	s_cselect_b32 s5, 0, 0
	s_add_u32 s50, s2, s6
	s_addc_u32 s51, s3, s5
	s_add_i32 s4, 0, 0x10000
	s_add_u32 s52, s40, s6
	s_addc_u32 s53, s41, s5
	s_add_i32 s5, 0, 0x14000
	s_add_u32 s56, s42, s20
	s_addc_u32 s57, s43, 0
	s_add_i32 s85, s4, s11
	s_add_i32 m0, s12, 0xc000
	s_add_i32 s86, s12, 0xe000
	s_add_i32 s67, s85, 0x2000
	s_add_u32 s54, s52, 0x20000
	v_add_u32_e32 v142, s4, v140
	s_addc_u32 s55, s53, 0
	s_add_i32 s84, s5, s11
	ds_read_b128 v[146:149], v142
	ds_read_b128 v[150:153], v142 offset:1024
	ds_read_b128 v[158:161], v142 offset:2048
	ds_read_b128 v[162:165], v142 offset:3072
	v_add_u32_e32 v142, s5, v140
	s_add_i32 s70, s84, 0x2000
	s_add_i32 s6, 0, 0x18000
	s_add_i32 s7, 0, 0x1c000
	ds_read_b128 v[196:199], v142
	ds_read_b128 v[200:203], v142 offset:1024
	ds_read_b128 v[204:207], v142 offset:2048
	ds_read_b128 v[208:211], v142 offset:3072
	s_add_u32 s48, s50, 0x10000
	s_addc_u32 s49, s51, 0
	s_add_i32 s66, s6, s11
	s_add_i32 s63, s66, 0x2000
	s_add_u32 s46, s52, 0x20080
	s_addc_u32 s47, s53, 0
	s_add_i32 s65, s7, s11
	s_add_i32 s20, s65, 0x2000
	v_lshl_add_u64 v[142:143], s[56:57], 0, v[26:27]
	v_lshl_add_u64 v[142:143], v[142:143], 0, s[24:25]
	ds_read_b128 v[212:215], v141
	ds_read_b128 v[216:219], v141 offset:1024
	ds_read_b128 v[220:223], v141 offset:2048
	ds_read_b128 v[224:227], v141 offset:3072
	ds_read_b128 v[228:231], v141 offset:4096
	ds_read_b128 v[232:235], v141 offset:5120
	ds_read_b128 v[236:239], v141 offset:6144
	ds_read_b128 v[240:243], v141 offset:7168
	global_load_lds_dwordx4 v[142:143], off
	v_lshl_add_u64 v[142:143], s[56:57], 0, v[28:29]
	v_lshl_add_u64 v[142:143], v[142:143], 0, s[24:25]
	s_mov_b32 m0, s86
	s_nop 0
	global_load_lds_dwordx4 v[142:143], off
	s_waitcnt vmcnt(8)
	s_waitcnt lgkmcnt(0)
	s_barrier
	s_setprio 1
	v_mfma_f32_16x16x32_bf16 v[134:137], v[146:149], v[212:215], v[134:137]
	v_mfma_f32_16x16x32_bf16 v[130:133], v[158:161], v[212:215], v[130:133]
	v_mfma_f32_16x16x32_bf16 v[118:121], v[146:149], v[220:223], v[118:121]
	v_mfma_f32_16x16x32_bf16 v[114:117], v[158:161], v[220:223], v[114:117]
	v_mfma_f32_16x16x32_bf16 v[102:105], v[146:149], v[228:231], v[102:105]
	v_mfma_f32_16x16x32_bf16 v[98:101], v[158:161], v[228:231], v[98:101]
	v_mfma_f32_16x16x32_bf16 v[86:89], v[146:149], v[236:239], v[86:89]
	v_mfma_f32_16x16x32_bf16 v[82:85], v[158:161], v[236:239], v[82:85]
	s_setprio 0
	s_setprio 1
	v_mfma_f32_16x16x32_bf16 v[134:137], v[150:153], v[216:219], v[134:137]
	v_mfma_f32_16x16x32_bf16 v[130:133], v[162:165], v[216:219], v[130:133]
	v_mfma_f32_16x16x32_bf16 v[118:121], v[150:153], v[224:227], v[118:121]
	v_mfma_f32_16x16x32_bf16 v[114:117], v[162:165], v[224:227], v[114:117]
	v_mfma_f32_16x16x32_bf16 v[102:105], v[150:153], v[232:235], v[102:105]
	v_mfma_f32_16x16x32_bf16 v[98:101], v[162:165], v[232:235], v[98:101]
	v_mfma_f32_16x16x32_bf16 v[86:89], v[150:153], v[240:243], v[86:89]
	v_mfma_f32_16x16x32_bf16 v[82:85], v[162:165], v[240:243], v[82:85]
	s_setprio 0
	s_setprio 1
	v_mfma_f32_16x16x32_bf16 v[126:129], v[196:199], v[212:215], v[126:129]
	v_mfma_f32_16x16x32_bf16 v[122:125], v[204:207], v[212:215], v[122:125]
	v_mfma_f32_16x16x32_bf16 v[110:113], v[196:199], v[220:223], v[110:113]
	v_mfma_f32_16x16x32_bf16 v[106:109], v[204:207], v[220:223], v[106:109]
	v_mfma_f32_16x16x32_bf16 v[94:97], v[196:199], v[228:231], v[94:97]
	v_mfma_f32_16x16x32_bf16 v[90:93], v[204:207], v[228:231], v[90:93]
	v_mfma_f32_16x16x32_bf16 v[78:81], v[196:199], v[236:239], v[78:81]
	v_mfma_f32_16x16x32_bf16 v[74:77], v[204:207], v[236:239], v[74:77]
	s_setprio 0
	s_setprio 1
	v_mfma_f32_16x16x32_bf16 v[126:129], v[200:203], v[216:219], v[126:129]
	v_mfma_f32_16x16x32_bf16 v[122:125], v[208:211], v[216:219], v[122:125]
	v_mfma_f32_16x16x32_bf16 v[110:113], v[200:203], v[224:227], v[110:113]
	v_mfma_f32_16x16x32_bf16 v[106:109], v[208:211], v[224:227], v[106:109]
	v_mfma_f32_16x16x32_bf16 v[94:97], v[200:203], v[232:235], v[94:97]
	v_mfma_f32_16x16x32_bf16 v[90:93], v[208:211], v[232:235], v[90:93]
	v_mfma_f32_16x16x32_bf16 v[78:81], v[200:203], v[240:243], v[78:81]
	v_mfma_f32_16x16x32_bf16 v[74:77], v[208:211], v[240:243], v[74:77]
	s_setprio 0
	s_barrier
	s_mov_b32 m0, s85
	v_lshl_add_u64 v[142:143], s[52:53], 0, v[0:1]
	ds_read_b128 v[212:215], v141 offset:16384
	ds_read_b128 v[216:219], v141 offset:17408
	ds_read_b128 v[220:223], v141 offset:18432
	ds_read_b128 v[224:227], v141 offset:19456
	ds_read_b128 v[228:231], v141 offset:20480
	ds_read_b128 v[232:235], v141 offset:21504
	ds_read_b128 v[236:239], v141 offset:22528
	ds_read_b128 v[240:243], v141 offset:23552
	global_load_lds_dwordx4 v[142:143], off
	v_lshl_add_u64 v[154:155], s[52:53], 0, v[38:39]
	s_mov_b32 m0, s67
	v_lshl_add_u64 v[244:245], s[54:55], 0, v[0:1]
	global_load_lds_dwordx4 v[154:155], off
	s_mov_b32 m0, s84
	v_lshl_add_u64 v[246:247], s[50:51], 0, v[28:29]
	global_load_lds_dwordx4 v[244:245], off
	v_lshl_add_u64 v[244:245], s[54:55], 0, v[38:39]
	s_mov_b32 m0, s70
	s_nop 0
	global_load_lds_dwordx4 v[244:245], off
	v_lshl_add_u64 v[244:245], s[50:51], 0, v[26:27]
	s_mov_b32 m0, s12
	s_nop 0
	global_load_lds_dwordx4 v[244:245], off
	s_mov_b32 m0, s13
	s_nop 0
	global_load_lds_dwordx4 v[246:247], off
	s_waitcnt vmcnt(8)
	s_waitcnt lgkmcnt(0)
	s_barrier
	s_setprio 1
	v_mfma_f32_16x16x32_bf16 v[70:73], v[146:149], v[212:215], v[70:73]
	v_mfma_f32_16x16x32_bf16 v[66:69], v[158:161], v[212:215], v[66:69]
	v_mfma_f32_16x16x32_bf16 v[54:57], v[146:149], v[220:223], v[54:57]
	v_mfma_f32_16x16x32_bf16 v[50:53], v[158:161], v[220:223], v[50:53]
	v_mfma_f32_16x16x32_bf16 v[34:37], v[146:149], v[228:231], v[34:37]
	v_mfma_f32_16x16x32_bf16 v[30:33], v[158:161], v[228:231], v[30:33]
	v_mfma_f32_16x16x32_bf16 v[14:17], v[146:149], v[236:239], v[14:17]
	v_mfma_f32_16x16x32_bf16 v[10:13], v[158:161], v[236:239], v[10:13]
	s_setprio 0
	s_setprio 1
	v_mfma_f32_16x16x32_bf16 v[70:73], v[150:153], v[216:219], v[70:73]
	v_mfma_f32_16x16x32_bf16 v[66:69], v[162:165], v[216:219], v[66:69]
	v_mfma_f32_16x16x32_bf16 v[54:57], v[150:153], v[224:227], v[54:57]
	v_mfma_f32_16x16x32_bf16 v[50:53], v[162:165], v[224:227], v[50:53]
	v_mfma_f32_16x16x32_bf16 v[34:37], v[150:153], v[232:235], v[34:37]
	v_mfma_f32_16x16x32_bf16 v[30:33], v[162:165], v[232:235], v[30:33]
	v_mfma_f32_16x16x32_bf16 v[14:17], v[150:153], v[240:243], v[14:17]
	v_mfma_f32_16x16x32_bf16 v[10:13], v[162:165], v[240:243], v[10:13]
	s_setprio 0
	s_setprio 1
	v_mfma_f32_16x16x32_bf16 v[62:65], v[196:199], v[212:215], v[62:65]
	v_mfma_f32_16x16x32_bf16 v[58:61], v[204:207], v[212:215], v[58:61]
	v_mfma_f32_16x16x32_bf16 v[46:49], v[196:199], v[220:223], v[46:49]
	v_mfma_f32_16x16x32_bf16 v[42:45], v[204:207], v[220:223], v[42:45]
	v_mfma_f32_16x16x32_bf16 v[22:25], v[196:199], v[228:231], v[22:25]
	v_mfma_f32_16x16x32_bf16 v[18:21], v[204:207], v[228:231], v[18:21]
	v_mfma_f32_16x16x32_bf16 v[6:9], v[196:199], v[236:239], v[6:9]
	v_mfma_f32_16x16x32_bf16 v[2:5], v[204:207], v[236:239], v[2:5]
	s_setprio 0
	s_setprio 1
	v_mfma_f32_16x16x32_bf16 v[62:65], v[200:203], v[216:219], v[62:65]
	v_mfma_f32_16x16x32_bf16 v[58:61], v[208:211], v[216:219], v[58:61]
	v_mfma_f32_16x16x32_bf16 v[46:49], v[200:203], v[224:227], v[46:49]
	v_mfma_f32_16x16x32_bf16 v[42:45], v[208:211], v[224:227], v[42:45]
	v_mfma_f32_16x16x32_bf16 v[22:25], v[200:203], v[232:235], v[22:25]
	v_mfma_f32_16x16x32_bf16 v[18:21], v[208:211], v[232:235], v[18:21]
	v_mfma_f32_16x16x32_bf16 v[6:9], v[200:203], v[240:243], v[6:9]
	v_mfma_f32_16x16x32_bf16 v[2:5], v[208:211], v[240:243], v[2:5]
	s_setprio 0
	s_barrier
	v_add_u32_e32 v145, s6, v140
	ds_read_b128 v[146:149], v145
	ds_read_b128 v[150:153], v145 offset:1024
	ds_read_b128 v[158:161], v145 offset:2048
	ds_read_b128 v[162:165], v145 offset:3072
	v_add_u32_e32 v145, s7, v140
	ds_read_b128 v[196:199], v145
	ds_read_b128 v[200:203], v145 offset:1024
	ds_read_b128 v[204:207], v145 offset:2048
	ds_read_b128 v[208:211], v145 offset:3072
	s_mov_b32 m0, s16
	v_lshl_add_u64 v[248:249], s[48:49], 0, v[26:27]
	ds_read_b128 v[212:215], v141 offset:32768
	ds_read_b128 v[216:219], v141 offset:33792
	ds_read_b128 v[220:223], v141 offset:34816
	ds_read_b128 v[224:227], v141 offset:35840
	ds_read_b128 v[228:231], v141 offset:36864
	ds_read_b128 v[232:235], v141 offset:37888
	ds_read_b128 v[236:239], v141 offset:38912
	ds_read_b128 v[240:243], v141 offset:39936
	global_load_lds_dwordx4 v[248:249], off
	v_lshl_add_u64 v[248:249], s[48:49], 0, v[28:29]
	s_mov_b32 m0, s17
	s_nop 0
	global_load_lds_dwordx4 v[248:249], off
	s_waitcnt vmcnt(8)
	s_waitcnt lgkmcnt(0)
	s_barrier
	s_setprio 1
	v_mfma_f32_16x16x32_bf16 v[134:137], v[146:149], v[212:215], v[134:137]
	v_mfma_f32_16x16x32_bf16 v[130:133], v[158:161], v[212:215], v[130:133]
	v_mfma_f32_16x16x32_bf16 v[118:121], v[146:149], v[220:223], v[118:121]
	v_mfma_f32_16x16x32_bf16 v[114:117], v[158:161], v[220:223], v[114:117]
	v_mfma_f32_16x16x32_bf16 v[102:105], v[146:149], v[228:231], v[102:105]
	v_mfma_f32_16x16x32_bf16 v[98:101], v[158:161], v[228:231], v[98:101]
	v_mfma_f32_16x16x32_bf16 v[86:89], v[146:149], v[236:239], v[86:89]
	v_mfma_f32_16x16x32_bf16 v[82:85], v[158:161], v[236:239], v[82:85]
	s_setprio 0
	s_setprio 1
	v_mfma_f32_16x16x32_bf16 v[134:137], v[150:153], v[216:219], v[134:137]
	v_mfma_f32_16x16x32_bf16 v[130:133], v[162:165], v[216:219], v[130:133]
	v_mfma_f32_16x16x32_bf16 v[118:121], v[150:153], v[224:227], v[118:121]
	v_mfma_f32_16x16x32_bf16 v[114:117], v[162:165], v[224:227], v[114:117]
	v_mfma_f32_16x16x32_bf16 v[102:105], v[150:153], v[232:235], v[102:105]
	v_mfma_f32_16x16x32_bf16 v[98:101], v[162:165], v[232:235], v[98:101]
	v_mfma_f32_16x16x32_bf16 v[86:89], v[150:153], v[240:243], v[86:89]
	v_mfma_f32_16x16x32_bf16 v[82:85], v[162:165], v[240:243], v[82:85]
	s_setprio 0
	s_setprio 1
	v_mfma_f32_16x16x32_bf16 v[126:129], v[196:199], v[212:215], v[126:129]
	v_mfma_f32_16x16x32_bf16 v[122:125], v[204:207], v[212:215], v[122:125]
	v_mfma_f32_16x16x32_bf16 v[110:113], v[196:199], v[220:223], v[110:113]
	v_mfma_f32_16x16x32_bf16 v[106:109], v[204:207], v[220:223], v[106:109]
	v_mfma_f32_16x16x32_bf16 v[94:97], v[196:199], v[228:231], v[94:97]
	v_mfma_f32_16x16x32_bf16 v[90:93], v[204:207], v[228:231], v[90:93]
	v_mfma_f32_16x16x32_bf16 v[78:81], v[196:199], v[236:239], v[78:81]
	v_mfma_f32_16x16x32_bf16 v[74:77], v[204:207], v[236:239], v[74:77]
	s_setprio 0
	s_setprio 1
	v_mfma_f32_16x16x32_bf16 v[126:129], v[200:203], v[216:219], v[126:129]
	v_mfma_f32_16x16x32_bf16 v[122:125], v[208:211], v[216:219], v[122:125]
	v_mfma_f32_16x16x32_bf16 v[110:113], v[200:203], v[224:227], v[110:113]
	v_mfma_f32_16x16x32_bf16 v[106:109], v[208:211], v[224:227], v[106:109]
	v_mfma_f32_16x16x32_bf16 v[94:97], v[200:203], v[232:235], v[94:97]
	v_mfma_f32_16x16x32_bf16 v[90:93], v[208:211], v[232:235], v[90:93]
	v_mfma_f32_16x16x32_bf16 v[78:81], v[200:203], v[240:243], v[78:81]
	v_mfma_f32_16x16x32_bf16 v[74:77], v[208:211], v[240:243], v[74:77]
	s_setprio 0
	s_barrier
	s_mov_b32 m0, s66
	v_lshl_add_u64 v[142:143], v[142:143], 0, s[24:25]
	ds_read_b128 v[212:215], v141 offset:49152
	ds_read_b128 v[216:219], v141 offset:50176
	ds_read_b128 v[220:223], v141 offset:51200
	ds_read_b128 v[224:227], v141 offset:52224
	ds_read_b128 v[228:231], v141 offset:53248
	ds_read_b128 v[232:235], v141 offset:54272
	ds_read_b128 v[236:239], v141 offset:55296
	ds_read_b128 v[240:243], v141 offset:56320
	global_load_lds_dwordx4 v[142:143], off
	v_lshl_add_u64 v[142:143], v[154:155], 0, s[24:25]
	s_mov_b32 m0, s63
	s_nop 0
	global_load_lds_dwordx4 v[142:143], off
	v_lshl_add_u64 v[142:143], s[46:47], 0, v[0:1]
	s_mov_b32 m0, s65
	s_nop 0
	global_load_lds_dwordx4 v[142:143], off
	v_lshl_add_u64 v[142:143], s[46:47], 0, v[38:39]
	s_mov_b32 m0, s20
	s_nop 0
	global_load_lds_dwordx4 v[142:143], off
	v_lshl_add_u64 v[142:143], v[244:245], 0, s[24:25]
	s_mov_b32 m0, s19
	s_nop 0
	global_load_lds_dwordx4 v[142:143], off
	v_lshl_add_u64 v[142:143], v[246:247], 0, s[24:25]
	s_mov_b32 m0, s62
	s_nop 0
	global_load_lds_dwordx4 v[142:143], off
	s_waitcnt vmcnt(8)
	s_waitcnt lgkmcnt(0)
	s_barrier
	s_setprio 1
	v_mfma_f32_16x16x32_bf16 v[70:73], v[146:149], v[212:215], v[70:73]
	v_mfma_f32_16x16x32_bf16 v[66:69], v[158:161], v[212:215], v[66:69]
	v_mfma_f32_16x16x32_bf16 v[54:57], v[146:149], v[220:223], v[54:57]
	v_mfma_f32_16x16x32_bf16 v[50:53], v[158:161], v[220:223], v[50:53]
	v_mfma_f32_16x16x32_bf16 v[34:37], v[146:149], v[228:231], v[34:37]
	v_mfma_f32_16x16x32_bf16 v[30:33], v[158:161], v[228:231], v[30:33]
	v_mfma_f32_16x16x32_bf16 v[14:17], v[146:149], v[236:239], v[14:17]
	v_mfma_f32_16x16x32_bf16 v[10:13], v[158:161], v[236:239], v[10:13]
	s_setprio 0
	s_setprio 1
	v_mfma_f32_16x16x32_bf16 v[70:73], v[150:153], v[216:219], v[70:73]
	v_mfma_f32_16x16x32_bf16 v[66:69], v[162:165], v[216:219], v[66:69]
	v_mfma_f32_16x16x32_bf16 v[54:57], v[150:153], v[224:227], v[54:57]
	v_mfma_f32_16x16x32_bf16 v[50:53], v[162:165], v[224:227], v[50:53]
	v_mfma_f32_16x16x32_bf16 v[34:37], v[150:153], v[232:235], v[34:37]
	v_mfma_f32_16x16x32_bf16 v[30:33], v[162:165], v[232:235], v[30:33]
	v_mfma_f32_16x16x32_bf16 v[14:17], v[150:153], v[240:243], v[14:17]
	v_mfma_f32_16x16x32_bf16 v[10:13], v[162:165], v[240:243], v[10:13]
	s_setprio 0
	s_setprio 1
	v_mfma_f32_16x16x32_bf16 v[62:65], v[196:199], v[212:215], v[62:65]
	v_mfma_f32_16x16x32_bf16 v[58:61], v[204:207], v[212:215], v[58:61]
	v_mfma_f32_16x16x32_bf16 v[46:49], v[196:199], v[220:223], v[46:49]
	v_mfma_f32_16x16x32_bf16 v[42:45], v[204:207], v[220:223], v[42:45]
	v_mfma_f32_16x16x32_bf16 v[22:25], v[196:199], v[228:231], v[22:25]
	v_mfma_f32_16x16x32_bf16 v[18:21], v[204:207], v[228:231], v[18:21]
	v_mfma_f32_16x16x32_bf16 v[6:9], v[196:199], v[236:239], v[6:9]
	v_mfma_f32_16x16x32_bf16 v[2:5], v[204:207], v[236:239], v[2:5]
	s_setprio 0
	s_setprio 1
	v_mfma_f32_16x16x32_bf16 v[62:65], v[200:203], v[216:219], v[62:65]
	v_mfma_f32_16x16x32_bf16 v[58:61], v[208:211], v[216:219], v[58:61]
	v_mfma_f32_16x16x32_bf16 v[46:49], v[200:203], v[224:227], v[46:49]
	v_mfma_f32_16x16x32_bf16 v[42:45], v[208:211], v[224:227], v[42:45]
	v_mfma_f32_16x16x32_bf16 v[22:25], v[200:203], v[232:235], v[22:25]
	v_mfma_f32_16x16x32_bf16 v[18:21], v[208:211], v[232:235], v[18:21]
	v_mfma_f32_16x16x32_bf16 v[6:9], v[200:203], v[240:243], v[6:9]
	v_mfma_f32_16x16x32_bf16 v[2:5], v[208:211], v[240:243], v[2:5]
	s_setprio 0
	s_barrier
	s_andn2_b64 vcc, exec, s[44:45]
	s_mov_b64 s[46:47], -1
	s_mov_b64 s[44:45], 0
	s_movk_i32 s20, 0x100
	s_cbranch_vccz .LBB0_476
	s_waitcnt vmcnt(0)
	s_cmpk_lt_u32 s10, 0x100
	s_cbranch_scc0 .LBB0_479
	s_barrier

.LBB0_482:
	s_add_i32 s48, s20, 0x100
	s_and_b64 s[46:47], s[46:47], exec
	s_cselect_b32 s47, 0, s48
	s_cselect_b32 s46, 0, 0
	s_add_u32 s50, s2, s47
	s_addc_u32 s51, s3, s46
	s_add_u32 s52, s40, s47
	s_addc_u32 s53, s41, s46
	s_add_u32 s66, s42, s20
	s_addc_u32 s67, s43, 0
	s_add_i32 s65, s4, s10
	s_add_i32 m0, s11, 0xc000
	s_add_i32 s63, s11, 0xe000
	s_add_i32 s70, s65, 0x2000
	s_add_u32 s54, s52, 0x20200
	v_add_u32_e32 v142, s4, v40
	s_addc_u32 s55, s53, 0
	s_add_i32 s82, s5, s10
	ds_read_b128 v[138:141], v142
	ds_read_b128 v[146:149], v142 offset:1024
	ds_read_b128 v[150:153], v142 offset:2048
	ds_read_b128 v[158:161], v142 offset:3072
	v_add_u32_e32 v142, s5, v40
	s_add_i32 s83, s82, 0x2000
	ds_read_b128 v[162:165], v142
	ds_read_b128 v[196:199], v142 offset:1024
	ds_read_b128 v[200:203], v142 offset:2048
	ds_read_b128 v[204:207], v142 offset:3072
	s_add_u32 s48, s50, 0x10000
	s_addc_u32 s49, s51, 0
	s_add_i32 s62, s6, s10
	s_add_i32 s56, s62, 0x2000
	s_add_u32 s46, s52, 0x20280
	s_addc_u32 s47, s53, 0
	s_add_i32 s57, s7, s10
	s_add_i32 s20, s57, 0x2000
	v_lshl_add_u64 v[142:143], s[66:67], 0, v[26:27]
	v_lshl_add_u64 v[142:143], v[142:143], 0, s[24:25]
	ds_read_b128 v[208:211], v41
	ds_read_b128 v[212:215], v41 offset:1024
	ds_read_b128 v[216:219], v41 offset:2048
	ds_read_b128 v[220:223], v41 offset:3072
	ds_read_b128 v[224:227], v41 offset:4096
	ds_read_b128 v[228:231], v41 offset:5120
	ds_read_b128 v[232:235], v41 offset:6144
	ds_read_b128 v[236:239], v41 offset:7168
	global_load_lds_dwordx4 v[142:143], off
	v_lshl_add_u64 v[142:143], s[66:67], 0, v[28:29]
	v_lshl_add_u64 v[142:143], v[142:143], 0, s[24:25]
	s_mov_b32 m0, s63
	s_nop 0
	global_load_lds_dwordx4 v[142:143], off
	s_waitcnt vmcnt(8)
	s_waitcnt lgkmcnt(0)
	s_barrier
	s_setprio 1
	v_mfma_f32_16x16x32_bf16 v[134:137], v[138:141], v[208:211], v[134:137]
	v_mfma_f32_16x16x32_bf16 v[130:133], v[150:153], v[208:211], v[130:133]
	v_mfma_f32_16x16x32_bf16 v[118:121], v[138:141], v[216:219], v[118:121]
	v_mfma_f32_16x16x32_bf16 v[114:117], v[150:153], v[216:219], v[114:117]
	v_mfma_f32_16x16x32_bf16 v[102:105], v[138:141], v[224:227], v[102:105]
	v_mfma_f32_16x16x32_bf16 v[98:101], v[150:153], v[224:227], v[98:101]
	v_mfma_f32_16x16x32_bf16 v[86:89], v[138:141], v[232:235], v[86:89]
	v_mfma_f32_16x16x32_bf16 v[82:85], v[150:153], v[232:235], v[82:85]
	s_setprio 0
	s_setprio 1
	v_mfma_f32_16x16x32_bf16 v[134:137], v[146:149], v[212:215], v[134:137]
	v_mfma_f32_16x16x32_bf16 v[130:133], v[158:161], v[212:215], v[130:133]
	v_mfma_f32_16x16x32_bf16 v[118:121], v[146:149], v[220:223], v[118:121]
	v_mfma_f32_16x16x32_bf16 v[114:117], v[158:161], v[220:223], v[114:117]
	v_mfma_f32_16x16x32_bf16 v[102:105], v[146:149], v[228:231], v[102:105]
	v_mfma_f32_16x16x32_bf16 v[98:101], v[158:161], v[228:231], v[98:101]
	v_mfma_f32_16x16x32_bf16 v[86:89], v[146:149], v[236:239], v[86:89]
	v_mfma_f32_16x16x32_bf16 v[82:85], v[158:161], v[236:239], v[82:85]
	s_setprio 0
	s_setprio 1
	v_mfma_f32_16x16x32_bf16 v[126:129], v[162:165], v[208:211], v[126:129]
	v_mfma_f32_16x16x32_bf16 v[122:125], v[200:203], v[208:211], v[122:125]
	v_mfma_f32_16x16x32_bf16 v[110:113], v[162:165], v[216:219], v[110:113]
	v_mfma_f32_16x16x32_bf16 v[106:109], v[200:203], v[216:219], v[106:109]
	v_mfma_f32_16x16x32_bf16 v[94:97], v[162:165], v[224:227], v[94:97]
	v_mfma_f32_16x16x32_bf16 v[90:93], v[200:203], v[224:227], v[90:93]
	v_mfma_f32_16x16x32_bf16 v[78:81], v[162:165], v[232:235], v[78:81]
	v_mfma_f32_16x16x32_bf16 v[74:77], v[200:203], v[232:235], v[74:77]
	s_setprio 0
	s_setprio 1
	v_mfma_f32_16x16x32_bf16 v[126:129], v[196:199], v[212:215], v[126:129]
	v_mfma_f32_16x16x32_bf16 v[122:125], v[204:207], v[212:215], v[122:125]
	v_mfma_f32_16x16x32_bf16 v[110:113], v[196:199], v[220:223], v[110:113]
	v_mfma_f32_16x16x32_bf16 v[106:109], v[204:207], v[220:223], v[106:109]
	v_mfma_f32_16x16x32_bf16 v[94:97], v[196:199], v[228:231], v[94:97]
	v_mfma_f32_16x16x32_bf16 v[90:93], v[204:207], v[228:231], v[90:93]
	v_mfma_f32_16x16x32_bf16 v[78:81], v[196:199], v[236:239], v[78:81]
	v_mfma_f32_16x16x32_bf16 v[74:77], v[204:207], v[236:239], v[74:77]
	s_setprio 0
	s_barrier
	v_lshl_add_u64 v[142:143], s[52:53], 0, v[0:1]
	s_mov_b32 m0, s65
	v_lshl_add_u64 v[154:155], v[142:143], 0, s[84:85]
	ds_read_b128 v[208:211], v41 offset:16384
	ds_read_b128 v[212:215], v41 offset:17408
	ds_read_b128 v[216:219], v41 offset:18432
	ds_read_b128 v[220:223], v41 offset:19456
	ds_read_b128 v[224:227], v41 offset:20480
	ds_read_b128 v[228:231], v41 offset:21504
	ds_read_b128 v[232:235], v41 offset:22528
	ds_read_b128 v[236:239], v41 offset:23552
	global_load_lds_dwordx4 v[154:155], off
	v_lshl_add_u64 v[154:155], s[52:53], 0, v[38:39]
	v_lshl_add_u64 v[240:241], v[154:155], 0, s[84:85]
	s_mov_b32 m0, s70
	v_lshl_add_u64 v[242:243], s[50:51], 0, v[28:29]
	global_load_lds_dwordx4 v[240:241], off
	v_lshl_add_u64 v[240:241], s[54:55], 0, v[0:1]
	s_mov_b32 m0, s82
	s_nop 0
	global_load_lds_dwordx4 v[240:241], off
	v_lshl_add_u64 v[240:241], s[54:55], 0, v[38:39]
	s_mov_b32 m0, s83
	s_nop 0
	global_load_lds_dwordx4 v[240:241], off
	v_lshl_add_u64 v[240:241], s[50:51], 0, v[26:27]
	s_mov_b32 m0, s11
	s_nop 0
	global_load_lds_dwordx4 v[240:241], off
	s_mov_b32 m0, s12
	s_nop 0
	global_load_lds_dwordx4 v[242:243], off
	s_waitcnt vmcnt(8)
	s_waitcnt lgkmcnt(0)
	s_barrier
	s_setprio 1
	v_mfma_f32_16x16x32_bf16 v[70:73], v[138:141], v[208:211], v[70:73]
	v_mfma_f32_16x16x32_bf16 v[66:69], v[150:153], v[208:211], v[66:69]
	v_mfma_f32_16x16x32_bf16 v[54:57], v[138:141], v[216:219], v[54:57]
	v_mfma_f32_16x16x32_bf16 v[50:53], v[150:153], v[216:219], v[50:53]
	v_mfma_f32_16x16x32_bf16 v[34:37], v[138:141], v[224:227], v[34:37]
	v_mfma_f32_16x16x32_bf16 v[30:33], v[150:153], v[224:227], v[30:33]
	v_mfma_f32_16x16x32_bf16 v[14:17], v[138:141], v[232:235], v[14:17]
	v_mfma_f32_16x16x32_bf16 v[10:13], v[150:153], v[232:235], v[10:13]
	s_setprio 0
	s_setprio 1
	v_mfma_f32_16x16x32_bf16 v[70:73], v[146:149], v[212:215], v[70:73]
	v_mfma_f32_16x16x32_bf16 v[66:69], v[158:161], v[212:215], v[66:69]
	v_mfma_f32_16x16x32_bf16 v[54:57], v[146:149], v[220:223], v[54:57]
	v_mfma_f32_16x16x32_bf16 v[50:53], v[158:161], v[220:223], v[50:53]
	v_mfma_f32_16x16x32_bf16 v[34:37], v[146:149], v[228:231], v[34:37]
	v_mfma_f32_16x16x32_bf16 v[30:33], v[158:161], v[228:231], v[30:33]
	v_mfma_f32_16x16x32_bf16 v[14:17], v[146:149], v[236:239], v[14:17]
	v_mfma_f32_16x16x32_bf16 v[10:13], v[158:161], v[236:239], v[10:13]
	s_setprio 0
	s_setprio 1
	v_mfma_f32_16x16x32_bf16 v[62:65], v[162:165], v[208:211], v[62:65]
	v_mfma_f32_16x16x32_bf16 v[58:61], v[200:203], v[208:211], v[58:61]
	v_mfma_f32_16x16x32_bf16 v[46:49], v[162:165], v[216:219], v[46:49]
	v_mfma_f32_16x16x32_bf16 v[42:45], v[200:203], v[216:219], v[42:45]
	v_mfma_f32_16x16x32_bf16 v[22:25], v[162:165], v[224:227], v[22:25]
	v_mfma_f32_16x16x32_bf16 v[18:21], v[200:203], v[224:227], v[18:21]
	v_mfma_f32_16x16x32_bf16 v[6:9], v[162:165], v[232:235], v[6:9]
	v_mfma_f32_16x16x32_bf16 v[2:5], v[200:203], v[232:235], v[2:5]
	s_setprio 0
	s_setprio 1
	v_mfma_f32_16x16x32_bf16 v[62:65], v[196:199], v[212:215], v[62:65]
	v_mfma_f32_16x16x32_bf16 v[58:61], v[204:207], v[212:215], v[58:61]
	v_mfma_f32_16x16x32_bf16 v[46:49], v[196:199], v[220:223], v[46:49]
	v_mfma_f32_16x16x32_bf16 v[42:45], v[204:207], v[220:223], v[42:45]
	v_mfma_f32_16x16x32_bf16 v[22:25], v[196:199], v[228:231], v[22:25]
	v_mfma_f32_16x16x32_bf16 v[18:21], v[204:207], v[228:231], v[18:21]
	v_mfma_f32_16x16x32_bf16 v[6:9], v[196:199], v[236:239], v[6:9]
	v_mfma_f32_16x16x32_bf16 v[2:5], v[204:207], v[236:239], v[2:5]
	s_setprio 0
	s_barrier
	v_add_u32_e32 v145, s6, v40
	ds_read_b128 v[138:141], v145
	ds_read_b128 v[146:149], v145 offset:1024
	ds_read_b128 v[150:153], v145 offset:2048
	ds_read_b128 v[158:161], v145 offset:3072
	v_add_u32_e32 v145, s7, v40
	ds_read_b128 v[162:165], v145
	ds_read_b128 v[196:199], v145 offset:1024
	ds_read_b128 v[200:203], v145 offset:2048
	ds_read_b128 v[204:207], v145 offset:3072
	s_mov_b32 m0, s13
	v_lshl_add_u64 v[244:245], s[48:49], 0, v[26:27]
	ds_read_b128 v[208:211], v41 offset:32768
	ds_read_b128 v[212:215], v41 offset:33792
	ds_read_b128 v[216:219], v41 offset:34816
	ds_read_b128 v[220:223], v41 offset:35840
	ds_read_b128 v[224:227], v41 offset:36864
	ds_read_b128 v[228:231], v41 offset:37888
	ds_read_b128 v[232:235], v41 offset:38912
	ds_read_b128 v[236:239], v41 offset:39936
	global_load_lds_dwordx4 v[244:245], off
	v_lshl_add_u64 v[244:245], s[48:49], 0, v[28:29]
	s_mov_b32 m0, s16
	s_mov_b64 s[48:49], 0x280
	global_load_lds_dwordx4 v[244:245], off
	s_waitcnt vmcnt(8)
	s_waitcnt lgkmcnt(0)
	s_barrier
	s_setprio 1
	v_mfma_f32_16x16x32_bf16 v[134:137], v[138:141], v[208:211], v[134:137]
	v_mfma_f32_16x16x32_bf16 v[130:133], v[150:153], v[208:211], v[130:133]
	v_mfma_f32_16x16x32_bf16 v[118:121], v[138:141], v[216:219], v[118:121]
	v_mfma_f32_16x16x32_bf16 v[114:117], v[150:153], v[216:219], v[114:117]
	v_mfma_f32_16x16x32_bf16 v[102:105], v[138:141], v[224:227], v[102:105]
	v_mfma_f32_16x16x32_bf16 v[98:101], v[150:153], v[224:227], v[98:101]
	v_mfma_f32_16x16x32_bf16 v[86:89], v[138:141], v[232:235], v[86:89]
	v_mfma_f32_16x16x32_bf16 v[82:85], v[150:153], v[232:235], v[82:85]
	s_setprio 0
	s_setprio 1
	v_mfma_f32_16x16x32_bf16 v[134:137], v[146:149], v[212:215], v[134:137]
	v_mfma_f32_16x16x32_bf16 v[130:133], v[158:161], v[212:215], v[130:133]
	v_mfma_f32_16x16x32_bf16 v[118:121], v[146:149], v[220:223], v[118:121]
	v_mfma_f32_16x16x32_bf16 v[114:117], v[158:161], v[220:223], v[114:117]
	v_mfma_f32_16x16x32_bf16 v[102:105], v[146:149], v[228:231], v[102:105]
	v_mfma_f32_16x16x32_bf16 v[98:101], v[158:161], v[228:231], v[98:101]
	v_mfma_f32_16x16x32_bf16 v[86:89], v[146:149], v[236:239], v[86:89]
	v_mfma_f32_16x16x32_bf16 v[82:85], v[158:161], v[236:239], v[82:85]
	s_setprio 0
	s_setprio 1
	v_mfma_f32_16x16x32_bf16 v[126:129], v[162:165], v[208:211], v[126:129]
	v_mfma_f32_16x16x32_bf16 v[122:125], v[200:203], v[208:211], v[122:125]
	v_mfma_f32_16x16x32_bf16 v[110:113], v[162:165], v[216:219], v[110:113]
	v_mfma_f32_16x16x32_bf16 v[106:109], v[200:203], v[216:219], v[106:109]
	v_mfma_f32_16x16x32_bf16 v[94:97], v[162:165], v[224:227], v[94:97]
	v_mfma_f32_16x16x32_bf16 v[90:93], v[200:203], v[224:227], v[90:93]
	v_mfma_f32_16x16x32_bf16 v[78:81], v[162:165], v[232:235], v[78:81]
	v_mfma_f32_16x16x32_bf16 v[74:77], v[200:203], v[232:235], v[74:77]
	s_setprio 0
	s_setprio 1
	v_mfma_f32_16x16x32_bf16 v[126:129], v[196:199], v[212:215], v[126:129]
	v_mfma_f32_16x16x32_bf16 v[122:125], v[204:207], v[212:215], v[122:125]
	v_mfma_f32_16x16x32_bf16 v[110:113], v[196:199], v[220:223], v[110:113]
	v_mfma_f32_16x16x32_bf16 v[106:109], v[204:207], v[220:223], v[106:109]
	v_mfma_f32_16x16x32_bf16 v[94:97], v[196:199], v[228:231], v[94:97]
	v_mfma_f32_16x16x32_bf16 v[90:93], v[204:207], v[228:231], v[90:93]
	v_mfma_f32_16x16x32_bf16 v[78:81], v[196:199], v[236:239], v[78:81]
	v_mfma_f32_16x16x32_bf16 v[74:77], v[204:207], v[236:239], v[74:77]
	s_setprio 0
	s_barrier
	s_mov_b32 m0, s62
	v_lshl_add_u64 v[142:143], v[142:143], 0, s[48:49]
	ds_read_b128 v[208:211], v41 offset:49152
	ds_read_b128 v[212:215], v41 offset:50176
	ds_read_b128 v[216:219], v41 offset:51200
	ds_read_b128 v[220:223], v41 offset:52224
	ds_read_b128 v[224:227], v41 offset:53248
	ds_read_b128 v[228:231], v41 offset:54272
	ds_read_b128 v[232:235], v41 offset:55296
	ds_read_b128 v[236:239], v41 offset:56320
	global_load_lds_dwordx4 v[142:143], off
	v_lshl_add_u64 v[142:143], v[154:155], 0, s[48:49]
	s_mov_b32 m0, s56
	s_nop 0
	global_load_lds_dwordx4 v[142:143], off
	v_lshl_add_u64 v[142:143], s[46:47], 0, v[0:1]
	s_mov_b32 m0, s57
	s_nop 0
	global_load_lds_dwordx4 v[142:143], off
	v_lshl_add_u64 v[142:143], s[46:47], 0, v[38:39]
	s_mov_b32 m0, s20
	s_nop 0
	global_load_lds_dwordx4 v[142:143], off
	v_lshl_add_u64 v[142:143], v[240:241], 0, s[24:25]
	s_mov_b32 m0, s17
	s_nop 0
	global_load_lds_dwordx4 v[142:143], off
	v_lshl_add_u64 v[142:143], v[242:243], 0, s[24:25]
	s_mov_b32 m0, s19
	s_nop 0
	global_load_lds_dwordx4 v[142:143], off
	s_waitcnt vmcnt(8)
	s_waitcnt lgkmcnt(0)
	s_barrier
	s_setprio 1
	v_mfma_f32_16x16x32_bf16 v[70:73], v[138:141], v[208:211], v[70:73]
	v_mfma_f32_16x16x32_bf16 v[66:69], v[150:153], v[208:211], v[66:69]
	v_mfma_f32_16x16x32_bf16 v[54:57], v[138:141], v[216:219], v[54:57]
	v_mfma_f32_16x16x32_bf16 v[50:53], v[150:153], v[216:219], v[50:53]
	v_mfma_f32_16x16x32_bf16 v[34:37], v[138:141], v[224:227], v[34:37]
	v_mfma_f32_16x16x32_bf16 v[30:33], v[150:153], v[224:227], v[30:33]
	v_mfma_f32_16x16x32_bf16 v[14:17], v[138:141], v[232:235], v[14:17]
	v_mfma_f32_16x16x32_bf16 v[10:13], v[150:153], v[232:235], v[10:13]
	s_setprio 0
	s_setprio 1
	v_mfma_f32_16x16x32_bf16 v[70:73], v[146:149], v[212:215], v[70:73]
	v_mfma_f32_16x16x32_bf16 v[66:69], v[158:161], v[212:215], v[66:69]
	v_mfma_f32_16x16x32_bf16 v[54:57], v[146:149], v[220:223], v[54:57]
	v_mfma_f32_16x16x32_bf16 v[50:53], v[158:161], v[220:223], v[50:53]
	v_mfma_f32_16x16x32_bf16 v[34:37], v[146:149], v[228:231], v[34:37]
	v_mfma_f32_16x16x32_bf16 v[30:33], v[158:161], v[228:231], v[30:33]
	v_mfma_f32_16x16x32_bf16 v[14:17], v[146:149], v[236:239], v[14:17]
	v_mfma_f32_16x16x32_bf16 v[10:13], v[158:161], v[236:239], v[10:13]
	s_setprio 0
	s_setprio 1
	v_mfma_f32_16x16x32_bf16 v[62:65], v[162:165], v[208:211], v[62:65]
	v_mfma_f32_16x16x32_bf16 v[58:61], v[200:203], v[208:211], v[58:61]
	v_mfma_f32_16x16x32_bf16 v[46:49], v[162:165], v[216:219], v[46:49]
	v_mfma_f32_16x16x32_bf16 v[42:45], v[200:203], v[216:219], v[42:45]
	v_mfma_f32_16x16x32_bf16 v[22:25], v[162:165], v[224:227], v[22:25]
	v_mfma_f32_16x16x32_bf16 v[18:21], v[200:203], v[224:227], v[18:21]
	v_mfma_f32_16x16x32_bf16 v[6:9], v[162:165], v[232:235], v[6:9]
	v_mfma_f32_16x16x32_bf16 v[2:5], v[200:203], v[232:235], v[2:5]
	s_setprio 0
	s_setprio 1
	v_mfma_f32_16x16x32_bf16 v[62:65], v[196:199], v[212:215], v[62:65]
	v_mfma_f32_16x16x32_bf16 v[58:61], v[204:207], v[212:215], v[58:61]
	v_mfma_f32_16x16x32_bf16 v[46:49], v[196:199], v[220:223], v[46:49]
	v_mfma_f32_16x16x32_bf16 v[42:45], v[204:207], v[220:223], v[42:45]
	v_mfma_f32_16x16x32_bf16 v[22:25], v[196:199], v[228:231], v[22:25]
	v_mfma_f32_16x16x32_bf16 v[18:21], v[204:207], v[228:231], v[18:21]
	v_mfma_f32_16x16x32_bf16 v[6:9], v[196:199], v[236:239], v[6:9]
	v_mfma_f32_16x16x32_bf16 v[2:5], v[204:207], v[236:239], v[2:5]
	s_setprio 0
	s_barrier
	s_andn2_b64 vcc, exec, s[44:45]
	s_mov_b64 s[46:47], -1
	s_mov_b64 s[44:45], 0
	s_movk_i32 s20, 0x100
	s_cbranch_vccz .LBB0_482
	s_waitcnt vmcnt(0)
	s_cmpk_lt_u32 s9, 0x100
	s_movk_i32 s83, 0x2000
	s_movk_i32 s86, 0x1fff
	s_cbranch_scc0 .LBB0_485
	s_barrier

.LBB0_1254:
	s_add_i32 s44, s20, 0x100
	s_and_b64 s[42:43], s[42:43], exec
	s_cselect_b32 s43, 0, s44
	s_cselect_b32 s42, 0, 0
	s_add_u32 s46, s2, s43
	s_addc_u32 s47, s3, s42
	s_add_i32 s70, 0, 0x10000
	s_add_u32 s52, s8, s43
	s_addc_u32 s53, s9, s42
	s_add_i32 s43, 0, 0x14000
	s_add_u32 s56, s18, s20
	s_addc_u32 s57, s19, 0
	s_add_i32 s67, s70, s10
	s_add_i32 m0, s11, 0xc000
	s_add_i32 s82, s11, 0xe000
	s_add_i32 s63, s67, 0x2000
	v_add_u32_e32 v139, s70, v137
	s_add_u32 s54, s52, 0x10000
	ds_read_b128 v[140:143], v139
	ds_read_b128 v[144:147], v139 offset:1024
	ds_read_b128 v[148:151], v139 offset:2048
	ds_read_b128 v[152:155], v139 offset:3072
	v_add_u32_e32 v139, s43, v137
	s_addc_u32 s55, s53, 0
	s_add_i32 s66, s43, s10
	ds_read_b128 v[158:161], v139
	ds_read_b128 v[162:165], v139 offset:1024
	ds_read_b128 v[196:199], v139 offset:2048
	ds_read_b128 v[200:203], v139 offset:3072
	s_add_i32 s65, s66, 0x2000
	s_add_i32 s62, 0, 0x18000
	s_add_i32 s59, 0, 0x1c000
	s_add_u32 s44, s46, 0x10000
	s_addc_u32 s45, s47, 0
	s_add_i32 s58, s62, s10
	s_add_i32 s20, s58, 0x2000
	s_add_u32 s42, s52, 0x10080
	s_addc_u32 s43, s53, 0
	s_add_i32 s84, s59, s10
	s_add_i32 s70, s84, 0x2000
	v_lshl_add_u64 v[236:237], s[56:57], 0, v[130:131]
	v_lshl_add_u64 v[236:237], v[236:237], 0, s[24:25]
	ds_read_b128 v[204:207], v138
	ds_read_b128 v[208:211], v138 offset:1024
	ds_read_b128 v[212:215], v138 offset:2048
	ds_read_b128 v[216:219], v138 offset:3072
	ds_read_b128 v[220:223], v138 offset:4096
	ds_read_b128 v[224:227], v138 offset:5120
	ds_read_b128 v[228:231], v138 offset:6144
	ds_read_b128 v[232:235], v138 offset:7168
	global_load_lds_dwordx4 v[236:237], off
	v_lshl_add_u64 v[236:237], s[56:57], 0, v[132:133]
	v_lshl_add_u64 v[236:237], v[236:237], 0, s[24:25]
	s_mov_b32 m0, s82
	s_nop 0
	global_load_lds_dwordx4 v[236:237], off
	s_waitcnt vmcnt(8)
	s_waitcnt lgkmcnt(0)
	s_barrier
	s_setprio 1
	v_mfma_f32_16x16x32_bf16 v[126:129], v[140:143], v[204:207], v[126:129]
	v_mfma_f32_16x16x32_bf16 v[122:125], v[148:151], v[204:207], v[122:125]
	v_mfma_f32_16x16x32_bf16 v[118:121], v[140:143], v[212:215], v[118:121]
	v_mfma_f32_16x16x32_bf16 v[114:117], v[148:151], v[212:215], v[114:117]
	v_mfma_f32_16x16x32_bf16 v[102:105], v[140:143], v[220:223], v[102:105]
	v_mfma_f32_16x16x32_bf16 v[98:101], v[148:151], v[220:223], v[98:101]
	v_mfma_f32_16x16x32_bf16 v[86:89], v[140:143], v[228:231], v[86:89]
	v_mfma_f32_16x16x32_bf16 v[82:85], v[148:151], v[228:231], v[82:85]
	s_setprio 0
	s_setprio 1
	v_mfma_f32_16x16x32_bf16 v[126:129], v[144:147], v[208:211], v[126:129]
	v_mfma_f32_16x16x32_bf16 v[122:125], v[152:155], v[208:211], v[122:125]
	v_mfma_f32_16x16x32_bf16 v[118:121], v[144:147], v[216:219], v[118:121]
	v_mfma_f32_16x16x32_bf16 v[114:117], v[152:155], v[216:219], v[114:117]
	v_mfma_f32_16x16x32_bf16 v[102:105], v[144:147], v[224:227], v[102:105]
	v_mfma_f32_16x16x32_bf16 v[98:101], v[152:155], v[224:227], v[98:101]
	v_mfma_f32_16x16x32_bf16 v[86:89], v[144:147], v[232:235], v[86:89]
	v_mfma_f32_16x16x32_bf16 v[82:85], v[152:155], v[232:235], v[82:85]
	s_setprio 0
	s_setprio 1
	v_mfma_f32_16x16x32_bf16 v[110:113], v[158:161], v[204:207], v[110:113]
	v_mfma_f32_16x16x32_bf16 v[106:109], v[196:199], v[204:207], v[106:109]
	v_mfma_f32_16x16x32_bf16 v[94:97], v[158:161], v[212:215], v[94:97]
	v_mfma_f32_16x16x32_bf16 v[90:93], v[196:199], v[212:215], v[90:93]
	v_mfma_f32_16x16x32_bf16 v[78:81], v[158:161], v[220:223], v[78:81]
	v_mfma_f32_16x16x32_bf16 v[74:77], v[196:199], v[220:223], v[74:77]
	v_mfma_f32_16x16x32_bf16 v[70:73], v[158:161], v[228:231], v[70:73]
	v_mfma_f32_16x16x32_bf16 v[66:69], v[196:199], v[228:231], v[66:69]
	s_setprio 0
	s_setprio 1
	v_mfma_f32_16x16x32_bf16 v[110:113], v[162:165], v[208:211], v[110:113]
	v_mfma_f32_16x16x32_bf16 v[106:109], v[200:203], v[208:211], v[106:109]
	v_mfma_f32_16x16x32_bf16 v[94:97], v[162:165], v[216:219], v[94:97]
	v_mfma_f32_16x16x32_bf16 v[90:93], v[200:203], v[216:219], v[90:93]
	v_mfma_f32_16x16x32_bf16 v[78:81], v[162:165], v[224:227], v[78:81]
	v_mfma_f32_16x16x32_bf16 v[74:77], v[200:203], v[224:227], v[74:77]
	v_mfma_f32_16x16x32_bf16 v[70:73], v[162:165], v[232:235], v[70:73]
	v_mfma_f32_16x16x32_bf16 v[66:69], v[200:203], v[232:235], v[66:69]
	s_setprio 0
	s_barrier
	s_mov_b32 m0, s67
	v_lshl_add_u64 v[236:237], s[52:53], 0, v[0:1]
	ds_read_b128 v[204:207], v138 offset:16384
	ds_read_b128 v[208:211], v138 offset:17408
	ds_read_b128 v[212:215], v138 offset:18432
	ds_read_b128 v[216:219], v138 offset:19456
	ds_read_b128 v[220:223], v138 offset:20480
	ds_read_b128 v[224:227], v138 offset:21504
	ds_read_b128 v[228:231], v138 offset:22528
	ds_read_b128 v[232:235], v138 offset:23552
	global_load_lds_dwordx4 v[236:237], off
	v_lshl_add_u64 v[238:239], s[52:53], 0, v[134:135]
	s_mov_b32 m0, s63
	v_lshl_add_u64 v[240:241], s[54:55], 0, v[0:1]
	global_load_lds_dwordx4 v[238:239], off
	s_mov_b32 m0, s66
	v_lshl_add_u64 v[242:243], s[46:47], 0, v[132:133]
	global_load_lds_dwordx4 v[240:241], off
	v_lshl_add_u64 v[240:241], s[54:55], 0, v[134:135]
	s_mov_b32 m0, s65
	s_nop 0
	global_load_lds_dwordx4 v[240:241], off
	v_lshl_add_u64 v[240:241], s[46:47], 0, v[130:131]
	s_mov_b32 m0, s11
	s_nop 0
	global_load_lds_dwordx4 v[240:241], off
	s_mov_b32 m0, s12
	s_nop 0
	global_load_lds_dwordx4 v[242:243], off
	s_waitcnt vmcnt(8)
	s_waitcnt lgkmcnt(0)
	s_barrier
	s_setprio 1
	v_mfma_f32_16x16x32_bf16 v[62:65], v[140:143], v[204:207], v[62:65]
	v_mfma_f32_16x16x32_bf16 v[58:61], v[148:151], v[204:207], v[58:61]
	v_mfma_f32_16x16x32_bf16 v[54:57], v[140:143], v[212:215], v[54:57]
	v_mfma_f32_16x16x32_bf16 v[50:53], v[148:151], v[212:215], v[50:53]
	v_mfma_f32_16x16x32_bf16 v[38:41], v[140:143], v[220:223], v[38:41]
	v_mfma_f32_16x16x32_bf16 v[34:37], v[148:151], v[220:223], v[34:37]
	v_mfma_f32_16x16x32_bf16 v[22:25], v[140:143], v[228:231], v[22:25]
	v_mfma_f32_16x16x32_bf16 v[18:21], v[148:151], v[228:231], v[18:21]
	s_setprio 0
	s_setprio 1
	v_mfma_f32_16x16x32_bf16 v[62:65], v[144:147], v[208:211], v[62:65]
	v_mfma_f32_16x16x32_bf16 v[58:61], v[152:155], v[208:211], v[58:61]
	v_mfma_f32_16x16x32_bf16 v[54:57], v[144:147], v[216:219], v[54:57]
	v_mfma_f32_16x16x32_bf16 v[50:53], v[152:155], v[216:219], v[50:53]
	v_mfma_f32_16x16x32_bf16 v[38:41], v[144:147], v[224:227], v[38:41]
	v_mfma_f32_16x16x32_bf16 v[34:37], v[152:155], v[224:227], v[34:37]
	v_mfma_f32_16x16x32_bf16 v[22:25], v[144:147], v[232:235], v[22:25]
	v_mfma_f32_16x16x32_bf16 v[18:21], v[152:155], v[232:235], v[18:21]
	s_setprio 0
	s_setprio 1
	v_mfma_f32_16x16x32_bf16 v[46:49], v[158:161], v[204:207], v[46:49]
	v_mfma_f32_16x16x32_bf16 v[42:45], v[196:199], v[204:207], v[42:45]
	v_mfma_f32_16x16x32_bf16 v[30:33], v[158:161], v[212:215], v[30:33]
	v_mfma_f32_16x16x32_bf16 v[26:29], v[196:199], v[212:215], v[26:29]
	v_mfma_f32_16x16x32_bf16 v[14:17], v[158:161], v[220:223], v[14:17]
	v_mfma_f32_16x16x32_bf16 v[10:13], v[196:199], v[220:223], v[10:13]
	v_mfma_f32_16x16x32_bf16 v[6:9], v[158:161], v[228:231], v[6:9]
	v_mfma_f32_16x16x32_bf16 v[2:5], v[196:199], v[228:231], v[2:5]
	s_setprio 0
	s_setprio 1
	v_mfma_f32_16x16x32_bf16 v[46:49], v[162:165], v[208:211], v[46:49]
	v_mfma_f32_16x16x32_bf16 v[42:45], v[200:203], v[208:211], v[42:45]
	v_mfma_f32_16x16x32_bf16 v[30:33], v[162:165], v[216:219], v[30:33]
	v_mfma_f32_16x16x32_bf16 v[26:29], v[200:203], v[216:219], v[26:29]
	v_mfma_f32_16x16x32_bf16 v[14:17], v[162:165], v[224:227], v[14:17]
	v_mfma_f32_16x16x32_bf16 v[10:13], v[200:203], v[224:227], v[10:13]
	v_mfma_f32_16x16x32_bf16 v[6:9], v[162:165], v[232:235], v[6:9]
	v_mfma_f32_16x16x32_bf16 v[2:5], v[200:203], v[232:235], v[2:5]
	s_setprio 0
	s_barrier
	v_add_u32_e32 v139, s62, v137
	ds_read_b128 v[140:143], v139
	ds_read_b128 v[144:147], v139 offset:1024
	ds_read_b128 v[148:151], v139 offset:2048
	ds_read_b128 v[152:155], v139 offset:3072
	v_add_u32_e32 v139, s59, v137
	ds_read_b128 v[158:161], v139
	ds_read_b128 v[162:165], v139 offset:1024
	ds_read_b128 v[196:199], v139 offset:2048
	ds_read_b128 v[200:203], v139 offset:3072
	s_mov_b32 m0, s13
	v_lshl_add_u64 v[244:245], s[44:45], 0, v[130:131]
	ds_read_b128 v[204:207], v138 offset:32768
	ds_read_b128 v[208:211], v138 offset:33792
	ds_read_b128 v[212:215], v138 offset:34816
	ds_read_b128 v[216:219], v138 offset:35840
	ds_read_b128 v[220:223], v138 offset:36864
	ds_read_b128 v[224:227], v138 offset:37888
	ds_read_b128 v[228:231], v138 offset:38912
	ds_read_b128 v[232:235], v138 offset:39936
	global_load_lds_dwordx4 v[244:245], off
	v_lshl_add_u64 v[244:245], s[44:45], 0, v[132:133]
	s_mov_b32 m0, s16
	s_nop 0
	global_load_lds_dwordx4 v[244:245], off
	s_waitcnt vmcnt(8)
	s_waitcnt lgkmcnt(0)
	s_barrier
	s_setprio 1
	v_mfma_f32_16x16x32_bf16 v[126:129], v[140:143], v[204:207], v[126:129]
	v_mfma_f32_16x16x32_bf16 v[122:125], v[148:151], v[204:207], v[122:125]
	v_mfma_f32_16x16x32_bf16 v[118:121], v[140:143], v[212:215], v[118:121]
	v_mfma_f32_16x16x32_bf16 v[114:117], v[148:151], v[212:215], v[114:117]
	v_mfma_f32_16x16x32_bf16 v[102:105], v[140:143], v[220:223], v[102:105]
	v_mfma_f32_16x16x32_bf16 v[98:101], v[148:151], v[220:223], v[98:101]
	v_mfma_f32_16x16x32_bf16 v[86:89], v[140:143], v[228:231], v[86:89]
	v_mfma_f32_16x16x32_bf16 v[82:85], v[148:151], v[228:231], v[82:85]
	s_setprio 0
	s_setprio 1
	v_mfma_f32_16x16x32_bf16 v[126:129], v[144:147], v[208:211], v[126:129]
	v_mfma_f32_16x16x32_bf16 v[122:125], v[152:155], v[208:211], v[122:125]
	v_mfma_f32_16x16x32_bf16 v[118:121], v[144:147], v[216:219], v[118:121]
	v_mfma_f32_16x16x32_bf16 v[114:117], v[152:155], v[216:219], v[114:117]
	v_mfma_f32_16x16x32_bf16 v[102:105], v[144:147], v[224:227], v[102:105]
	v_mfma_f32_16x16x32_bf16 v[98:101], v[152:155], v[224:227], v[98:101]
	v_mfma_f32_16x16x32_bf16 v[86:89], v[144:147], v[232:235], v[86:89]
	v_mfma_f32_16x16x32_bf16 v[82:85], v[152:155], v[232:235], v[82:85]
	s_setprio 0
	s_setprio 1
	v_mfma_f32_16x16x32_bf16 v[110:113], v[158:161], v[204:207], v[110:113]
	v_mfma_f32_16x16x32_bf16 v[106:109], v[196:199], v[204:207], v[106:109]
	v_mfma_f32_16x16x32_bf16 v[94:97], v[158:161], v[212:215], v[94:97]
	v_mfma_f32_16x16x32_bf16 v[90:93], v[196:199], v[212:215], v[90:93]
	v_mfma_f32_16x16x32_bf16 v[78:81], v[158:161], v[220:223], v[78:81]
	v_mfma_f32_16x16x32_bf16 v[74:77], v[196:199], v[220:223], v[74:77]
	v_mfma_f32_16x16x32_bf16 v[70:73], v[158:161], v[228:231], v[70:73]
	v_mfma_f32_16x16x32_bf16 v[66:69], v[196:199], v[228:231], v[66:69]
	s_setprio 0
	s_setprio 1
	v_mfma_f32_16x16x32_bf16 v[110:113], v[162:165], v[208:211], v[110:113]
	v_mfma_f32_16x16x32_bf16 v[106:109], v[200:203], v[208:211], v[106:109]
	v_mfma_f32_16x16x32_bf16 v[94:97], v[162:165], v[216:219], v[94:97]
	v_mfma_f32_16x16x32_bf16 v[90:93], v[200:203], v[216:219], v[90:93]
	v_mfma_f32_16x16x32_bf16 v[78:81], v[162:165], v[224:227], v[78:81]
	v_mfma_f32_16x16x32_bf16 v[74:77], v[200:203], v[224:227], v[74:77]
	v_mfma_f32_16x16x32_bf16 v[70:73], v[162:165], v[232:235], v[70:73]
	v_mfma_f32_16x16x32_bf16 v[66:69], v[200:203], v[232:235], v[66:69]
	s_setprio 0
	s_barrier
	s_mov_b32 m0, s58
	v_lshl_add_u64 v[236:237], v[236:237], 0, s[24:25]
	ds_read_b128 v[204:207], v138 offset:49152
	ds_read_b128 v[208:211], v138 offset:50176
	ds_read_b128 v[212:215], v138 offset:51200
	ds_read_b128 v[216:219], v138 offset:52224
	ds_read_b128 v[220:223], v138 offset:53248
	ds_read_b128 v[224:227], v138 offset:54272
	ds_read_b128 v[228:231], v138 offset:55296
	ds_read_b128 v[232:235], v138 offset:56320
	global_load_lds_dwordx4 v[236:237], off
	v_lshl_add_u64 v[236:237], v[238:239], 0, s[24:25]
	s_mov_b32 m0, s20
	s_nop 0
	global_load_lds_dwordx4 v[236:237], off
	v_lshl_add_u64 v[236:237], s[42:43], 0, v[0:1]
	s_mov_b32 m0, s84
	s_nop 0
	global_load_lds_dwordx4 v[236:237], off
	v_lshl_add_u64 v[236:237], s[42:43], 0, v[134:135]
	s_mov_b32 m0, s70
	s_nop 0
	global_load_lds_dwordx4 v[236:237], off
	v_lshl_add_u64 v[236:237], v[240:241], 0, s[24:25]
	s_mov_b32 m0, s17
	s_nop 0
	global_load_lds_dwordx4 v[236:237], off
	v_lshl_add_u64 v[236:237], v[242:243], 0, s[24:25]
	s_mov_b32 m0, s28
	s_nop 0
	global_load_lds_dwordx4 v[236:237], off
	s_waitcnt vmcnt(8)
	s_waitcnt lgkmcnt(0)
	s_barrier
	s_setprio 1
	v_mfma_f32_16x16x32_bf16 v[62:65], v[140:143], v[204:207], v[62:65]
	v_mfma_f32_16x16x32_bf16 v[58:61], v[148:151], v[204:207], v[58:61]
	v_mfma_f32_16x16x32_bf16 v[54:57], v[140:143], v[212:215], v[54:57]
	v_mfma_f32_16x16x32_bf16 v[50:53], v[148:151], v[212:215], v[50:53]
	v_mfma_f32_16x16x32_bf16 v[38:41], v[140:143], v[220:223], v[38:41]
	v_mfma_f32_16x16x32_bf16 v[34:37], v[148:151], v[220:223], v[34:37]
	v_mfma_f32_16x16x32_bf16 v[22:25], v[140:143], v[228:231], v[22:25]
	v_mfma_f32_16x16x32_bf16 v[18:21], v[148:151], v[228:231], v[18:21]
	s_setprio 0
	s_setprio 1
	v_mfma_f32_16x16x32_bf16 v[62:65], v[144:147], v[208:211], v[62:65]
	v_mfma_f32_16x16x32_bf16 v[58:61], v[152:155], v[208:211], v[58:61]
	v_mfma_f32_16x16x32_bf16 v[54:57], v[144:147], v[216:219], v[54:57]
	v_mfma_f32_16x16x32_bf16 v[50:53], v[152:155], v[216:219], v[50:53]
	v_mfma_f32_16x16x32_bf16 v[38:41], v[144:147], v[224:227], v[38:41]
	v_mfma_f32_16x16x32_bf16 v[34:37], v[152:155], v[224:227], v[34:37]
	v_mfma_f32_16x16x32_bf16 v[22:25], v[144:147], v[232:235], v[22:25]
	v_mfma_f32_16x16x32_bf16 v[18:21], v[152:155], v[232:235], v[18:21]
	s_setprio 0
	s_setprio 1
	v_mfma_f32_16x16x32_bf16 v[46:49], v[158:161], v[204:207], v[46:49]
	v_mfma_f32_16x16x32_bf16 v[42:45], v[196:199], v[204:207], v[42:45]
	v_mfma_f32_16x16x32_bf16 v[30:33], v[158:161], v[212:215], v[30:33]
	v_mfma_f32_16x16x32_bf16 v[26:29], v[196:199], v[212:215], v[26:29]
	v_mfma_f32_16x16x32_bf16 v[14:17], v[158:161], v[220:223], v[14:17]
	v_mfma_f32_16x16x32_bf16 v[10:13], v[196:199], v[220:223], v[10:13]
	v_mfma_f32_16x16x32_bf16 v[6:9], v[158:161], v[228:231], v[6:9]
	v_mfma_f32_16x16x32_bf16 v[2:5], v[196:199], v[228:231], v[2:5]
	s_setprio 0
	s_setprio 1
	v_mfma_f32_16x16x32_bf16 v[46:49], v[162:165], v[208:211], v[46:49]
	v_mfma_f32_16x16x32_bf16 v[42:45], v[200:203], v[208:211], v[42:45]
	v_mfma_f32_16x16x32_bf16 v[30:33], v[162:165], v[216:219], v[30:33]
	v_mfma_f32_16x16x32_bf16 v[26:29], v[200:203], v[216:219], v[26:29]
	v_mfma_f32_16x16x32_bf16 v[14:17], v[162:165], v[224:227], v[14:17]
	v_mfma_f32_16x16x32_bf16 v[10:13], v[200:203], v[224:227], v[10:13]
	v_mfma_f32_16x16x32_bf16 v[6:9], v[162:165], v[232:235], v[6:9]
	v_mfma_f32_16x16x32_bf16 v[2:5], v[200:203], v[232:235], v[2:5]
	s_setprio 0
	s_barrier
	s_andn2_b64 vcc, exec, s[40:41]
	s_mov_b64 s[42:43], -1
	s_mov_b64 s[40:41], 0
	s_movk_i32 s20, 0x100
	s_cbranch_vccz .LBB0_1254
	s_waitcnt vmcnt(0)
	s_cmpk_lt_u32 s7, 0x100
	s_cbranch_scc0 .LBB0_1257
	s_barrier

.LBB0_1302:
	s_add_u32 s17, s40, 0xfce78080
	s_addc_u32 s20, s41, -1
	s_cmp_lg_u32 s16, 12
	s_cselect_b32 s17, s17, 0
	s_cselect_b32 s20, s20, 0
	s_add_u32 s44, s6, s17
	s_addc_u32 s45, s7, s20
	s_add_i32 s46, 0, 0x10000
	s_add_u32 s42, s8, s17
	v_add_u32_e32 v143, s46, v141
	s_addc_u32 s43, s9, s20
	s_add_i32 s17, 0, 0x14000
	ds_read_b128 v[144:147], v143
	ds_read_b128 v[148:151], v143 offset:1024
	ds_read_b128 v[152:155], v143 offset:2048
	ds_read_b128 v[158:161], v143 offset:3072
	v_add_u32_e32 v143, s17, v141
	ds_read_b128 v[162:165], v143
	ds_read_b128 v[196:199], v143 offset:1024
	ds_read_b128 v[200:203], v143 offset:2048
	ds_read_b128 v[204:207], v143 offset:3072
	v_lshl_add_u64 v[240:241], v[138:139], 0, s[40:41]
	s_add_i32 m0, s4, 0xc000
	ds_read_b128 v[208:211], v142
	ds_read_b128 v[212:215], v142 offset:1024
	ds_read_b128 v[216:219], v142 offset:2048
	ds_read_b128 v[220:223], v142 offset:3072
	ds_read_b128 v[224:227], v142 offset:4096
	ds_read_b128 v[228:231], v142 offset:5120
	ds_read_b128 v[232:235], v142 offset:6144
	ds_read_b128 v[236:239], v142 offset:7168
	global_load_lds_dwordx4 v[240:241], off
	v_lshl_add_u64 v[240:241], v[136:137], 0, s[40:41]
	s_add_i32 m0, s4, 0xe000
	s_nop 0
	global_load_lds_dwordx4 v[240:241], off
	s_waitcnt vmcnt(8)
	s_waitcnt lgkmcnt(0)
	s_barrier
	s_setprio 1
	v_mfma_f32_16x16x32_bf16 v[126:129], v[144:147], v[208:211], v[126:129]
	v_mfma_f32_16x16x32_bf16 v[122:125], v[152:155], v[208:211], v[122:125]
	v_mfma_f32_16x16x32_bf16 v[110:113], v[144:147], v[216:219], v[110:113]
	v_mfma_f32_16x16x32_bf16 v[106:109], v[152:155], v[216:219], v[106:109]
	v_mfma_f32_16x16x32_bf16 v[94:97], v[144:147], v[224:227], v[94:97]
	v_mfma_f32_16x16x32_bf16 v[90:93], v[152:155], v[224:227], v[90:93]
	v_mfma_f32_16x16x32_bf16 v[78:81], v[144:147], v[232:235], v[78:81]
	v_mfma_f32_16x16x32_bf16 v[74:77], v[152:155], v[232:235], v[74:77]
	s_setprio 0
	s_setprio 1
	v_mfma_f32_16x16x32_bf16 v[126:129], v[148:151], v[212:215], v[126:129]
	v_mfma_f32_16x16x32_bf16 v[122:125], v[158:161], v[212:215], v[122:125]
	v_mfma_f32_16x16x32_bf16 v[110:113], v[148:151], v[220:223], v[110:113]
	v_mfma_f32_16x16x32_bf16 v[106:109], v[158:161], v[220:223], v[106:109]
	v_mfma_f32_16x16x32_bf16 v[94:97], v[148:151], v[228:231], v[94:97]
	v_mfma_f32_16x16x32_bf16 v[90:93], v[158:161], v[228:231], v[90:93]
	v_mfma_f32_16x16x32_bf16 v[78:81], v[148:151], v[236:239], v[78:81]
	v_mfma_f32_16x16x32_bf16 v[74:77], v[158:161], v[236:239], v[74:77]
	s_setprio 0
	s_setprio 1
	v_mfma_f32_16x16x32_bf16 v[118:121], v[162:165], v[208:211], v[118:121]
	v_mfma_f32_16x16x32_bf16 v[114:117], v[200:203], v[208:211], v[114:117]
	v_mfma_f32_16x16x32_bf16 v[102:105], v[162:165], v[216:219], v[102:105]
	v_mfma_f32_16x16x32_bf16 v[98:101], v[200:203], v[216:219], v[98:101]
	v_mfma_f32_16x16x32_bf16 v[86:89], v[162:165], v[224:227], v[86:89]
	v_mfma_f32_16x16x32_bf16 v[82:85], v[200:203], v[224:227], v[82:85]
	v_mfma_f32_16x16x32_bf16 v[70:73], v[162:165], v[232:235], v[70:73]
	v_mfma_f32_16x16x32_bf16 v[66:69], v[200:203], v[232:235], v[66:69]
	s_setprio 0
	s_setprio 1
	v_mfma_f32_16x16x32_bf16 v[118:121], v[196:199], v[212:215], v[118:121]
	v_mfma_f32_16x16x32_bf16 v[114:117], v[204:207], v[212:215], v[114:117]
	v_mfma_f32_16x16x32_bf16 v[102:105], v[196:199], v[220:223], v[102:105]
	v_mfma_f32_16x16x32_bf16 v[98:101], v[204:207], v[220:223], v[98:101]
	v_mfma_f32_16x16x32_bf16 v[86:89], v[196:199], v[228:231], v[86:89]
	v_mfma_f32_16x16x32_bf16 v[82:85], v[204:207], v[228:231], v[82:85]
	v_mfma_f32_16x16x32_bf16 v[70:73], v[196:199], v[236:239], v[70:73]
	v_mfma_f32_16x16x32_bf16 v[66:69], v[204:207], v[236:239], v[66:69]
	s_setprio 0
	s_barrier
	s_add_i32 s20, s46, s3
	v_lshl_add_u64 v[240:241], s[42:43], 0, v[0:1]
	s_mov_b32 m0, s20
	ds_read_b128 v[208:211], v142 offset:16384
	ds_read_b128 v[212:215], v142 offset:17408
	ds_read_b128 v[216:219], v142 offset:18432
	ds_read_b128 v[220:223], v142 offset:19456
	ds_read_b128 v[224:227], v142 offset:20480
	ds_read_b128 v[228:231], v142 offset:21504
	ds_read_b128 v[232:235], v142 offset:22528
	ds_read_b128 v[236:239], v142 offset:23552
	global_load_lds_dwordx4 v[240:241], off
	s_add_i32 m0, s20, 0x2000
	s_add_u32 s46, s42, 0x10000
	v_lshl_add_u64 v[242:243], s[42:43], 0, v[134:135]
	s_addc_u32 s47, s43, 0
	s_add_i32 s17, s17, s3
	global_load_lds_dwordx4 v[242:243], off
	v_lshl_add_u64 v[244:245], s[46:47], 0, v[0:1]
	s_mov_b32 m0, s17
	v_lshl_add_u64 v[246:247], s[44:45], 0, v[132:133]
	global_load_lds_dwordx4 v[244:245], off
	v_lshl_add_u64 v[244:245], s[46:47], 0, v[134:135]
	s_add_i32 m0, s17, 0x2000
	s_nop 0
	global_load_lds_dwordx4 v[244:245], off
	v_lshl_add_u64 v[244:245], s[44:45], 0, v[130:131]
	s_mov_b32 m0, s4
	s_nop 0
	global_load_lds_dwordx4 v[244:245], off
	s_mov_b32 m0, s5
	s_nop 0
	global_load_lds_dwordx4 v[246:247], off
	s_waitcnt vmcnt(8)
	s_waitcnt lgkmcnt(0)
	s_barrier
	s_setprio 1
	v_mfma_f32_16x16x32_bf16 v[62:65], v[144:147], v[208:211], v[62:65]
	v_mfma_f32_16x16x32_bf16 v[58:61], v[152:155], v[208:211], v[58:61]
	v_mfma_f32_16x16x32_bf16 v[46:49], v[144:147], v[216:219], v[46:49]
	v_mfma_f32_16x16x32_bf16 v[42:45], v[152:155], v[216:219], v[42:45]
	v_mfma_f32_16x16x32_bf16 v[30:33], v[144:147], v[224:227], v[30:33]
	v_mfma_f32_16x16x32_bf16 v[26:29], v[152:155], v[224:227], v[26:29]
	v_mfma_f32_16x16x32_bf16 v[14:17], v[144:147], v[232:235], v[14:17]
	v_mfma_f32_16x16x32_bf16 v[10:13], v[152:155], v[232:235], v[10:13]
	s_setprio 0
	s_setprio 1
	v_mfma_f32_16x16x32_bf16 v[62:65], v[148:151], v[212:215], v[62:65]
	v_mfma_f32_16x16x32_bf16 v[58:61], v[158:161], v[212:215], v[58:61]
	v_mfma_f32_16x16x32_bf16 v[46:49], v[148:151], v[220:223], v[46:49]
	v_mfma_f32_16x16x32_bf16 v[42:45], v[158:161], v[220:223], v[42:45]
	v_mfma_f32_16x16x32_bf16 v[30:33], v[148:151], v[228:231], v[30:33]
	v_mfma_f32_16x16x32_bf16 v[26:29], v[158:161], v[228:231], v[26:29]
	v_mfma_f32_16x16x32_bf16 v[14:17], v[148:151], v[236:239], v[14:17]
	v_mfma_f32_16x16x32_bf16 v[10:13], v[158:161], v[236:239], v[10:13]
	s_setprio 0
	s_setprio 1
	v_mfma_f32_16x16x32_bf16 v[54:57], v[162:165], v[208:211], v[54:57]
	v_mfma_f32_16x16x32_bf16 v[50:53], v[200:203], v[208:211], v[50:53]
	v_mfma_f32_16x16x32_bf16 v[38:41], v[162:165], v[216:219], v[38:41]
	v_mfma_f32_16x16x32_bf16 v[34:37], v[200:203], v[216:219], v[34:37]
	v_mfma_f32_16x16x32_bf16 v[22:25], v[162:165], v[224:227], v[22:25]
	v_mfma_f32_16x16x32_bf16 v[18:21], v[200:203], v[224:227], v[18:21]
	v_mfma_f32_16x16x32_bf16 v[6:9], v[162:165], v[232:235], v[6:9]
	v_mfma_f32_16x16x32_bf16 v[2:5], v[200:203], v[232:235], v[2:5]
	s_setprio 0
	s_setprio 1
	v_mfma_f32_16x16x32_bf16 v[54:57], v[196:199], v[212:215], v[54:57]
	v_mfma_f32_16x16x32_bf16 v[50:53], v[204:207], v[212:215], v[50:53]
	v_mfma_f32_16x16x32_bf16 v[38:41], v[196:199], v[220:223], v[38:41]
	v_mfma_f32_16x16x32_bf16 v[34:37], v[204:207], v[220:223], v[34:37]
	v_mfma_f32_16x16x32_bf16 v[22:25], v[196:199], v[228:231], v[22:25]
	v_mfma_f32_16x16x32_bf16 v[18:21], v[204:207], v[228:231], v[18:21]
	v_mfma_f32_16x16x32_bf16 v[6:9], v[196:199], v[236:239], v[6:9]
	v_mfma_f32_16x16x32_bf16 v[2:5], v[204:207], v[236:239], v[2:5]
	s_setprio 0
	s_barrier
	s_add_i32 s17, 0, 0x18000
	v_add_u32_e32 v143, s17, v141
	s_add_i32 s20, 0, 0x1c000
	ds_read_b128 v[144:147], v143
	ds_read_b128 v[148:151], v143 offset:1024
	ds_read_b128 v[152:155], v143 offset:2048
	ds_read_b128 v[158:161], v143 offset:3072
	v_add_u32_e32 v143, s20, v141
	ds_read_b128 v[162:165], v143
	ds_read_b128 v[196:199], v143 offset:1024
	ds_read_b128 v[200:203], v143 offset:2048
	ds_read_b128 v[204:207], v143 offset:3072
	s_add_u32 s44, s44, 0x40000
	s_addc_u32 s45, s45, 0
	s_mov_b32 m0, s10
	v_lshl_add_u64 v[248:249], s[44:45], 0, v[130:131]
	ds_read_b128 v[208:211], v142 offset:32768
	ds_read_b128 v[212:215], v142 offset:33792
	ds_read_b128 v[216:219], v142 offset:34816
	ds_read_b128 v[220:223], v142 offset:35840
	ds_read_b128 v[224:227], v142 offset:36864
	ds_read_b128 v[228:231], v142 offset:37888
	ds_read_b128 v[232:235], v142 offset:38912
	ds_read_b128 v[236:239], v142 offset:39936
	global_load_lds_dwordx4 v[248:249], off
	v_lshl_add_u64 v[248:249], s[44:45], 0, v[132:133]
	s_mov_b32 m0, s11
	s_nop 0
	global_load_lds_dwordx4 v[248:249], off
	s_waitcnt vmcnt(8)
	s_waitcnt lgkmcnt(0)
	s_barrier
	s_setprio 1
	v_mfma_f32_16x16x32_bf16 v[126:129], v[144:147], v[208:211], v[126:129]
	v_mfma_f32_16x16x32_bf16 v[122:125], v[152:155], v[208:211], v[122:125]
	v_mfma_f32_16x16x32_bf16 v[110:113], v[144:147], v[216:219], v[110:113]
	v_mfma_f32_16x16x32_bf16 v[106:109], v[152:155], v[216:219], v[106:109]
	v_mfma_f32_16x16x32_bf16 v[94:97], v[144:147], v[224:227], v[94:97]
	v_mfma_f32_16x16x32_bf16 v[90:93], v[152:155], v[224:227], v[90:93]
	v_mfma_f32_16x16x32_bf16 v[78:81], v[144:147], v[232:235], v[78:81]
	v_mfma_f32_16x16x32_bf16 v[74:77], v[152:155], v[232:235], v[74:77]
	s_setprio 0
	s_setprio 1
	v_mfma_f32_16x16x32_bf16 v[126:129], v[148:151], v[212:215], v[126:129]
	v_mfma_f32_16x16x32_bf16 v[122:125], v[158:161], v[212:215], v[122:125]
	v_mfma_f32_16x16x32_bf16 v[110:113], v[148:151], v[220:223], v[110:113]
	v_mfma_f32_16x16x32_bf16 v[106:109], v[158:161], v[220:223], v[106:109]
	v_mfma_f32_16x16x32_bf16 v[94:97], v[148:151], v[228:231], v[94:97]
	v_mfma_f32_16x16x32_bf16 v[90:93], v[158:161], v[228:231], v[90:93]
	v_mfma_f32_16x16x32_bf16 v[78:81], v[148:151], v[236:239], v[78:81]
	v_mfma_f32_16x16x32_bf16 v[74:77], v[158:161], v[236:239], v[74:77]
	s_setprio 0
	s_setprio 1
	v_mfma_f32_16x16x32_bf16 v[118:121], v[162:165], v[208:211], v[118:121]
	v_mfma_f32_16x16x32_bf16 v[114:117], v[200:203], v[208:211], v[114:117]
	v_mfma_f32_16x16x32_bf16 v[102:105], v[162:165], v[216:219], v[102:105]
	v_mfma_f32_16x16x32_bf16 v[98:101], v[200:203], v[216:219], v[98:101]
	v_mfma_f32_16x16x32_bf16 v[86:89], v[162:165], v[224:227], v[86:89]
	v_mfma_f32_16x16x32_bf16 v[82:85], v[200:203], v[224:227], v[82:85]
	v_mfma_f32_16x16x32_bf16 v[70:73], v[162:165], v[232:235], v[70:73]
	v_mfma_f32_16x16x32_bf16 v[66:69], v[200:203], v[232:235], v[66:69]
	s_setprio 0
	s_setprio 1
	v_mfma_f32_16x16x32_bf16 v[118:121], v[196:199], v[212:215], v[118:121]
	v_mfma_f32_16x16x32_bf16 v[114:117], v[204:207], v[212:215], v[114:117]
	v_mfma_f32_16x16x32_bf16 v[102:105], v[196:199], v[220:223], v[102:105]
	v_mfma_f32_16x16x32_bf16 v[98:101], v[204:207], v[220:223], v[98:101]
	v_mfma_f32_16x16x32_bf16 v[86:89], v[196:199], v[228:231], v[86:89]
	v_mfma_f32_16x16x32_bf16 v[82:85], v[204:207], v[228:231], v[82:85]
	v_mfma_f32_16x16x32_bf16 v[70:73], v[196:199], v[236:239], v[70:73]
	v_mfma_f32_16x16x32_bf16 v[66:69], v[204:207], v[236:239], v[66:69]
	s_setprio 0
	s_barrier
	s_add_i32 s17, s17, s3
	v_lshl_add_u64 v[240:241], v[240:241], 0, s[24:25]
	s_mov_b32 m0, s17
	ds_read_b128 v[208:211], v142 offset:49152
	ds_read_b128 v[212:215], v142 offset:50176
	ds_read_b128 v[216:219], v142 offset:51200
	ds_read_b128 v[220:223], v142 offset:52224
	ds_read_b128 v[224:227], v142 offset:53248
	ds_read_b128 v[228:231], v142 offset:54272
	ds_read_b128 v[232:235], v142 offset:55296
	ds_read_b128 v[236:239], v142 offset:56320
	global_load_lds_dwordx4 v[240:241], off
	s_add_i32 m0, s17, 0x2000
	s_add_u32 s42, s42, 0x10080
	v_lshl_add_u64 v[240:241], v[242:243], 0, s[24:25]
	s_addc_u32 s43, s43, 0
	s_add_i32 s17, s20, s3
	global_load_lds_dwordx4 v[240:241], off
	v_lshl_add_u64 v[240:241], s[42:43], 0, v[0:1]
	s_mov_b32 m0, s17
	s_nop 0
	global_load_lds_dwordx4 v[240:241], off
	v_lshl_add_u64 v[240:241], s[42:43], 0, v[134:135]
	s_add_i32 m0, s17, 0x2000
	s_nop 0
	global_load_lds_dwordx4 v[240:241], off
	v_lshl_add_u64 v[240:241], v[244:245], 0, s[24:25]
	s_mov_b32 m0, s12
	s_nop 0
	global_load_lds_dwordx4 v[240:241], off
	v_lshl_add_u64 v[240:241], v[246:247], 0, s[24:25]
	s_mov_b32 m0, s13
	s_nop 0
	global_load_lds_dwordx4 v[240:241], off
	s_waitcnt vmcnt(8)
	s_waitcnt lgkmcnt(0)
	s_barrier
	s_setprio 1
	v_mfma_f32_16x16x32_bf16 v[62:65], v[144:147], v[208:211], v[62:65]
	v_mfma_f32_16x16x32_bf16 v[58:61], v[152:155], v[208:211], v[58:61]
	v_mfma_f32_16x16x32_bf16 v[46:49], v[144:147], v[216:219], v[46:49]
	v_mfma_f32_16x16x32_bf16 v[42:45], v[152:155], v[216:219], v[42:45]
	v_mfma_f32_16x16x32_bf16 v[30:33], v[144:147], v[224:227], v[30:33]
	v_mfma_f32_16x16x32_bf16 v[26:29], v[152:155], v[224:227], v[26:29]
	v_mfma_f32_16x16x32_bf16 v[14:17], v[144:147], v[232:235], v[14:17]
	v_mfma_f32_16x16x32_bf16 v[10:13], v[152:155], v[232:235], v[10:13]
	s_setprio 0
	s_setprio 1
	v_mfma_f32_16x16x32_bf16 v[62:65], v[148:151], v[212:215], v[62:65]
	v_mfma_f32_16x16x32_bf16 v[58:61], v[158:161], v[212:215], v[58:61]
	v_mfma_f32_16x16x32_bf16 v[46:49], v[148:151], v[220:223], v[46:49]
	v_mfma_f32_16x16x32_bf16 v[42:45], v[158:161], v[220:223], v[42:45]
	v_mfma_f32_16x16x32_bf16 v[30:33], v[148:151], v[228:231], v[30:33]
	v_mfma_f32_16x16x32_bf16 v[26:29], v[158:161], v[228:231], v[26:29]
	v_mfma_f32_16x16x32_bf16 v[14:17], v[148:151], v[236:239], v[14:17]
	v_mfma_f32_16x16x32_bf16 v[10:13], v[158:161], v[236:239], v[10:13]
	s_setprio 0
	s_setprio 1
	v_mfma_f32_16x16x32_bf16 v[54:57], v[162:165], v[208:211], v[54:57]
	v_mfma_f32_16x16x32_bf16 v[50:53], v[200:203], v[208:211], v[50:53]
	v_mfma_f32_16x16x32_bf16 v[38:41], v[162:165], v[216:219], v[38:41]
	v_mfma_f32_16x16x32_bf16 v[34:37], v[200:203], v[216:219], v[34:37]
	v_mfma_f32_16x16x32_bf16 v[22:25], v[162:165], v[224:227], v[22:25]
	v_mfma_f32_16x16x32_bf16 v[18:21], v[200:203], v[224:227], v[18:21]
	v_mfma_f32_16x16x32_bf16 v[6:9], v[162:165], v[232:235], v[6:9]
	v_mfma_f32_16x16x32_bf16 v[2:5], v[200:203], v[232:235], v[2:5]
	s_setprio 0
	s_setprio 1
	v_mfma_f32_16x16x32_bf16 v[54:57], v[196:199], v[212:215], v[54:57]
	v_mfma_f32_16x16x32_bf16 v[50:53], v[204:207], v[212:215], v[50:53]
	v_mfma_f32_16x16x32_bf16 v[38:41], v[196:199], v[220:223], v[38:41]
	v_mfma_f32_16x16x32_bf16 v[34:37], v[204:207], v[220:223], v[34:37]
	v_mfma_f32_16x16x32_bf16 v[22:25], v[196:199], v[228:231], v[22:25]
	v_mfma_f32_16x16x32_bf16 v[18:21], v[204:207], v[228:231], v[18:21]
	v_mfma_f32_16x16x32_bf16 v[6:9], v[196:199], v[236:239], v[6:9]
	v_mfma_f32_16x16x32_bf16 v[2:5], v[204:207], v[236:239], v[2:5]
	s_setprio 0
	s_barrier
	s_add_i32 s16, s16, 2
	s_add_u32 s40, s40, 0x100
	s_addc_u32 s41, s41, 0
	s_cmp_gt_u32 s16, 13
	s_cbranch_scc0 .LBB0_1302
	s_waitcnt vmcnt(0)
	s_mov_b32 s12, s58
	s_cmpk_lt_u32 s1, 0x100
	s_cbranch_scc0 .LBB0_1305
	s_barrier
